# v30 plus stacked bit-identical micro-edits: compress k-loop read batching, redundant mid-block setprio pairs removed, stale lgkmcnt waits in epilogue row sums removed, permlane32 max exchange in diff
# speedup vs baseline: 1.0027x; 1.0027x over previous
; __device__ __forceinline__ float ex2(float x) { return __builtin_amdgcn_exp2f(x); }
; __device__ __forceinline__ f32x16 splat16(float v) { f32x16 z; for (int i = 0; i < 16; ++i) z[i] = v; return z; }
; template <int NDB>
; __device__ __forceinline__ void softmax_rel(f32x16& s0, f32x16& s1, float& m, f32x16& negm, float& l, f32x16 (&o)[NDB]) {
;     float mx = fmaxf(s0[0], s1[0]);
; #pragma unroll
;     for (int r = 1; r < 16; ++r) mx = fmaxf(fmaxf(mx, s0[r]), s1[r]);
;     mx = fmaxf(mx, __shfl_xor(mx, 32));
;     if (__any(mx > 0.f)) {
;         const float delta = fmaxf(mx, 0.f), alpha = ex2(-delta);
;         m += delta; l *= alpha; negm = splat16(-m);
; #pragma unroll
;         for (int db = 0; db < NDB; ++db) o[db] *= alpha;
; #pragma unroll
;         for (int r = 0; r < 16; ++r) { s0[r] -= delta; s1[r] -= delta; }
;     }
.LBB0_311:
	s_or_b64 exec, exec, s[18:19]
	s_nop 8
	v_max_f32_e32 v0, v112, v112
	v_max_f32_e32 v1, v96, v96
	v_max_f32_e32 v0, v1, v0
	v_max3_f32 v0, v0, v97, v113
	v_max3_f32 v0, v0, v98, v114
	v_max3_f32 v0, v0, v99, v115
	v_max3_f32 v0, v0, v100, v116
	v_max3_f32 v0, v0, v101, v117
	v_max3_f32 v0, v0, v102, v118
	v_max3_f32 v0, v0, v103, v119
	v_max3_f32 v0, v0, v104, v120
	v_max3_f32 v0, v0, v105, v121
	v_max3_f32 v0, v0, v106, v122
	v_max3_f32 v0, v0, v107, v123
	v_max3_f32 v0, v0, v108, v124
	v_max3_f32 v0, v0, v109, v125
	v_max3_f32 v0, v0, v110, v126
	v_max3_f32 v0, v0, v111, v127
	v_mov_b32_e32 v1, v0
	s_nop 1
	v_permlane32_swap_b32_e32 v1, v0
	v_max_f32_e32 v1, v1, v1
	v_max_f32_e32 v0, v0, v1
	v_cmp_lt_f32_e32 vcc, 0, v0
	s_cbranch_vccz .LBB0_313
	v_max_f32_e32 v0, v0, v0
	v_max_f32_e32 v0, 0, v0
	v_exp_f32_e64 v2, -v0
	v_add_f32_e32 v228, v228, v0
	v_xor_b32_e32 v80, 0x80000000, v228
	v_mov_b32_e32 v81, v80
	v_mul_f32_e32 v4, v4, v2
	v_mov_b32_e32 v82, v80
	v_mov_b32_e32 v83, v80
	v_mov_b32_e32 v84, v80
	v_mov_b32_e32 v85, v80
	v_mov_b32_e32 v86, v80
	v_mov_b32_e32 v87, v80
	v_mov_b32_e32 v88, v80
	v_mov_b32_e32 v89, v80
	v_mov_b32_e32 v90, v80
	v_mov_b32_e32 v91, v80
	v_mov_b32_e32 v92, v80
	v_mov_b32_e32 v93, v80
	v_mov_b32_e32 v94, v80
	v_mov_b32_e32 v95, v80
	v_pk_mul_f32 v[78:79], v[78:79], v[2:3] op_sel_hi:[1,0]
	v_pk_mul_f32 v[76:77], v[76:77], v[2:3] op_sel_hi:[1,0]
	v_pk_mul_f32 v[74:75], v[74:75], v[2:3] op_sel_hi:[1,0]
	v_pk_mul_f32 v[72:73], v[72:73], v[2:3] op_sel_hi:[1,0]
	v_pk_mul_f32 v[70:71], v[70:71], v[2:3] op_sel_hi:[1,0]
	v_pk_mul_f32 v[68:69], v[68:69], v[2:3] op_sel_hi:[1,0]
	v_pk_mul_f32 v[66:67], v[66:67], v[2:3] op_sel_hi:[1,0]
	v_pk_mul_f32 v[64:65], v[64:65], v[2:3] op_sel_hi:[1,0]
	v_pk_mul_f32 v[62:63], v[62:63], v[2:3] op_sel_hi:[1,0]
	v_pk_mul_f32 v[60:61], v[60:61], v[2:3] op_sel_hi:[1,0]
	v_pk_mul_f32 v[58:59], v[58:59], v[2:3] op_sel_hi:[1,0]
	v_pk_mul_f32 v[56:57], v[56:57], v[2:3] op_sel_hi:[1,0]
	v_pk_mul_f32 v[54:55], v[54:55], v[2:3] op_sel_hi:[1,0]
	v_pk_mul_f32 v[52:53], v[52:53], v[2:3] op_sel_hi:[1,0]
	v_pk_mul_f32 v[50:51], v[50:51], v[2:3] op_sel_hi:[1,0]
	v_pk_mul_f32 v[48:49], v[48:49], v[2:3] op_sel_hi:[1,0]
	v_pk_mul_f32 v[46:47], v[46:47], v[2:3] op_sel_hi:[1,0]
	v_pk_mul_f32 v[44:45], v[44:45], v[2:3] op_sel_hi:[1,0]
	v_pk_mul_f32 v[42:43], v[42:43], v[2:3] op_sel_hi:[1,0]
	v_pk_mul_f32 v[40:41], v[40:41], v[2:3] op_sel_hi:[1,0]
	v_pk_mul_f32 v[38:39], v[38:39], v[2:3] op_sel_hi:[1,0]
	v_pk_mul_f32 v[36:37], v[36:37], v[2:3] op_sel_hi:[1,0]
	v_pk_mul_f32 v[34:35], v[34:35], v[2:3] op_sel_hi:[1,0]
	v_pk_mul_f32 v[32:33], v[32:33], v[2:3] op_sel_hi:[1,0]
	v_pk_mul_f32 v[30:31], v[30:31], v[2:3] op_sel_hi:[1,0]
	v_pk_mul_f32 v[28:29], v[28:29], v[2:3] op_sel_hi:[1,0]
	v_pk_mul_f32 v[26:27], v[26:27], v[2:3] op_sel_hi:[1,0]
	v_pk_mul_f32 v[24:25], v[24:25], v[2:3] op_sel_hi:[1,0]
	v_pk_mul_f32 v[22:23], v[22:23], v[2:3] op_sel_hi:[1,0]
	v_pk_mul_f32 v[20:21], v[20:21], v[2:3] op_sel_hi:[1,0]
	v_pk_mul_f32 v[18:19], v[18:19], v[2:3] op_sel_hi:[1,0]
	v_pk_mul_f32 v[16:17], v[16:17], v[2:3] op_sel_hi:[1,0]
	v_pk_add_f32 v[96:97], v[96:97], v[0:1] op_sel_hi:[1,0] neg_lo:[0,1] neg_hi:[0,1]
	v_pk_add_f32 v[112:113], v[112:113], v[0:1] op_sel_hi:[1,0] neg_lo:[0,1] neg_hi:[0,1]
	v_pk_add_f32 v[98:99], v[98:99], v[0:1] op_sel_hi:[1,0] neg_lo:[0,1] neg_hi:[0,1]
	v_pk_add_f32 v[114:115], v[114:115], v[0:1] op_sel_hi:[1,0] neg_lo:[0,1] neg_hi:[0,1]
	v_pk_add_f32 v[100:101], v[100:101], v[0:1] op_sel_hi:[1,0] neg_lo:[0,1] neg_hi:[0,1]
	v_pk_add_f32 v[116:117], v[116:117], v[0:1] op_sel_hi:[1,0] neg_lo:[0,1] neg_hi:[0,1]
	v_pk_add_f32 v[102:103], v[102:103], v[0:1] op_sel_hi:[1,0] neg_lo:[0,1] neg_hi:[0,1]
	v_pk_add_f32 v[118:119], v[118:119], v[0:1] op_sel_hi:[1,0] neg_lo:[0,1] neg_hi:[0,1]
	v_pk_add_f32 v[104:105], v[104:105], v[0:1] op_sel_hi:[1,0] neg_lo:[0,1] neg_hi:[0,1]
	v_pk_add_f32 v[120:121], v[120:121], v[0:1] op_sel_hi:[1,0] neg_lo:[0,1] neg_hi:[0,1]
	v_pk_add_f32 v[106:107], v[106:107], v[0:1] op_sel_hi:[1,0] neg_lo:[0,1] neg_hi:[0,1]
	v_pk_add_f32 v[122:123], v[122:123], v[0:1] op_sel_hi:[1,0] neg_lo:[0,1] neg_hi:[0,1]
	v_pk_add_f32 v[108:109], v[108:109], v[0:1] op_sel_hi:[1,0] neg_lo:[0,1] neg_hi:[0,1]
	v_pk_add_f32 v[124:125], v[124:125], v[0:1] op_sel_hi:[1,0] neg_lo:[0,1] neg_hi:[0,1]
	v_pk_add_f32 v[110:111], v[110:111], v[0:1] op_sel_hi:[1,0] neg_lo:[0,1] neg_hi:[0,1]
	v_pk_add_f32 v[126:127], v[126:127], v[0:1] op_sel_hi:[1,0] neg_lo:[0,1] neg_hi:[0,1]

; __device__ __forceinline__ float ex2(float x) { return __builtin_amdgcn_exp2f(x); }
; __device__ __forceinline__ f32x16 splat16(float v) { f32x16 z; for (int i = 0; i < 16; ++i) z[i] = v; return z; }
; template <int NDB>
; __device__ __forceinline__ void softmax_rel(f32x16& s0, f32x16& s1, float& m, f32x16& negm, float& l, f32x16 (&o)[NDB]) {
;     float mx = fmaxf(s0[0], s1[0]);
; #pragma unroll
;     for (int r = 1; r < 16; ++r) mx = fmaxf(fmaxf(mx, s0[r]), s1[r]);
;     mx = fmaxf(mx, __shfl_xor(mx, 32));
;     if (__any(mx > 0.f)) {
;         const float delta = fmaxf(mx, 0.f), alpha = ex2(-delta);
;         m += delta; l *= alpha; negm = splat16(-m);
; #pragma unroll
;         for (int db = 0; db < NDB; ++db) o[db] *= alpha;
; #pragma unroll
;         for (int r = 0; r < 16; ++r) { s0[r] -= delta; s1[r] -= delta; }
;     }
.LBB0_320:
	s_or_b64 exec, exec, s[20:21]
	s_nop 8
	v_max_f32_e32 v0, v112, v112
	v_max_f32_e32 v1, v96, v96
	v_max_f32_e32 v0, v1, v0
	v_max3_f32 v0, v0, v97, v113
	v_max3_f32 v0, v0, v98, v114
	v_max3_f32 v0, v0, v99, v115
	v_max3_f32 v0, v0, v100, v116
	v_max3_f32 v0, v0, v101, v117
	v_max3_f32 v0, v0, v102, v118
	v_max3_f32 v0, v0, v103, v119
	v_max3_f32 v0, v0, v104, v120
	v_max3_f32 v0, v0, v105, v121
	v_max3_f32 v0, v0, v106, v122
	v_max3_f32 v0, v0, v107, v123
	v_max3_f32 v0, v0, v108, v124
	v_max3_f32 v0, v0, v109, v125
	v_max3_f32 v0, v0, v110, v126
	v_max3_f32 v0, v0, v111, v127
	v_mov_b32_e32 v1, v0
	s_nop 1
	v_permlane32_swap_b32_e32 v1, v0
	v_max_f32_e32 v1, v1, v1
	v_max_f32_e32 v0, v0, v1
	v_cmp_lt_f32_e32 vcc, 0, v0
	s_cbranch_vccz .LBB0_322
	v_max_f32_e32 v0, v0, v0
	v_max_f32_e32 v0, 0, v0
	v_exp_f32_e64 v2, -v0
	v_add_f32_e32 v228, v228, v0
	v_xor_b32_e32 v80, 0x80000000, v228
	v_mov_b32_e32 v81, v80
	v_mul_f32_e32 v4, v4, v2
	v_mov_b32_e32 v82, v80
	v_mov_b32_e32 v83, v80
	v_mov_b32_e32 v84, v80
	v_mov_b32_e32 v85, v80
	v_mov_b32_e32 v86, v80
	v_mov_b32_e32 v87, v80
	v_mov_b32_e32 v88, v80
	v_mov_b32_e32 v89, v80
	v_mov_b32_e32 v90, v80
	v_mov_b32_e32 v91, v80
	v_mov_b32_e32 v92, v80
	v_mov_b32_e32 v93, v80
	v_mov_b32_e32 v94, v80
	v_mov_b32_e32 v95, v80
	v_pk_mul_f32 v[78:79], v[78:79], v[2:3] op_sel_hi:[1,0]
	v_pk_mul_f32 v[76:77], v[76:77], v[2:3] op_sel_hi:[1,0]
	v_pk_mul_f32 v[74:75], v[74:75], v[2:3] op_sel_hi:[1,0]
	v_pk_mul_f32 v[72:73], v[72:73], v[2:3] op_sel_hi:[1,0]
	v_pk_mul_f32 v[70:71], v[70:71], v[2:3] op_sel_hi:[1,0]
	v_pk_mul_f32 v[68:69], v[68:69], v[2:3] op_sel_hi:[1,0]
	v_pk_mul_f32 v[66:67], v[66:67], v[2:3] op_sel_hi:[1,0]
	v_pk_mul_f32 v[64:65], v[64:65], v[2:3] op_sel_hi:[1,0]
	v_pk_mul_f32 v[62:63], v[62:63], v[2:3] op_sel_hi:[1,0]
	v_pk_mul_f32 v[60:61], v[60:61], v[2:3] op_sel_hi:[1,0]
	v_pk_mul_f32 v[58:59], v[58:59], v[2:3] op_sel_hi:[1,0]
	v_pk_mul_f32 v[56:57], v[56:57], v[2:3] op_sel_hi:[1,0]
	v_pk_mul_f32 v[54:55], v[54:55], v[2:3] op_sel_hi:[1,0]
	v_pk_mul_f32 v[52:53], v[52:53], v[2:3] op_sel_hi:[1,0]
	v_pk_mul_f32 v[50:51], v[50:51], v[2:3] op_sel_hi:[1,0]
	v_pk_mul_f32 v[48:49], v[48:49], v[2:3] op_sel_hi:[1,0]
	v_pk_mul_f32 v[46:47], v[46:47], v[2:3] op_sel_hi:[1,0]
	v_pk_mul_f32 v[44:45], v[44:45], v[2:3] op_sel_hi:[1,0]
	v_pk_mul_f32 v[42:43], v[42:43], v[2:3] op_sel_hi:[1,0]
	v_pk_mul_f32 v[40:41], v[40:41], v[2:3] op_sel_hi:[1,0]
	v_pk_mul_f32 v[38:39], v[38:39], v[2:3] op_sel_hi:[1,0]
	v_pk_mul_f32 v[36:37], v[36:37], v[2:3] op_sel_hi:[1,0]
	v_pk_mul_f32 v[34:35], v[34:35], v[2:3] op_sel_hi:[1,0]
	v_pk_mul_f32 v[32:33], v[32:33], v[2:3] op_sel_hi:[1,0]
	v_pk_mul_f32 v[30:31], v[30:31], v[2:3] op_sel_hi:[1,0]
	v_pk_mul_f32 v[28:29], v[28:29], v[2:3] op_sel_hi:[1,0]
	v_pk_mul_f32 v[26:27], v[26:27], v[2:3] op_sel_hi:[1,0]
	v_pk_mul_f32 v[24:25], v[24:25], v[2:3] op_sel_hi:[1,0]
	v_pk_mul_f32 v[22:23], v[22:23], v[2:3] op_sel_hi:[1,0]
	v_pk_mul_f32 v[20:21], v[20:21], v[2:3] op_sel_hi:[1,0]
	v_pk_mul_f32 v[18:19], v[18:19], v[2:3] op_sel_hi:[1,0]
	v_pk_mul_f32 v[16:17], v[16:17], v[2:3] op_sel_hi:[1,0]
	v_pk_add_f32 v[96:97], v[96:97], v[0:1] op_sel_hi:[1,0] neg_lo:[0,1] neg_hi:[0,1]
	v_pk_add_f32 v[112:113], v[112:113], v[0:1] op_sel_hi:[1,0] neg_lo:[0,1] neg_hi:[0,1]
	v_pk_add_f32 v[98:99], v[98:99], v[0:1] op_sel_hi:[1,0] neg_lo:[0,1] neg_hi:[0,1]
	v_pk_add_f32 v[114:115], v[114:115], v[0:1] op_sel_hi:[1,0] neg_lo:[0,1] neg_hi:[0,1]
	v_pk_add_f32 v[100:101], v[100:101], v[0:1] op_sel_hi:[1,0] neg_lo:[0,1] neg_hi:[0,1]
	v_pk_add_f32 v[116:117], v[116:117], v[0:1] op_sel_hi:[1,0] neg_lo:[0,1] neg_hi:[0,1]
	v_pk_add_f32 v[102:103], v[102:103], v[0:1] op_sel_hi:[1,0] neg_lo:[0,1] neg_hi:[0,1]
	v_pk_add_f32 v[118:119], v[118:119], v[0:1] op_sel_hi:[1,0] neg_lo:[0,1] neg_hi:[0,1]
	v_pk_add_f32 v[104:105], v[104:105], v[0:1] op_sel_hi:[1,0] neg_lo:[0,1] neg_hi:[0,1]
	v_pk_add_f32 v[120:121], v[120:121], v[0:1] op_sel_hi:[1,0] neg_lo:[0,1] neg_hi:[0,1]
	v_pk_add_f32 v[106:107], v[106:107], v[0:1] op_sel_hi:[1,0] neg_lo:[0,1] neg_hi:[0,1]
	v_pk_add_f32 v[122:123], v[122:123], v[0:1] op_sel_hi:[1,0] neg_lo:[0,1] neg_hi:[0,1]
	v_pk_add_f32 v[108:109], v[108:109], v[0:1] op_sel_hi:[1,0] neg_lo:[0,1] neg_hi:[0,1]
	v_pk_add_f32 v[124:125], v[124:125], v[0:1] op_sel_hi:[1,0] neg_lo:[0,1] neg_hi:[0,1]
	v_pk_add_f32 v[110:111], v[110:111], v[0:1] op_sel_hi:[1,0] neg_lo:[0,1] neg_hi:[0,1]
	v_pk_add_f32 v[126:127], v[126:127], v[0:1] op_sel_hi:[1,0] neg_lo:[0,1] neg_hi:[0,1]

; __device__ __forceinline__ float ex2(float x) { return __builtin_amdgcn_exp2f(x); }
; template <int NDB>
; __device__ __forceinline__ void softmax_fast(f32x16& s0, f32x16& s1, float a0, float a1, float base, float c32, bool lane_on, float& m, float& l, f32x16 (&o)[NDB]) {
;     float mx = lane_on ? fmaxf(a0, a1 + c32) + base : NEGB;
;     mx = fmaxf(mx, __shfl_xor(mx, 32));
;     if (__any(mx > m)) {
;         const float mn = fmaxf(m, mx), alpha = ex2(m - mn); m = mn; l *= alpha;
; #pragma unroll
;         for (int db = 0; db < NDB; ++db) o[db] *= alpha;
.LBB0_575:
	v_cvt_f32_i32_e32 v2, v2
	v_add_f32_e32 v49, v240, v228
	v_max_f32_e32 v50, v227, v227
	v_max_f32_e32 v49, v50, v49
	v_fmac_f32_e32 v49, v162, v2
	v_mov_b32_e32 v50, v49
	s_nop 1
	v_permlane32_swap_b32_e32 v50, v49
	v_max_f32_e32 v50, v50, v50
	v_max_f32_e32 v49, v49, v50
	v_cmp_gt_f32_e32 vcc, v49, v191
	s_cbranch_vccz .LBB0_577
	v_max_f32_e32 v49, v49, v49
	v_max_f32_e32 v50, v191, v191
	v_max_f32_e32 v49, v50, v49
	v_sub_f32_e32 v50, v191, v49
	v_exp_f32_e32 v50, v50
	v_mov_b32_e32 v191, v49
	v_mul_f32_e32 v157, v157, v50
	v_pk_mul_f32 v[46:47], v[46:47], v[50:51] op_sel_hi:[1,0]
	v_pk_mul_f32 v[44:45], v[44:45], v[50:51] op_sel_hi:[1,0]
	v_pk_mul_f32 v[42:43], v[42:43], v[50:51] op_sel_hi:[1,0]
	v_pk_mul_f32 v[40:41], v[40:41], v[50:51] op_sel_hi:[1,0]
	v_pk_mul_f32 v[38:39], v[38:39], v[50:51] op_sel_hi:[1,0]
	v_pk_mul_f32 v[36:37], v[36:37], v[50:51] op_sel_hi:[1,0]
	v_pk_mul_f32 v[34:35], v[34:35], v[50:51] op_sel_hi:[1,0]
	v_pk_mul_f32 v[32:33], v[32:33], v[50:51] op_sel_hi:[1,0]
	v_pk_mul_f32 v[30:31], v[30:31], v[50:51] op_sel_hi:[1,0]
	v_pk_mul_f32 v[28:29], v[28:29], v[50:51] op_sel_hi:[1,0]
	v_pk_mul_f32 v[26:27], v[26:27], v[50:51] op_sel_hi:[1,0]
	v_pk_mul_f32 v[24:25], v[24:25], v[50:51] op_sel_hi:[1,0]
	v_pk_mul_f32 v[22:23], v[22:23], v[50:51] op_sel_hi:[1,0]
	v_pk_mul_f32 v[20:21], v[20:21], v[50:51] op_sel_hi:[1,0]
	v_pk_mul_f32 v[18:19], v[18:19], v[50:51] op_sel_hi:[1,0]
	v_pk_mul_f32 v[16:17], v[16:17], v[50:51] op_sel_hi:[1,0]

; __device__ __forceinline__ float ex2(float x) { return __builtin_amdgcn_exp2f(x); }
; template <int NDB>
; __device__ __forceinline__ void softmax_fast(f32x16& s0, f32x16& s1, float a0, float a1, float base, float c32, bool lane_on, float& m, float& l, f32x16 (&o)[NDB]) {
;     float mx = lane_on ? fmaxf(a0, a1 + c32) + base : NEGB;
;     mx = fmaxf(mx, __shfl_xor(mx, 32));
;     if (__any(mx > m)) {
;         const float mn = fmaxf(m, mx), alpha = ex2(m - mn); m = mn; l *= alpha;
; #pragma unroll
;         for (int db = 0; db < NDB; ++db) o[db] *= alpha;
.LBB0_603:
	v_cvt_f32_i32_e32 v2, v2
	v_add_f32_e32 v49, v240, v248
	v_max_f32_e32 v50, v247, v247
	v_max_f32_e32 v49, v50, v49
	v_fmac_f32_e32 v49, v162, v2
	v_cndmask_b32_e64 v49, v232, v49, s[16:17]
	v_mov_b32_e32 v50, v49
	s_nop 1
	v_permlane32_swap_b32_e32 v50, v49
	v_max_f32_e32 v50, v50, v50
	v_max_f32_e32 v49, v49, v50
	v_cmp_gt_f32_e32 vcc, v49, v227
	s_cbranch_vccz .LBB0_605
	v_max_f32_e32 v49, v49, v49
	v_max_f32_e32 v50, v227, v227
	v_max_f32_e32 v49, v50, v49
	v_sub_f32_e32 v50, v227, v49
	v_exp_f32_e32 v50, v50
	v_mov_b32_e32 v227, v49
	v_mul_f32_e32 v165, v165, v50
	v_pk_mul_f32 v[46:47], v[46:47], v[50:51] op_sel_hi:[1,0]
	v_pk_mul_f32 v[44:45], v[44:45], v[50:51] op_sel_hi:[1,0]
	v_pk_mul_f32 v[42:43], v[42:43], v[50:51] op_sel_hi:[1,0]
	v_pk_mul_f32 v[40:41], v[40:41], v[50:51] op_sel_hi:[1,0]
	v_pk_mul_f32 v[38:39], v[38:39], v[50:51] op_sel_hi:[1,0]
	v_pk_mul_f32 v[36:37], v[36:37], v[50:51] op_sel_hi:[1,0]
	v_pk_mul_f32 v[34:35], v[34:35], v[50:51] op_sel_hi:[1,0]
	v_pk_mul_f32 v[32:33], v[32:33], v[50:51] op_sel_hi:[1,0]
	v_pk_mul_f32 v[30:31], v[30:31], v[50:51] op_sel_hi:[1,0]
	v_pk_mul_f32 v[28:29], v[28:29], v[50:51] op_sel_hi:[1,0]
	v_pk_mul_f32 v[26:27], v[26:27], v[50:51] op_sel_hi:[1,0]
	v_pk_mul_f32 v[24:25], v[24:25], v[50:51] op_sel_hi:[1,0]
	v_pk_mul_f32 v[22:23], v[22:23], v[50:51] op_sel_hi:[1,0]
	v_pk_mul_f32 v[20:21], v[20:21], v[50:51] op_sel_hi:[1,0]
	v_pk_mul_f32 v[18:19], v[18:19], v[50:51] op_sel_hi:[1,0]
	v_pk_mul_f32 v[16:17], v[16:17], v[50:51] op_sel_hi:[1,0]

; __device__ __forceinline__ float ex2(float x) { return __builtin_amdgcn_exp2f(x); }
; template <int NDB>
; __device__ __forceinline__ void softmax_fast(f32x16& s0, f32x16& s1, float a0, float a1, float base, float c32, bool lane_on, float& m, float& l, f32x16 (&o)[NDB]) {
;     float mx = lane_on ? fmaxf(a0, a1 + c32) + base : NEGB;
;     mx = fmaxf(mx, __shfl_xor(mx, 32));
;     if (__any(mx > m)) {
;         const float mn = fmaxf(m, mx), alpha = ex2(m - mn); m = mn; l *= alpha;
; #pragma unroll
;         for (int db = 0; db < NDB; ++db) o[db] *= alpha;
.LBB0_614:
	v_cvt_f32_i32_e32 v2, v2
	v_add_f32_e32 v49, v240, v247
	v_max_f32_e32 v50, v246, v246
	v_max_f32_e32 v49, v50, v49
	v_fmac_f32_e32 v49, v162, v2
	v_cndmask_b32_e64 v49, v232, v49, s[16:17]
	v_mov_b32_e32 v50, v49
	s_nop 1
	v_permlane32_swap_b32_e32 v50, v49
	v_max_f32_e32 v50, v50, v50
	v_max_f32_e32 v49, v49, v50
	v_cmp_gt_f32_e32 vcc, v49, v227
	s_cbranch_vccz .LBB0_594
	v_max_f32_e32 v49, v49, v49
	v_max_f32_e32 v50, v227, v227
	v_max_f32_e32 v49, v50, v49
	v_sub_f32_e32 v50, v227, v49
	v_exp_f32_e32 v50, v50
	v_mov_b32_e32 v227, v49
	v_mul_f32_e32 v165, v165, v50
	v_pk_mul_f32 v[46:47], v[46:47], v[50:51] op_sel_hi:[1,0]
	v_pk_mul_f32 v[44:45], v[44:45], v[50:51] op_sel_hi:[1,0]
	v_pk_mul_f32 v[42:43], v[42:43], v[50:51] op_sel_hi:[1,0]
	v_pk_mul_f32 v[40:41], v[40:41], v[50:51] op_sel_hi:[1,0]
	v_pk_mul_f32 v[38:39], v[38:39], v[50:51] op_sel_hi:[1,0]
	v_pk_mul_f32 v[36:37], v[36:37], v[50:51] op_sel_hi:[1,0]
	v_pk_mul_f32 v[34:35], v[34:35], v[50:51] op_sel_hi:[1,0]
	v_pk_mul_f32 v[32:33], v[32:33], v[50:51] op_sel_hi:[1,0]
	v_pk_mul_f32 v[30:31], v[30:31], v[50:51] op_sel_hi:[1,0]
	v_pk_mul_f32 v[28:29], v[28:29], v[50:51] op_sel_hi:[1,0]
	v_pk_mul_f32 v[26:27], v[26:27], v[50:51] op_sel_hi:[1,0]
	v_pk_mul_f32 v[24:25], v[24:25], v[50:51] op_sel_hi:[1,0]
	v_pk_mul_f32 v[22:23], v[22:23], v[50:51] op_sel_hi:[1,0]
	v_pk_mul_f32 v[20:21], v[20:21], v[50:51] op_sel_hi:[1,0]
	v_pk_mul_f32 v[18:19], v[18:19], v[50:51] op_sel_hi:[1,0]
	v_pk_mul_f32 v[16:17], v[16:17], v[50:51] op_sel_hi:[1,0]
	s_branch .LBB0_594

; #define PG8_STAGE(bufoff, gbase, voff) do { _Pragma("unroll") for (int _i = 0; _i < 2; ++_i) \
;         __builtin_amdgcn_global_load_lds((const unsigned*)((const char*)(gbase) + (voff)[_i]), (PG8_LAS unsigned*)(lds + (bufoff) + ldsw + _i * 8192), 16, 0, 0); } while (0)
; #define PG8_LDA(dst, b, h) do { _Pragma("unroll") for (int m = 0; m < 4; ++m) _Pragma("unroll") for (int k = 0; k < 2; ++k) dst[m][k] = *(const PG8_LAS bf16x8*)(lds + PG8_SA(b, h) + aoff + m * 2048 + k * 1024); } while (0)
; #define PG8_LDB(dst, b, h) do { _Pragma("unroll") for (int n = 0; n < 2; ++n) _Pragma("unroll") for (int k = 0; k < 2; ++k) dst[n][k] = *(const PG8_LAS bf16x8*)(lds + PG8_SB(b, h) + boff + n * 2048 + k * 1024); } while (0)
; #define PG8_MMA(ai, bj, At, Bt) do { __builtin_amdgcn_s_setprio(1); _Pragma("unroll") for (int m = 0; m < 4; ++m) _Pragma("unroll") for (int n = 0; n < 2; ++n) _Pragma("unroll") for (int k = 0; k < 2; ++k) \
;         acc[ai][bj][m][n] = __builtin_amdgcn_mfma_f32_16x16x32_bf16(Bt[n][k], At[m][k], acc[ai][bj][m][n], 0, 0, 0); __builtin_amdgcn_s_setprio(0); } while (0)
; #define PG8_WAIT_V(n) asm volatile("s_waitcnt vmcnt(" #n ")" ::: "memory")
; #define PG8_WAIT_L(n) asm volatile("s_waitcnt lgkmcnt(" #n ")" ::: "memory")
; #define PG8_BAR __builtin_amdgcn_s_barrier()
; #define PG8_SCHED __builtin_amdgcn_sched_barrier(0)
; template <class Epi, class Sched, bool ALIGN_EPI = false, bool SP2 = false>
; __device__ __forceinline__ void gemm_phase(PG8_LAS unsigned char* lds, const Gemm g, const Sched& S, const Epi& E) {
;     ...
;             PG8_LDB(B0, 0, 0); PG8_LDB(B1, 0, 1); PG8_SCHED; PG8_LDA(At, 0, 0); PG8_STAGE(PG8_SA(1, 1), a1 + hstep, voffA);
;             PG8_WAIT_V(8); PG8_WAIT_L(0); PG8_BAR; PG8_MMA(0, 0, At, B0); PG8_MMA(0, 1, At, B1); PG8_BAR; PG8_SCHED;
;             PG8_LDA(At, 0, 1); PG8_STAGE(PG8_SB(0, 0), b2, voffB); PG8_STAGE(PG8_SB(0, 1), b2 + hstep, voffB); PG8_STAGE(PG8_SA(0, 0), a2, voffA);
;             PG8_WAIT_V(8); PG8_WAIT_L(0); PG8_BAR; PG8_MMA(1, 0, At, B0); PG8_MMA(1, 1, At, B1); PG8_BAR; PG8_SCHED;
.LBB0_694:
	s_add_u32 s30, s28, 0xfffc0080
	s_addc_u32 s31, s29, -1
	s_add_i32 s46, 0, 0x10000
	s_cmp_eq_u32 s52, 12
	s_cselect_b32 s35, s21, s31
	s_cselect_b32 s34, vcc_lo, s30
	v_add_u32_e32 v140, s46, v142
	s_cselect_b32 s31, s19, s55
	s_cselect_b32 s30, vcc_hi, s54
	s_add_i32 s94, 0, 0x14000
	ds_read_b128 v[146:149], v140
	ds_read_b128 v[150:153], v140 offset:1024
	ds_read_b128 v[154:157], v140 offset:2048
	ds_read_b128 v[158:161], v140 offset:3072
	v_add_u32_e32 v140, s94, v142
	ds_read_b128 v[162:165], v140
	ds_read_b128 v[166:169], v140 offset:1024
	ds_read_b128 v[170:173], v140 offset:2048
	ds_read_b128 v[174:177], v140 offset:3072
	v_lshl_add_u64 v[194:195], s[28:29], 0, v[136:137]
	s_add_i32 m0, s27, 0xc000
	ds_read_b128 v[178:181], v144
	ds_read_b128 v[182:185], v144 offset:1024
	ds_read_b128 v[186:189], v144 offset:2048
	ds_read_b128 v[190:193], v144 offset:3072
	ds_read_b128 v[204:207], v144 offset:4096
	ds_read_b128 v[208:211], v144 offset:5120
	ds_read_b128 v[212:215], v144 offset:6144
	ds_read_b128 v[216:219], v144 offset:7168
	global_load_lds_dwordx4 v[194:195], off
	v_lshl_add_u64 v[194:195], s[28:29], 0, v[138:139]
	s_add_i32 m0, s27, 0xe000
	s_nop 0
	global_load_lds_dwordx4 v[194:195], off
	s_waitcnt vmcnt(8)
	s_waitcnt lgkmcnt(0)
	s_barrier
	s_setprio 1
	s_waitcnt lgkmcnt(0)
	v_mfma_f32_16x16x32_bf16 v[128:131], v[146:149], v[178:181], v[128:131]
	v_mfma_f32_16x16x32_bf16 v[124:127], v[154:157], v[178:181], v[124:127]
	v_mfma_f32_16x16x32_bf16 v[116:119], v[146:149], v[186:189], v[116:119]
	v_mfma_f32_16x16x32_bf16 v[108:111], v[154:157], v[186:189], v[108:111]
	v_mfma_f32_16x16x32_bf16 v[100:103], v[146:149], v[204:207], v[100:103]
	v_mfma_f32_16x16x32_bf16 v[92:95], v[154:157], v[204:207], v[92:95]
	v_mfma_f32_16x16x32_bf16 v[84:87], v[146:149], v[212:215], v[84:87]
	v_mfma_f32_16x16x32_bf16 v[76:79], v[154:157], v[212:215], v[76:79]
	v_mfma_f32_16x16x32_bf16 v[128:131], v[150:153], v[182:185], v[128:131]
	v_mfma_f32_16x16x32_bf16 v[124:127], v[158:161], v[182:185], v[124:127]
	v_mfma_f32_16x16x32_bf16 v[116:119], v[150:153], v[190:193], v[116:119]
	v_mfma_f32_16x16x32_bf16 v[108:111], v[158:161], v[190:193], v[108:111]
	v_mfma_f32_16x16x32_bf16 v[100:103], v[150:153], v[208:211], v[100:103]
	v_mfma_f32_16x16x32_bf16 v[92:95], v[158:161], v[208:211], v[92:95]
	v_mfma_f32_16x16x32_bf16 v[84:87], v[150:153], v[216:219], v[84:87]
	v_mfma_f32_16x16x32_bf16 v[76:79], v[158:161], v[216:219], v[76:79]
	v_mfma_f32_16x16x32_bf16 v[120:123], v[162:165], v[178:181], v[120:123]
	v_mfma_f32_16x16x32_bf16 v[112:115], v[170:173], v[178:181], v[112:115]
	v_mfma_f32_16x16x32_bf16 v[104:107], v[162:165], v[186:189], v[104:107]
	v_mfma_f32_16x16x32_bf16 v[96:99], v[170:173], v[186:189], v[96:99]
	v_mfma_f32_16x16x32_bf16 v[88:91], v[162:165], v[204:207], v[88:91]
	v_mfma_f32_16x16x32_bf16 v[80:83], v[170:173], v[204:207], v[80:83]
	v_mfma_f32_16x16x32_bf16 v[72:75], v[162:165], v[212:215], v[72:75]
	v_mfma_f32_16x16x32_bf16 v[68:71], v[170:173], v[212:215], v[68:71]
	v_mfma_f32_16x16x32_bf16 v[120:123], v[166:169], v[182:185], v[120:123]
	v_mfma_f32_16x16x32_bf16 v[112:115], v[174:177], v[182:185], v[112:115]
	v_mfma_f32_16x16x32_bf16 v[104:107], v[166:169], v[190:193], v[104:107]
	v_mfma_f32_16x16x32_bf16 v[96:99], v[174:177], v[190:193], v[96:99]
	v_mfma_f32_16x16x32_bf16 v[88:91], v[166:169], v[208:211], v[88:91]
	v_mfma_f32_16x16x32_bf16 v[80:83], v[174:177], v[208:211], v[80:83]
	v_mfma_f32_16x16x32_bf16 v[72:75], v[166:169], v[216:219], v[72:75]
	v_mfma_f32_16x16x32_bf16 v[68:71], v[174:177], v[216:219], v[68:71]
	s_setprio 0
	s_barrier
	s_add_i32 s46, s46, s85
	v_lshl_add_u64 v[194:195], s[30:31], 0, v[2:3]
	s_mov_b32 m0, s46
	ds_read_b128 v[178:181], v144 offset:16384
	ds_read_b128 v[182:185], v144 offset:17408
	ds_read_b128 v[186:189], v144 offset:18432
	ds_read_b128 v[190:193], v144 offset:19456
	ds_read_b128 v[204:207], v144 offset:20480
	ds_read_b128 v[208:211], v144 offset:21504
	ds_read_b128 v[212:215], v144 offset:22528
	ds_read_b128 v[216:219], v144 offset:23552
	global_load_lds_dwordx4 v[194:195], off
	s_add_i32 m0, s46, 0x2000
	s_add_u32 s46, s30, 0x40000
	v_lshl_add_u64 v[236:237], s[30:31], 0, v[134:135]
	s_addc_u32 s47, s31, 0
	s_add_i32 s94, s94, s85
	global_load_lds_dwordx4 v[236:237], off
	v_lshl_add_u64 v[238:239], s[46:47], 0, v[2:3]
	s_mov_b32 m0, s94
	v_lshl_add_u64 v[240:241], s[34:35], 0, v[132:133]
	global_load_lds_dwordx4 v[238:239], off
	v_lshl_add_u64 v[238:239], s[46:47], 0, v[134:135]
	s_add_i32 m0, s94, 0x2000
	s_nop 0
	global_load_lds_dwordx4 v[238:239], off
	v_lshl_add_u64 v[238:239], s[34:35], 0, v[0:1]
	s_mov_b32 m0, s27
	s_nop 0
	global_load_lds_dwordx4 v[238:239], off
	s_mov_b32 m0, s68
	s_nop 0
	global_load_lds_dwordx4 v[240:241], off
	s_waitcnt vmcnt(8)
	s_waitcnt lgkmcnt(0)
	s_barrier
; #define PG8_STAGE(bufoff, gbase, voff) do { _Pragma("unroll") for (int _i = 0; _i < 2; ++_i) \
;         __builtin_amdgcn_global_load_lds((const unsigned*)((const char*)(gbase) + (voff)[_i]), (PG8_LAS unsigned*)(lds + (bufoff) + ldsw + _i * 8192), 16, 0, 0); } while (0)
; #define PG8_LDA(dst, b, h) do { _Pragma("unroll") for (int m = 0; m < 4; ++m) _Pragma("unroll") for (int k = 0; k < 2; ++k) dst[m][k] = *(const PG8_LAS bf16x8*)(lds + PG8_SA(b, h) + aoff + m * 2048 + k * 1024); } while (0)
; #define PG8_LDB(dst, b, h) do { _Pragma("unroll") for (int n = 0; n < 2; ++n) _Pragma("unroll") for (int k = 0; k < 2; ++k) dst[n][k] = *(const PG8_LAS bf16x8*)(lds + PG8_SB(b, h) + boff + n * 2048 + k * 1024); } while (0)
; #define PG8_MMA(ai, bj, At, Bt) do { __builtin_amdgcn_s_setprio(1); _Pragma("unroll") for (int m = 0; m < 4; ++m) _Pragma("unroll") for (int n = 0; n < 2; ++n) _Pragma("unroll") for (int k = 0; k < 2; ++k) \
;         acc[ai][bj][m][n] = __builtin_amdgcn_mfma_f32_16x16x32_bf16(Bt[n][k], At[m][k], acc[ai][bj][m][n], 0, 0, 0); __builtin_amdgcn_s_setprio(0); } while (0)
; #define PG8_WAIT_V(n) asm volatile("s_waitcnt vmcnt(" #n ")" ::: "memory")
; #define PG8_WAIT_L(n) asm volatile("s_waitcnt lgkmcnt(" #n ")" ::: "memory")
; #define PG8_BAR __builtin_amdgcn_s_barrier()
; #define PG8_SCHED __builtin_amdgcn_sched_barrier(0)
; template <class Epi, class Sched, bool ALIGN_EPI = false, bool SP2 = false>
; __device__ __forceinline__ void gemm_phase(PG8_LAS unsigned char* lds, const Gemm g, const Sched& S, const Epi& E) {
;     ...
;             PG8_WAIT_V(8); PG8_WAIT_L(0); PG8_BAR; PG8_MMA(1, 0, At, B0); PG8_MMA(1, 1, At, B1); PG8_BAR; PG8_SCHED;
;             PG8_LDB(B0, 1, 0); PG8_LDB(B1, 1, 1); PG8_SCHED; PG8_LDA(At, 1, 0); PG8_STAGE(PG8_SA(0, 1), a2 + hstep, voffA);
;             PG8_WAIT_V(8); PG8_WAIT_L(0); PG8_BAR; PG8_MMA(0, 0, At, B0); PG8_MMA(0, 1, At, B1); PG8_BAR; PG8_SCHED;
	s_setprio 1
	s_waitcnt lgkmcnt(0)
	v_mfma_f32_16x16x32_bf16 v[64:67], v[146:149], v[178:181], v[64:67]
	v_mfma_f32_16x16x32_bf16 v[60:63], v[154:157], v[178:181], v[60:63]
	v_mfma_f32_16x16x32_bf16 v[52:55], v[146:149], v[186:189], v[52:55]
	v_mfma_f32_16x16x32_bf16 v[44:47], v[154:157], v[186:189], v[44:47]
	v_mfma_f32_16x16x32_bf16 v[36:39], v[146:149], v[204:207], v[36:39]
	v_mfma_f32_16x16x32_bf16 v[28:31], v[154:157], v[204:207], v[28:31]
	v_mfma_f32_16x16x32_bf16 v[20:23], v[146:149], v[212:215], v[20:23]
	v_mfma_f32_16x16x32_bf16 v[12:15], v[154:157], v[212:215], v[12:15]
	v_mfma_f32_16x16x32_bf16 v[64:67], v[150:153], v[182:185], v[64:67]
	v_mfma_f32_16x16x32_bf16 v[60:63], v[158:161], v[182:185], v[60:63]
	v_mfma_f32_16x16x32_bf16 v[52:55], v[150:153], v[190:193], v[52:55]
	v_mfma_f32_16x16x32_bf16 v[44:47], v[158:161], v[190:193], v[44:47]
	v_mfma_f32_16x16x32_bf16 v[36:39], v[150:153], v[208:211], v[36:39]
	v_mfma_f32_16x16x32_bf16 v[28:31], v[158:161], v[208:211], v[28:31]
	v_mfma_f32_16x16x32_bf16 v[20:23], v[150:153], v[216:219], v[20:23]
	v_mfma_f32_16x16x32_bf16 v[12:15], v[158:161], v[216:219], v[12:15]
	v_mfma_f32_16x16x32_bf16 v[56:59], v[162:165], v[178:181], v[56:59]
	v_mfma_f32_16x16x32_bf16 v[48:51], v[170:173], v[178:181], v[48:51]
	v_mfma_f32_16x16x32_bf16 v[40:43], v[162:165], v[186:189], v[40:43]
	v_mfma_f32_16x16x32_bf16 v[32:35], v[170:173], v[186:189], v[32:35]
	v_mfma_f32_16x16x32_bf16 v[24:27], v[162:165], v[204:207], v[24:27]
	v_mfma_f32_16x16x32_bf16 v[16:19], v[170:173], v[204:207], v[16:19]
	v_mfma_f32_16x16x32_bf16 v[8:11], v[162:165], v[212:215], v[8:11]
	v_mfma_f32_16x16x32_bf16 v[4:7], v[170:173], v[212:215], v[4:7]
	v_mfma_f32_16x16x32_bf16 v[56:59], v[166:169], v[182:185], v[56:59]
	v_mfma_f32_16x16x32_bf16 v[48:51], v[174:177], v[182:185], v[48:51]
	v_mfma_f32_16x16x32_bf16 v[40:43], v[166:169], v[190:193], v[40:43]
	v_mfma_f32_16x16x32_bf16 v[32:35], v[174:177], v[190:193], v[32:35]
	v_mfma_f32_16x16x32_bf16 v[24:27], v[166:169], v[208:211], v[24:27]
	v_mfma_f32_16x16x32_bf16 v[16:19], v[174:177], v[208:211], v[16:19]
	v_mfma_f32_16x16x32_bf16 v[8:11], v[166:169], v[216:219], v[8:11]
	v_mfma_f32_16x16x32_bf16 v[4:7], v[174:177], v[216:219], v[4:7]
	s_setprio 0
	s_barrier
	s_add_i32 s46, 0, 0x18000
	v_add_u32_e32 v140, s46, v142
	s_add_i32 s47, 0, 0x1c000
	ds_read_b128 v[146:149], v140
	ds_read_b128 v[150:153], v140 offset:1024
	ds_read_b128 v[154:157], v140 offset:2048
	ds_read_b128 v[158:161], v140 offset:3072
	v_add_u32_e32 v140, s47, v142
	ds_read_b128 v[162:165], v140
	ds_read_b128 v[166:169], v140 offset:1024
	ds_read_b128 v[170:173], v140 offset:2048
	ds_read_b128 v[174:177], v140 offset:3072
	s_add_u32 s34, s34, 0x40000
	s_addc_u32 s35, s35, 0
	s_mov_b32 m0, s69
	v_lshl_add_u64 v[242:243], s[34:35], 0, v[0:1]
	ds_read_b128 v[178:181], v144 offset:32768
	ds_read_b128 v[182:185], v144 offset:33792
	ds_read_b128 v[186:189], v144 offset:34816
	ds_read_b128 v[190:193], v144 offset:35840
	ds_read_b128 v[204:207], v144 offset:36864
	ds_read_b128 v[208:211], v144 offset:37888
	ds_read_b128 v[212:215], v144 offset:38912
	ds_read_b128 v[216:219], v144 offset:39936
	global_load_lds_dwordx4 v[242:243], off
	v_lshl_add_u64 v[242:243], s[34:35], 0, v[132:133]
	s_mov_b32 m0, s33
	s_nop 0
	global_load_lds_dwordx4 v[242:243], off
	s_waitcnt vmcnt(8)
	s_waitcnt lgkmcnt(0)
	s_barrier
	s_setprio 1
	s_waitcnt lgkmcnt(0)
	v_mfma_f32_16x16x32_bf16 v[128:131], v[146:149], v[178:181], v[128:131]
	v_mfma_f32_16x16x32_bf16 v[124:127], v[154:157], v[178:181], v[124:127]
	v_mfma_f32_16x16x32_bf16 v[116:119], v[146:149], v[186:189], v[116:119]
	v_mfma_f32_16x16x32_bf16 v[108:111], v[154:157], v[186:189], v[108:111]
	v_mfma_f32_16x16x32_bf16 v[100:103], v[146:149], v[204:207], v[100:103]
	v_mfma_f32_16x16x32_bf16 v[92:95], v[154:157], v[204:207], v[92:95]
	v_mfma_f32_16x16x32_bf16 v[84:87], v[146:149], v[212:215], v[84:87]
	v_mfma_f32_16x16x32_bf16 v[76:79], v[154:157], v[212:215], v[76:79]
	v_mfma_f32_16x16x32_bf16 v[128:131], v[150:153], v[182:185], v[128:131]
	v_mfma_f32_16x16x32_bf16 v[124:127], v[158:161], v[182:185], v[124:127]
	v_mfma_f32_16x16x32_bf16 v[116:119], v[150:153], v[190:193], v[116:119]
	v_mfma_f32_16x16x32_bf16 v[108:111], v[158:161], v[190:193], v[108:111]
	v_mfma_f32_16x16x32_bf16 v[100:103], v[150:153], v[208:211], v[100:103]
	v_mfma_f32_16x16x32_bf16 v[92:95], v[158:161], v[208:211], v[92:95]
	v_mfma_f32_16x16x32_bf16 v[84:87], v[150:153], v[216:219], v[84:87]
	v_mfma_f32_16x16x32_bf16 v[76:79], v[158:161], v[216:219], v[76:79]
	v_mfma_f32_16x16x32_bf16 v[120:123], v[162:165], v[178:181], v[120:123]
	v_mfma_f32_16x16x32_bf16 v[112:115], v[170:173], v[178:181], v[112:115]
	v_mfma_f32_16x16x32_bf16 v[104:107], v[162:165], v[186:189], v[104:107]
	v_mfma_f32_16x16x32_bf16 v[96:99], v[170:173], v[186:189], v[96:99]
	v_mfma_f32_16x16x32_bf16 v[88:91], v[162:165], v[204:207], v[88:91]
	v_mfma_f32_16x16x32_bf16 v[80:83], v[170:173], v[204:207], v[80:83]
	v_mfma_f32_16x16x32_bf16 v[72:75], v[162:165], v[212:215], v[72:75]
	v_mfma_f32_16x16x32_bf16 v[68:71], v[170:173], v[212:215], v[68:71]
	v_mfma_f32_16x16x32_bf16 v[120:123], v[166:169], v[182:185], v[120:123]
	v_mfma_f32_16x16x32_bf16 v[112:115], v[174:177], v[182:185], v[112:115]
	v_mfma_f32_16x16x32_bf16 v[104:107], v[166:169], v[190:193], v[104:107]
	v_mfma_f32_16x16x32_bf16 v[96:99], v[174:177], v[190:193], v[96:99]
	v_mfma_f32_16x16x32_bf16 v[88:91], v[166:169], v[208:211], v[88:91]
	v_mfma_f32_16x16x32_bf16 v[80:83], v[174:177], v[208:211], v[80:83]
	v_mfma_f32_16x16x32_bf16 v[72:75], v[166:169], v[216:219], v[72:75]
	v_mfma_f32_16x16x32_bf16 v[68:71], v[174:177], v[216:219], v[68:71]
	s_setprio 0
	s_barrier
; #define PG8_STAGE(bufoff, gbase, voff) do { _Pragma("unroll") for (int _i = 0; _i < 2; ++_i) \
;         __builtin_amdgcn_global_load_lds((const unsigned*)((const char*)(gbase) + (voff)[_i]), (PG8_LAS unsigned*)(lds + (bufoff) + ldsw + _i * 8192), 16, 0, 0); } while (0)
; #define PG8_LDA(dst, b, h) do { _Pragma("unroll") for (int m = 0; m < 4; ++m) _Pragma("unroll") for (int k = 0; k < 2; ++k) dst[m][k] = *(const PG8_LAS bf16x8*)(lds + PG8_SA(b, h) + aoff + m * 2048 + k * 1024); } while (0)
; #define PG8_MMA(ai, bj, At, Bt) do { __builtin_amdgcn_s_setprio(1); _Pragma("unroll") for (int m = 0; m < 4; ++m) _Pragma("unroll") for (int n = 0; n < 2; ++n) _Pragma("unroll") for (int k = 0; k < 2; ++k) \
;         acc[ai][bj][m][n] = __builtin_amdgcn_mfma_f32_16x16x32_bf16(Bt[n][k], At[m][k], acc[ai][bj][m][n], 0, 0, 0); __builtin_amdgcn_s_setprio(0); } while (0)
; #define PG8_WAIT_V(n) asm volatile("s_waitcnt vmcnt(" #n ")" ::: "memory")
; #define PG8_WAIT_L(n) asm volatile("s_waitcnt lgkmcnt(" #n ")" ::: "memory")
; #define PG8_BAR __builtin_amdgcn_s_barrier()
; #define PG8_SCHED __builtin_amdgcn_sched_barrier(0)
; template <class Epi, class Sched, bool ALIGN_EPI = false, bool SP2 = false>
; __device__ __forceinline__ void gemm_phase(PG8_LAS unsigned char* lds, const Gemm g, const Sched& S, const Epi& E) {
;     ...
;         for (int t = 0; t < nt; t += 2) {
;             const bool last = (t == nt - 2);
;             const char* a1 = cA + (size_t)(t + 1) * kstep;
;             const char* a2 = last ? nA : cA + (size_t)(t + 2) * kstep; const char* b2 = last ? nB : cB + (size_t)(t + 2) * kstep;
;     ...
;             PG8_LDA(At, 1, 1); PG8_STAGE(PG8_SB(1, 0), b3, voffB); PG8_STAGE(PG8_SB(1, 1), b3 + hstep, voffB); PG8_STAGE(PG8_SA(1, 0), a3, voffA);
;             PG8_WAIT_V(8); PG8_WAIT_L(0); PG8_BAR; PG8_MMA(1, 0, At, B0); PG8_MMA(1, 1, At, B1); PG8_BAR; PG8_SCHED;
;     ...
;         if constexpr (ALIGN_EPI) { if (wr == 0) PG8_BAR; }
	s_add_i32 s34, s46, s85
	v_lshl_add_u64 v[194:195], v[194:195], 0, s[42:43]
	s_mov_b32 m0, s34
	ds_read_b128 v[178:181], v144 offset:49152
	ds_read_b128 v[182:185], v144 offset:50176
	ds_read_b128 v[186:189], v144 offset:51200
	ds_read_b128 v[190:193], v144 offset:52224
	ds_read_b128 v[204:207], v144 offset:53248
	ds_read_b128 v[208:211], v144 offset:54272
	ds_read_b128 v[212:215], v144 offset:55296
	ds_read_b128 v[216:219], v144 offset:56320
	global_load_lds_dwordx4 v[194:195], off
	s_add_i32 m0, s34, 0x2000
	s_add_u32 s30, s30, 0x40080
	v_lshl_add_u64 v[194:195], v[236:237], 0, s[42:43]
	s_addc_u32 s31, s31, 0
	s_add_i32 s34, s47, s85
	global_load_lds_dwordx4 v[194:195], off
	v_lshl_add_u64 v[194:195], s[30:31], 0, v[2:3]
	s_mov_b32 m0, s34
	s_nop 0
	global_load_lds_dwordx4 v[194:195], off
	v_lshl_add_u64 v[194:195], s[30:31], 0, v[134:135]
	s_add_i32 m0, s34, 0x2000
	s_nop 0
	global_load_lds_dwordx4 v[194:195], off
	v_lshl_add_u64 v[194:195], v[238:239], 0, s[42:43]
	s_mov_b32 m0, s66
	s_nop 0
	global_load_lds_dwordx4 v[194:195], off
	v_lshl_add_u64 v[194:195], v[240:241], 0, s[42:43]
	s_mov_b32 m0, s67
	s_nop 0
	global_load_lds_dwordx4 v[194:195], off
	s_waitcnt vmcnt(8)
	s_waitcnt lgkmcnt(0)
	s_barrier
	s_setprio 1
	s_waitcnt lgkmcnt(0)
	v_mfma_f32_16x16x32_bf16 v[64:67], v[146:149], v[178:181], v[64:67]
	v_mfma_f32_16x16x32_bf16 v[60:63], v[154:157], v[178:181], v[60:63]
	v_mfma_f32_16x16x32_bf16 v[52:55], v[146:149], v[186:189], v[52:55]
	v_mfma_f32_16x16x32_bf16 v[44:47], v[154:157], v[186:189], v[44:47]
	v_mfma_f32_16x16x32_bf16 v[36:39], v[146:149], v[204:207], v[36:39]
	v_mfma_f32_16x16x32_bf16 v[28:31], v[154:157], v[204:207], v[28:31]
	v_mfma_f32_16x16x32_bf16 v[20:23], v[146:149], v[212:215], v[20:23]
	v_mfma_f32_16x16x32_bf16 v[12:15], v[154:157], v[212:215], v[12:15]
	v_mfma_f32_16x16x32_bf16 v[64:67], v[150:153], v[182:185], v[64:67]
	v_mfma_f32_16x16x32_bf16 v[60:63], v[158:161], v[182:185], v[60:63]
	v_mfma_f32_16x16x32_bf16 v[52:55], v[150:153], v[190:193], v[52:55]
	v_mfma_f32_16x16x32_bf16 v[44:47], v[158:161], v[190:193], v[44:47]
	v_mfma_f32_16x16x32_bf16 v[36:39], v[150:153], v[208:211], v[36:39]
	v_mfma_f32_16x16x32_bf16 v[28:31], v[158:161], v[208:211], v[28:31]
	v_mfma_f32_16x16x32_bf16 v[20:23], v[150:153], v[216:219], v[20:23]
	v_mfma_f32_16x16x32_bf16 v[12:15], v[158:161], v[216:219], v[12:15]
	v_mfma_f32_16x16x32_bf16 v[56:59], v[162:165], v[178:181], v[56:59]
	v_mfma_f32_16x16x32_bf16 v[48:51], v[170:173], v[178:181], v[48:51]
	v_mfma_f32_16x16x32_bf16 v[40:43], v[162:165], v[186:189], v[40:43]
	v_mfma_f32_16x16x32_bf16 v[32:35], v[170:173], v[186:189], v[32:35]
	v_mfma_f32_16x16x32_bf16 v[24:27], v[162:165], v[204:207], v[24:27]
	v_mfma_f32_16x16x32_bf16 v[16:19], v[170:173], v[204:207], v[16:19]
	v_mfma_f32_16x16x32_bf16 v[8:11], v[162:165], v[212:215], v[8:11]
	v_mfma_f32_16x16x32_bf16 v[4:7], v[170:173], v[212:215], v[4:7]
	v_mfma_f32_16x16x32_bf16 v[56:59], v[166:169], v[182:185], v[56:59]
	v_mfma_f32_16x16x32_bf16 v[48:51], v[174:177], v[182:185], v[48:51]
	v_mfma_f32_16x16x32_bf16 v[40:43], v[166:169], v[190:193], v[40:43]
	v_mfma_f32_16x16x32_bf16 v[32:35], v[174:177], v[190:193], v[32:35]
	v_mfma_f32_16x16x32_bf16 v[24:27], v[166:169], v[208:211], v[24:27]
	v_mfma_f32_16x16x32_bf16 v[16:19], v[174:177], v[208:211], v[16:19]
	v_mfma_f32_16x16x32_bf16 v[8:11], v[166:169], v[216:219], v[8:11]
	v_mfma_f32_16x16x32_bf16 v[4:7], v[174:177], v[216:219], v[4:7]
	s_setprio 0
	s_barrier
	s_add_i32 s52, s52, 2
	s_add_u32 s28, s28, 0x100
	s_addc_u32 s29, s29, 0
	s_add_u32 s54, s54, 0x100
	s_addc_u32 s55, s55, 0
	s_cmp_gt_u32 s52, 13
	s_cbranch_scc0 .LBB0_694
	s_and_b64 vcc, exec, s[16:17]
	s_cbranch_vccz .LBB0_697
	s_barrier

; #define PG8_STAGE(bufoff, gbase, voff) do { _Pragma("unroll") for (int _i = 0; _i < 2; ++_i) \
;         __builtin_amdgcn_global_load_lds((const unsigned*)((const char*)(gbase) + (voff)[_i]), (PG8_LAS unsigned*)(lds + (bufoff) + ldsw + _i * 8192), 16, 0, 0); } while (0)
; #define PG8_LDA(dst, b, h) do { _Pragma("unroll") for (int m = 0; m < 4; ++m) _Pragma("unroll") for (int k = 0; k < 2; ++k) dst[m][k] = *(const PG8_LAS bf16x8*)(lds + PG8_SA(b, h) + aoff + m * 2048 + k * 1024); } while (0)
; #define PG8_LDB(dst, b, h) do { _Pragma("unroll") for (int n = 0; n < 2; ++n) _Pragma("unroll") for (int k = 0; k < 2; ++k) dst[n][k] = *(const PG8_LAS bf16x8*)(lds + PG8_SB(b, h) + boff + n * 2048 + k * 1024); } while (0)
; #define PG8_MMA(ai, bj, At, Bt) do { __builtin_amdgcn_s_setprio(1); _Pragma("unroll") for (int m = 0; m < 4; ++m) _Pragma("unroll") for (int n = 0; n < 2; ++n) _Pragma("unroll") for (int k = 0; k < 2; ++k) \
;         acc[ai][bj][m][n] = __builtin_amdgcn_mfma_f32_16x16x32_bf16(Bt[n][k], At[m][k], acc[ai][bj][m][n], 0, 0, 0); __builtin_amdgcn_s_setprio(0); } while (0)
; #define PG8_WAIT_V(n) asm volatile("s_waitcnt vmcnt(" #n ")" ::: "memory")
; #define PG8_WAIT_L(n) asm volatile("s_waitcnt lgkmcnt(" #n ")" ::: "memory")
; #define PG8_BAR __builtin_amdgcn_s_barrier()
; #define PG8_SCHED __builtin_amdgcn_sched_barrier(0)
; template <class Epi, class Sched, bool ALIGN_EPI = false, bool SP2 = false>
; __device__ __forceinline__ void gemm_phase(PG8_LAS unsigned char* lds, const Gemm g, const Sched& S, const Epi& E) {
;     ...
;             PG8_LDB(B0, 0, 0); PG8_LDB(B1, 0, 1); PG8_SCHED; PG8_LDA(At, 0, 0); PG8_STAGE(PG8_SA(1, 1), a1 + hstep, voffA);
;             PG8_WAIT_V(8); PG8_WAIT_L(0); PG8_BAR; PG8_MMA(0, 0, At, B0); PG8_MMA(0, 1, At, B1); PG8_BAR; PG8_SCHED;
;             PG8_LDA(At, 0, 1); PG8_STAGE(PG8_SB(0, 0), b2, voffB); PG8_STAGE(PG8_SB(0, 1), b2 + hstep, voffB); PG8_STAGE(PG8_SA(0, 0), a2, voffA);
;             PG8_WAIT_V(8); PG8_WAIT_L(0); PG8_BAR; PG8_MMA(1, 0, At, B0); PG8_MMA(1, 1, At, B1); PG8_BAR; PG8_SCHED;
.LBB0_720:
	s_add_i32 s40, s20, 2
	s_add_u32 s41, s12, s18
	s_addc_u32 s21, s13, s19
	s_add_u32 s46, s8, s18
	s_addc_u32 s47, s9, s19
	s_add_i32 s52, 0, 0x10000
	s_cmp_eq_u32 s78, s20
	s_cselect_b32 s21, s1, s21
	s_cselect_b32 s20, s0, s41
	v_add_u32_e32 v134, s52, v120
	s_cselect_b32 s49, s15, s47
	s_cselect_b32 s48, s14, s46
	s_add_i32 s41, 0, 0x14000
	ds_read_b128 v[122:125], v134
	ds_read_b128 v[126:129], v134 offset:1024
	ds_read_b128 v[130:133], v134 offset:2048
	ds_read_b128 v[140:143], v134 offset:3072
	v_add_u32_e32 v134, s41, v120
	ds_read_b128 v[164:167], v134
	ds_read_b128 v[168:171], v134 offset:1024
	ds_read_b128 v[172:175], v134 offset:2048
	ds_read_b128 v[176:179], v134 offset:3072
	v_lshl_add_u64 v[134:135], s[12:13], 0, v[110:111]
	s_add_i32 m0, s23, 0xc000
	ds_read_b128 v[180:183], v121
	ds_read_b128 v[184:187], v121 offset:1024
	ds_read_b128 v[188:191], v121 offset:2048
	ds_read_b128 v[192:195], v121 offset:3072
	ds_read_b128 v[208:211], v121 offset:4096
	ds_read_b128 v[212:215], v121 offset:5120
	ds_read_b128 v[236:239], v121 offset:6144
	ds_read_b128 v[240:243], v121 offset:7168
	global_load_lds_dwordx4 v[134:135], off
	v_lshl_add_u64 v[134:135], s[12:13], 0, v[108:109]
	s_add_i32 m0, s23, 0xe000
	s_nop 0
	global_load_lds_dwordx4 v[134:135], off
	s_waitcnt vmcnt(8)
	s_waitcnt lgkmcnt(0)
	s_barrier
	s_setprio 1
	s_waitcnt lgkmcnt(0)
	v_mfma_f32_16x16x32_bf16 v[96:99], v[122:125], v[180:183], v[96:99]
	v_mfma_f32_16x16x32_bf16 v[160:163], v[130:133], v[180:183], v[160:163]
	v_mfma_f32_16x16x32_bf16 v[88:91], v[122:125], v[188:191], v[88:91]
	v_mfma_f32_16x16x32_bf16 v[156:159], v[130:133], v[188:191], v[156:159]
	v_mfma_f32_16x16x32_bf16 v[92:95], v[122:125], v[208:211], v[92:95]
	v_mfma_f32_16x16x32_bf16 v[152:155], v[130:133], v[208:211], v[152:155]
	v_mfma_f32_16x16x32_bf16 v[72:75], v[122:125], v[236:239], v[72:75]
	v_mfma_f32_16x16x32_bf16 v[148:151], v[130:133], v[236:239], v[148:151]
	v_mfma_f32_16x16x32_bf16 v[96:99], v[126:129], v[184:187], v[96:99]
	v_mfma_f32_16x16x32_bf16 v[160:163], v[140:143], v[184:187], v[160:163]
	v_mfma_f32_16x16x32_bf16 v[88:91], v[126:129], v[192:195], v[88:91]
	v_mfma_f32_16x16x32_bf16 v[156:159], v[140:143], v[192:195], v[156:159]
	v_mfma_f32_16x16x32_bf16 v[92:95], v[126:129], v[212:215], v[92:95]
	v_mfma_f32_16x16x32_bf16 v[152:155], v[140:143], v[212:215], v[152:155]
	v_mfma_f32_16x16x32_bf16 v[72:75], v[126:129], v[240:243], v[72:75]
	v_mfma_f32_16x16x32_bf16 v[148:151], v[140:143], v[240:243], v[148:151]
	v_mfma_f32_16x16x32_bf16 v[84:87], v[164:167], v[180:183], v[84:87]
	v_mfma_f32_16x16x32_bf16 v[32:35], v[172:175], v[180:183], v[32:35]
	v_mfma_f32_16x16x32_bf16 v[76:79], v[164:167], v[188:191], v[76:79]
	v_mfma_f32_16x16x32_bf16 v[28:31], v[172:175], v[188:191], v[28:31]
	v_mfma_f32_16x16x32_bf16 v[60:63], v[164:167], v[208:211], v[60:63]
	v_mfma_f32_16x16x32_bf16 v[24:27], v[172:175], v[208:211], v[24:27]
	v_mfma_f32_16x16x32_bf16 v[56:59], v[164:167], v[236:239], v[56:59]
	v_mfma_f32_16x16x32_bf16 v[20:23], v[172:175], v[236:239], v[20:23]
	v_mfma_f32_16x16x32_bf16 v[84:87], v[168:171], v[184:187], v[84:87]
	v_mfma_f32_16x16x32_bf16 v[32:35], v[176:179], v[184:187], v[32:35]
	v_mfma_f32_16x16x32_bf16 v[76:79], v[168:171], v[192:195], v[76:79]
	v_mfma_f32_16x16x32_bf16 v[28:31], v[176:179], v[192:195], v[28:31]
	v_mfma_f32_16x16x32_bf16 v[60:63], v[168:171], v[212:215], v[60:63]
	v_mfma_f32_16x16x32_bf16 v[24:27], v[176:179], v[212:215], v[24:27]
	v_mfma_f32_16x16x32_bf16 v[56:59], v[168:171], v[240:243], v[56:59]
	v_mfma_f32_16x16x32_bf16 v[20:23], v[176:179], v[240:243], v[20:23]
	s_setprio 0
	s_barrier
	s_add_i32 s46, s52, s22
	v_lshl_add_u64 v[204:205], s[48:49], 0, v[2:3]
	s_mov_b32 m0, s46
	ds_read_b128 v[180:183], v121 offset:16384
	ds_read_b128 v[184:187], v121 offset:17408
	ds_read_b128 v[188:191], v121 offset:18432
	ds_read_b128 v[192:195], v121 offset:19456
	ds_read_b128 v[208:211], v121 offset:20480
	ds_read_b128 v[212:215], v121 offset:21504
	ds_read_b128 v[236:239], v121 offset:22528
	ds_read_b128 v[240:243], v121 offset:23552
	global_load_lds_dwordx4 v[204:205], off
	s_add_i32 m0, s46, 0x2000
	v_lshl_add_u64 v[216:217], s[48:49], 0, v[0:1]
	s_add_u32 s48, s48, s77
	s_addc_u32 s49, s49, 0
	s_add_i32 s41, s41, s22
	global_load_lds_dwordx4 v[216:217], off
	v_lshl_add_u64 v[244:245], s[48:49], 0, v[2:3]
	s_mov_b32 m0, s41
	v_lshl_add_u64 v[246:247], s[48:49], 0, v[0:1]
	global_load_lds_dwordx4 v[244:245], off
	s_add_i32 m0, s41, 0x2000
	v_lshl_add_u64 v[248:249], s[20:21], 0, v[102:103]
	global_load_lds_dwordx4 v[246:247], off
	s_mov_b32 m0, s23
	v_lshl_add_u64 v[250:251], s[20:21], 0, v[100:101]
	global_load_lds_dwordx4 v[248:249], off
	s_mov_b32 m0, s24
	s_nop 0
	global_load_lds_dwordx4 v[250:251], off
	s_waitcnt vmcnt(8)
	s_waitcnt lgkmcnt(0)
	s_barrier
; #define PG8_STAGE(bufoff, gbase, voff) do { _Pragma("unroll") for (int _i = 0; _i < 2; ++_i) \
;         __builtin_amdgcn_global_load_lds((const unsigned*)((const char*)(gbase) + (voff)[_i]), (PG8_LAS unsigned*)(lds + (bufoff) + ldsw + _i * 8192), 16, 0, 0); } while (0)
; #define PG8_LDA(dst, b, h) do { _Pragma("unroll") for (int m = 0; m < 4; ++m) _Pragma("unroll") for (int k = 0; k < 2; ++k) dst[m][k] = *(const PG8_LAS bf16x8*)(lds + PG8_SA(b, h) + aoff + m * 2048 + k * 1024); } while (0)
; #define PG8_LDB(dst, b, h) do { _Pragma("unroll") for (int n = 0; n < 2; ++n) _Pragma("unroll") for (int k = 0; k < 2; ++k) dst[n][k] = *(const PG8_LAS bf16x8*)(lds + PG8_SB(b, h) + boff + n * 2048 + k * 1024); } while (0)
; #define PG8_MMA(ai, bj, At, Bt) do { __builtin_amdgcn_s_setprio(1); _Pragma("unroll") for (int m = 0; m < 4; ++m) _Pragma("unroll") for (int n = 0; n < 2; ++n) _Pragma("unroll") for (int k = 0; k < 2; ++k) \
;         acc[ai][bj][m][n] = __builtin_amdgcn_mfma_f32_16x16x32_bf16(Bt[n][k], At[m][k], acc[ai][bj][m][n], 0, 0, 0); __builtin_amdgcn_s_setprio(0); } while (0)
; #define PG8_WAIT_V(n) asm volatile("s_waitcnt vmcnt(" #n ")" ::: "memory")
; #define PG8_WAIT_L(n) asm volatile("s_waitcnt lgkmcnt(" #n ")" ::: "memory")
; #define PG8_BAR __builtin_amdgcn_s_barrier()
; #define PG8_SCHED __builtin_amdgcn_sched_barrier(0)
; template <class Epi, class Sched, bool ALIGN_EPI = false, bool SP2 = false>
; __device__ __forceinline__ void gemm_phase(PG8_LAS unsigned char* lds, const Gemm g, const Sched& S, const Epi& E) {
;     ...
;             PG8_WAIT_V(8); PG8_WAIT_L(0); PG8_BAR; PG8_MMA(1, 0, At, B0); PG8_MMA(1, 1, At, B1); PG8_BAR; PG8_SCHED;
;             PG8_LDB(B0, 1, 0); PG8_LDB(B1, 1, 1); PG8_SCHED; PG8_LDA(At, 1, 0); PG8_STAGE(PG8_SA(0, 1), a2 + hstep, voffA);
;             PG8_WAIT_V(8); PG8_WAIT_L(0); PG8_BAR; PG8_MMA(0, 0, At, B0); PG8_MMA(0, 1, At, B1); PG8_BAR; PG8_SCHED;
	s_setprio 1
	s_waitcnt lgkmcnt(0)
	v_mfma_f32_16x16x32_bf16 v[80:83], v[122:125], v[180:183], v[80:83]
	v_mfma_f32_16x16x32_bf16 v[144:147], v[130:133], v[180:183], v[144:147]
	v_mfma_f32_16x16x32_bf16 v[64:67], v[122:125], v[188:191], v[64:67]
	v_mfma_f32_16x16x32_bf16 v[134:137], v[130:133], v[188:191], v[136:139]
	v_mfma_f32_16x16x32_bf16 v[68:71], v[122:125], v[208:211], v[68:71]
	v_mfma_f32_16x16x32_bf16 v[116:119], v[130:133], v[208:211], v[116:119]
	v_mfma_f32_16x16x32_bf16 v[52:55], v[122:125], v[236:239], v[52:55]
	v_mfma_f32_16x16x32_bf16 v[112:115], v[130:133], v[236:239], v[112:115]
	v_mfma_f32_16x16x32_bf16 v[80:83], v[126:129], v[184:187], v[80:83]
	v_mfma_f32_16x16x32_bf16 v[144:147], v[140:143], v[184:187], v[144:147]
	v_mfma_f32_16x16x32_bf16 v[64:67], v[126:129], v[192:195], v[64:67]
	v_mfma_f32_16x16x32_bf16 v[134:137], v[140:143], v[192:195], v[134:137]
	v_mfma_f32_16x16x32_bf16 v[68:71], v[126:129], v[212:215], v[68:71]
	v_mfma_f32_16x16x32_bf16 v[116:119], v[140:143], v[212:215], v[116:119]
	v_mfma_f32_16x16x32_bf16 v[52:55], v[126:129], v[240:243], v[52:55]
	v_mfma_f32_16x16x32_bf16 v[112:115], v[140:143], v[240:243], v[112:115]
	v_mfma_f32_16x16x32_bf16 v[48:51], v[164:167], v[180:183], v[48:51]
	v_mfma_f32_16x16x32_bf16 v[16:19], v[172:175], v[180:183], v[16:19]
	v_mfma_f32_16x16x32_bf16 v[44:47], v[164:167], v[188:191], v[44:47]
	v_mfma_f32_16x16x32_bf16 v[12:15], v[172:175], v[188:191], v[12:15]
	v_mfma_f32_16x16x32_bf16 v[40:43], v[164:167], v[208:211], v[40:43]
	v_mfma_f32_16x16x32_bf16 v[8:11], v[172:175], v[208:211], v[8:11]
	v_mfma_f32_16x16x32_bf16 v[36:39], v[164:167], v[236:239], v[36:39]
	v_mfma_f32_16x16x32_bf16 v[4:7], v[172:175], v[236:239], v[4:7]
	v_mfma_f32_16x16x32_bf16 v[48:51], v[168:171], v[184:187], v[48:51]
	v_mfma_f32_16x16x32_bf16 v[16:19], v[176:179], v[184:187], v[16:19]
	v_mfma_f32_16x16x32_bf16 v[44:47], v[168:171], v[192:195], v[44:47]
	v_mfma_f32_16x16x32_bf16 v[12:15], v[176:179], v[192:195], v[12:15]
	v_mfma_f32_16x16x32_bf16 v[40:43], v[168:171], v[212:215], v[40:43]
	v_mfma_f32_16x16x32_bf16 v[8:11], v[176:179], v[212:215], v[8:11]
	v_mfma_f32_16x16x32_bf16 v[36:39], v[168:171], v[240:243], v[36:39]
	v_mfma_f32_16x16x32_bf16 v[4:7], v[176:179], v[240:243], v[4:7]
	s_setprio 0
	s_barrier
	s_add_i32 s41, 0, 0x18000
	v_add_u32_e32 v138, s41, v120
	s_add_i32 s46, 0, 0x1c000
	ds_read_b128 v[122:125], v138
	ds_read_b128 v[126:129], v138 offset:1024
	ds_read_b128 v[130:133], v138 offset:2048
	ds_read_b128 v[140:143], v138 offset:3072
	v_add_u32_e32 v138, s46, v120
	ds_read_b128 v[164:167], v138
	ds_read_b128 v[168:171], v138 offset:1024
	ds_read_b128 v[172:175], v138 offset:2048
	ds_read_b128 v[176:179], v138 offset:3072
	s_add_u32 s20, s20, s77
	s_addc_u32 s21, s21, 0
	s_mov_b32 m0, s25
	v_lshl_add_u64 v[138:139], s[20:21], 0, v[102:103]
	ds_read_b128 v[180:183], v121 offset:32768
	ds_read_b128 v[184:187], v121 offset:33792
	ds_read_b128 v[188:191], v121 offset:34816
	ds_read_b128 v[192:195], v121 offset:35840
	ds_read_b128 v[208:211], v121 offset:36864
	ds_read_b128 v[212:215], v121 offset:37888
	ds_read_b128 v[236:239], v121 offset:38912
	ds_read_b128 v[240:243], v121 offset:39936
	global_load_lds_dwordx4 v[138:139], off
	v_lshl_add_u64 v[138:139], s[20:21], 0, v[100:101]
	s_mov_b32 m0, s27
	s_nop 0
	global_load_lds_dwordx4 v[138:139], off
	s_waitcnt vmcnt(8)
	s_waitcnt lgkmcnt(0)
	s_barrier
	s_setprio 1
	s_waitcnt lgkmcnt(0)
	v_mfma_f32_16x16x32_bf16 v[96:99], v[122:125], v[180:183], v[96:99]
	v_mfma_f32_16x16x32_bf16 v[160:163], v[130:133], v[180:183], v[160:163]
	v_mfma_f32_16x16x32_bf16 v[88:91], v[122:125], v[188:191], v[88:91]
	v_mfma_f32_16x16x32_bf16 v[156:159], v[130:133], v[188:191], v[156:159]
	v_mfma_f32_16x16x32_bf16 v[92:95], v[122:125], v[208:211], v[92:95]
	v_mfma_f32_16x16x32_bf16 v[152:155], v[130:133], v[208:211], v[152:155]
	v_mfma_f32_16x16x32_bf16 v[72:75], v[122:125], v[236:239], v[72:75]
	v_mfma_f32_16x16x32_bf16 v[148:151], v[130:133], v[236:239], v[148:151]
	v_mfma_f32_16x16x32_bf16 v[96:99], v[126:129], v[184:187], v[96:99]
	v_mfma_f32_16x16x32_bf16 v[160:163], v[140:143], v[184:187], v[160:163]
	v_mfma_f32_16x16x32_bf16 v[88:91], v[126:129], v[192:195], v[88:91]
	v_mfma_f32_16x16x32_bf16 v[156:159], v[140:143], v[192:195], v[156:159]
	v_mfma_f32_16x16x32_bf16 v[92:95], v[126:129], v[212:215], v[92:95]
	v_mfma_f32_16x16x32_bf16 v[152:155], v[140:143], v[212:215], v[152:155]
	v_mfma_f32_16x16x32_bf16 v[72:75], v[126:129], v[240:243], v[72:75]
	v_mfma_f32_16x16x32_bf16 v[148:151], v[140:143], v[240:243], v[148:151]
	v_mfma_f32_16x16x32_bf16 v[84:87], v[164:167], v[180:183], v[84:87]
	v_mfma_f32_16x16x32_bf16 v[32:35], v[172:175], v[180:183], v[32:35]
	v_mfma_f32_16x16x32_bf16 v[76:79], v[164:167], v[188:191], v[76:79]
	v_mfma_f32_16x16x32_bf16 v[28:31], v[172:175], v[188:191], v[28:31]
	v_mfma_f32_16x16x32_bf16 v[60:63], v[164:167], v[208:211], v[60:63]
	v_mfma_f32_16x16x32_bf16 v[24:27], v[172:175], v[208:211], v[24:27]
	v_mfma_f32_16x16x32_bf16 v[56:59], v[164:167], v[236:239], v[56:59]
	v_mfma_f32_16x16x32_bf16 v[20:23], v[172:175], v[236:239], v[20:23]
	v_mfma_f32_16x16x32_bf16 v[84:87], v[168:171], v[184:187], v[84:87]
	v_mfma_f32_16x16x32_bf16 v[32:35], v[176:179], v[184:187], v[32:35]
	v_mfma_f32_16x16x32_bf16 v[76:79], v[168:171], v[192:195], v[76:79]
	v_mfma_f32_16x16x32_bf16 v[28:31], v[176:179], v[192:195], v[28:31]
	v_mfma_f32_16x16x32_bf16 v[60:63], v[168:171], v[212:215], v[60:63]
	v_mfma_f32_16x16x32_bf16 v[24:27], v[176:179], v[212:215], v[24:27]
	v_mfma_f32_16x16x32_bf16 v[56:59], v[168:171], v[240:243], v[56:59]
	v_mfma_f32_16x16x32_bf16 v[20:23], v[176:179], v[240:243], v[20:23]
	s_setprio 0
	s_barrier
; #define PG8_STAGE(bufoff, gbase, voff) do { _Pragma("unroll") for (int _i = 0; _i < 2; ++_i) \
;         __builtin_amdgcn_global_load_lds((const unsigned*)((const char*)(gbase) + (voff)[_i]), (PG8_LAS unsigned*)(lds + (bufoff) + ldsw + _i * 8192), 16, 0, 0); } while (0)
; #define PG8_LDA(dst, b, h) do { _Pragma("unroll") for (int m = 0; m < 4; ++m) _Pragma("unroll") for (int k = 0; k < 2; ++k) dst[m][k] = *(const PG8_LAS bf16x8*)(lds + PG8_SA(b, h) + aoff + m * 2048 + k * 1024); } while (0)
; #define PG8_MMA(ai, bj, At, Bt) do { __builtin_amdgcn_s_setprio(1); _Pragma("unroll") for (int m = 0; m < 4; ++m) _Pragma("unroll") for (int n = 0; n < 2; ++n) _Pragma("unroll") for (int k = 0; k < 2; ++k) \
;         acc[ai][bj][m][n] = __builtin_amdgcn_mfma_f32_16x16x32_bf16(Bt[n][k], At[m][k], acc[ai][bj][m][n], 0, 0, 0); __builtin_amdgcn_s_setprio(0); } while (0)
; #define PG8_WAIT_V(n) asm volatile("s_waitcnt vmcnt(" #n ")" ::: "memory")
; #define PG8_WAIT_L(n) asm volatile("s_waitcnt lgkmcnt(" #n ")" ::: "memory")
; #define PG8_BAR __builtin_amdgcn_s_barrier()
; #define PG8_SCHED __builtin_amdgcn_sched_barrier(0)
; template <class Epi, class Sched, bool ALIGN_EPI = false, bool SP2 = false>
; __device__ __forceinline__ void gemm_phase(PG8_LAS unsigned char* lds, const Gemm g, const Sched& S, const Epi& E) {
;     ...
;             PG8_LDA(At, 1, 1); PG8_STAGE(PG8_SB(1, 0), b3, voffB); PG8_STAGE(PG8_SB(1, 1), b3 + hstep, voffB); PG8_STAGE(PG8_SA(1, 0), a3, voffA);
;             PG8_WAIT_V(8); PG8_WAIT_L(0); PG8_BAR; PG8_MMA(1, 0, At, B0); PG8_MMA(1, 1, At, B1); PG8_BAR; PG8_SCHED;
;     ...
;         if (!has_next) break;
; #pragma unroll
;         for (int a = 0; a < 2; ++a)
; #pragma unroll
;             for (int b = 0; b < 2; ++b)
; #pragma unroll
;                 for (int m = 0; m < 4; ++m)
; #pragma unroll
;                     for (int n = 0; n < 2; ++n) acc[a][b][m][n] = (f32x4){0.f, 0.f, 0.f, 0.f};
;         cur = nxt; cA = nA; cB = nB; ++ui;
	s_add_i32 s20, s41, s22
	v_lshl_add_u64 v[138:139], v[204:205], 0, s[42:43]
	s_mov_b32 m0, s20
	ds_read_b128 v[180:183], v121 offset:49152
	ds_read_b128 v[184:187], v121 offset:50176
	ds_read_b128 v[188:191], v121 offset:51200
	ds_read_b128 v[192:195], v121 offset:52224
	ds_read_b128 v[208:211], v121 offset:53248
	ds_read_b128 v[212:215], v121 offset:54272
	ds_read_b128 v[236:239], v121 offset:55296
	ds_read_b128 v[240:243], v121 offset:56320
	global_load_lds_dwordx4 v[138:139], off
	v_lshl_add_u64 v[138:139], v[216:217], 0, s[42:43]
	s_add_i32 m0, s20, 0x2000
	s_add_i32 s20, s46, s22
	global_load_lds_dwordx4 v[138:139], off
	v_lshl_add_u64 v[138:139], v[244:245], 0, s[42:43]
	s_mov_b32 m0, s20
	s_nop 0
	global_load_lds_dwordx4 v[138:139], off
	v_lshl_add_u64 v[138:139], v[246:247], 0, s[42:43]
	s_add_i32 m0, s20, 0x2000
	s_nop 0
	global_load_lds_dwordx4 v[138:139], off
	v_lshl_add_u64 v[138:139], v[248:249], 0, s[42:43]
	s_mov_b32 m0, s28
	s_nop 0
	global_load_lds_dwordx4 v[138:139], off
	v_lshl_add_u64 v[138:139], v[250:251], 0, s[42:43]
	s_mov_b32 m0, s29
	s_nop 0
	global_load_lds_dwordx4 v[138:139], off
	s_waitcnt vmcnt(8)
	s_waitcnt lgkmcnt(0)
	s_barrier
	s_setprio 1
	s_waitcnt lgkmcnt(0)
	v_mfma_f32_16x16x32_bf16 v[80:83], v[122:125], v[180:183], v[80:83]
	v_mfma_f32_16x16x32_bf16 v[144:147], v[130:133], v[180:183], v[144:147]
	v_mfma_f32_16x16x32_bf16 v[64:67], v[122:125], v[188:191], v[64:67]
	v_mfma_f32_16x16x32_bf16 v[134:137], v[130:133], v[188:191], v[134:137]
	v_mfma_f32_16x16x32_bf16 v[68:71], v[122:125], v[208:211], v[68:71]
	v_mfma_f32_16x16x32_bf16 v[116:119], v[130:133], v[208:211], v[116:119]
	v_mfma_f32_16x16x32_bf16 v[52:55], v[122:125], v[236:239], v[52:55]
	v_mfma_f32_16x16x32_bf16 v[112:115], v[130:133], v[236:239], v[112:115]
	v_mfma_f32_16x16x32_bf16 v[80:83], v[126:129], v[184:187], v[80:83]
	v_mfma_f32_16x16x32_bf16 v[144:147], v[140:143], v[184:187], v[144:147]
	v_mfma_f32_16x16x32_bf16 v[64:67], v[126:129], v[192:195], v[64:67]
	v_mfma_f32_16x16x32_bf16 v[136:139], v[140:143], v[192:195], v[134:137]
	v_mfma_f32_16x16x32_bf16 v[68:71], v[126:129], v[212:215], v[68:71]
	v_mfma_f32_16x16x32_bf16 v[116:119], v[140:143], v[212:215], v[116:119]
	v_mfma_f32_16x16x32_bf16 v[52:55], v[126:129], v[240:243], v[52:55]
	v_mfma_f32_16x16x32_bf16 v[112:115], v[140:143], v[240:243], v[112:115]
	v_mfma_f32_16x16x32_bf16 v[48:51], v[164:167], v[180:183], v[48:51]
	v_mfma_f32_16x16x32_bf16 v[16:19], v[172:175], v[180:183], v[16:19]
	v_mfma_f32_16x16x32_bf16 v[44:47], v[164:167], v[188:191], v[44:47]
	v_mfma_f32_16x16x32_bf16 v[12:15], v[172:175], v[188:191], v[12:15]
	v_mfma_f32_16x16x32_bf16 v[40:43], v[164:167], v[208:211], v[40:43]
	v_mfma_f32_16x16x32_bf16 v[8:11], v[172:175], v[208:211], v[8:11]
	v_mfma_f32_16x16x32_bf16 v[36:39], v[164:167], v[236:239], v[36:39]
	v_mfma_f32_16x16x32_bf16 v[4:7], v[172:175], v[236:239], v[4:7]
	v_mfma_f32_16x16x32_bf16 v[48:51], v[168:171], v[184:187], v[48:51]
	v_mfma_f32_16x16x32_bf16 v[16:19], v[176:179], v[184:187], v[16:19]
	v_mfma_f32_16x16x32_bf16 v[44:47], v[168:171], v[192:195], v[44:47]
	v_mfma_f32_16x16x32_bf16 v[12:15], v[176:179], v[192:195], v[12:15]
	v_mfma_f32_16x16x32_bf16 v[40:43], v[168:171], v[212:215], v[40:43]
	v_mfma_f32_16x16x32_bf16 v[8:11], v[176:179], v[212:215], v[8:11]
	v_mfma_f32_16x16x32_bf16 v[36:39], v[168:171], v[240:243], v[36:39]
	v_mfma_f32_16x16x32_bf16 v[4:7], v[176:179], v[240:243], v[4:7]
	s_setprio 0
	s_barrier
	s_add_u32 s18, s18, 0x100
	s_addc_u32 s19, s19, 0
	v_lshl_add_u64 v[110:111], v[110:111], 0, s[92:93]
	v_lshl_add_u64 v[108:109], v[108:109], 0, s[92:93]
	s_cmp_ge_u32 s40, s97
	s_mov_b32 s20, s40
	s_cbranch_scc0 .LBB0_720
	s_and_b64 vcc, exec, s[4:5]
	s_cbranch_vccnz .LBB0_708
	v_mov_b32_e32 v4, 0
	s_mov_b32 s10, s31
	s_mov_b32 s39, s34
	s_mov_b64 s[8:9], s[14:15]
	s_mov_b64 s[12:13], s[0:1]
	s_mov_b32 s30, s35
	v_mov_b32_e32 v5, v4
	v_mov_b32_e32 v6, v4
	v_mov_b32_e32 v7, v4
	v_mov_b32_e32 v36, v4
	v_mov_b32_e32 v37, v4
	v_mov_b32_e32 v38, v4
	v_mov_b32_e32 v39, v4
	v_mov_b32_e32 v8, v4
	v_mov_b32_e32 v9, v4
	v_mov_b32_e32 v10, v4
	v_mov_b32_e32 v11, v4
	v_mov_b32_e32 v40, v4
	v_mov_b32_e32 v41, v4
	v_mov_b32_e32 v42, v4
	v_mov_b32_e32 v43, v4
	v_mov_b32_e32 v12, v4
	v_mov_b32_e32 v13, v4
	v_mov_b32_e32 v14, v4
	v_mov_b32_e32 v15, v4
	v_mov_b32_e32 v44, v4
	v_mov_b32_e32 v45, v4
	v_mov_b32_e32 v46, v4
	v_mov_b32_e32 v47, v4
	v_mov_b32_e32 v16, v4
	v_mov_b32_e32 v17, v4
	v_mov_b32_e32 v18, v4
	v_mov_b32_e32 v19, v4
	v_mov_b32_e32 v48, v4
	v_mov_b32_e32 v49, v4
	v_mov_b32_e32 v50, v4
	v_mov_b32_e32 v51, v4
	v_mov_b32_e32 v112, v4
	v_mov_b32_e32 v113, v4
	v_mov_b32_e32 v114, v4
	v_mov_b32_e32 v115, v4
	v_mov_b32_e32 v52, v4
	v_mov_b32_e32 v53, v4
	v_mov_b32_e32 v54, v4
	v_mov_b32_e32 v55, v4
	v_mov_b32_e32 v116, v4
	v_mov_b32_e32 v117, v4
	v_mov_b32_e32 v118, v4
	v_mov_b32_e32 v119, v4
	v_mov_b32_e32 v68, v4
	v_mov_b32_e32 v69, v4
	v_mov_b32_e32 v70, v4
	v_mov_b32_e32 v71, v4
	v_mov_b32_e32 v136, v4
	v_mov_b32_e32 v137, v4
	v_mov_b32_e32 v138, v4
	v_mov_b32_e32 v139, v4
	v_mov_b32_e32 v64, v4
	v_mov_b32_e32 v65, v4
	v_mov_b32_e32 v66, v4
	v_mov_b32_e32 v67, v4
	v_mov_b32_e32 v144, v4
	v_mov_b32_e32 v145, v4
	v_mov_b32_e32 v146, v4
	v_mov_b32_e32 v147, v4
	v_mov_b32_e32 v80, v4
	v_mov_b32_e32 v81, v4
	v_mov_b32_e32 v82, v4
	v_mov_b32_e32 v83, v4
	v_mov_b32_e32 v20, v4
	v_mov_b32_e32 v21, v4
	v_mov_b32_e32 v22, v4
	v_mov_b32_e32 v23, v4
	v_mov_b32_e32 v56, v4
	v_mov_b32_e32 v57, v4
	v_mov_b32_e32 v58, v4
	v_mov_b32_e32 v59, v4
	v_mov_b32_e32 v24, v4
	v_mov_b32_e32 v25, v4
	v_mov_b32_e32 v26, v4
	v_mov_b32_e32 v27, v4
	v_mov_b32_e32 v60, v4
	v_mov_b32_e32 v61, v4
	v_mov_b32_e32 v62, v4
	v_mov_b32_e32 v63, v4
	v_mov_b32_e32 v28, v4
	v_mov_b32_e32 v29, v4
	v_mov_b32_e32 v30, v4
	v_mov_b32_e32 v31, v4
	v_mov_b32_e32 v76, v4
	v_mov_b32_e32 v77, v4
	v_mov_b32_e32 v78, v4
	v_mov_b32_e32 v79, v4
	v_mov_b32_e32 v32, v4
	v_mov_b32_e32 v33, v4
	v_mov_b32_e32 v34, v4
	v_mov_b32_e32 v35, v4
	v_mov_b32_e32 v84, v4
	v_mov_b32_e32 v85, v4
	v_mov_b32_e32 v86, v4
	v_mov_b32_e32 v87, v4
	v_mov_b32_e32 v148, v4
	v_mov_b32_e32 v149, v4
	v_mov_b32_e32 v150, v4
	v_mov_b32_e32 v151, v4
	v_mov_b32_e32 v72, v4
	v_mov_b32_e32 v73, v4
	v_mov_b32_e32 v74, v4
	v_mov_b32_e32 v75, v4
	v_mov_b32_e32 v152, v4
	v_mov_b32_e32 v153, v4
	v_mov_b32_e32 v154, v4
	v_mov_b32_e32 v155, v4
	v_mov_b32_e32 v92, v4
	v_mov_b32_e32 v93, v4
	v_mov_b32_e32 v94, v4
	v_mov_b32_e32 v95, v4
	v_mov_b32_e32 v156, v4
	v_mov_b32_e32 v157, v4
	v_mov_b32_e32 v158, v4
	v_mov_b32_e32 v159, v4
	v_mov_b32_e32 v88, v4
	v_mov_b32_e32 v89, v4
	v_mov_b32_e32 v90, v4
	v_mov_b32_e32 v91, v4
	v_mov_b32_e32 v160, v4
	v_mov_b32_e32 v161, v4
	v_mov_b32_e32 v162, v4
	v_mov_b32_e32 v163, v4
	v_mov_b32_e32 v96, v4
	v_mov_b32_e32 v97, v4
	v_mov_b32_e32 v98, v4
	v_mov_b32_e32 v99, v4
	s_branch .LBB0_708

; __device__ __forceinline__ void panel_rstd(const f32x4 (&v)[2][2][4][2], const Unit& u, int wr, int wc, int fr, int fq, PG8_LAS unsigned char* lds, int wid, int lane,
;                                            float* xslots, unsigned* cnt, unsigned want, float eps) {
;     ...
; #pragma unroll
;     for (int ai = 0; ai < 2; ++ai)
; #pragma unroll
;         for (int m = 0; m < 4; ++m) {
;             float s = 0.f;
; #pragma unroll
;             for (int bj = 0; bj < 2; ++bj)
; #pragma unroll
;                 for (int n = 0; n < 2; ++n) { const f32x4 x = v[ai][bj][m][n]; s += (x[0] * x[0] + x[1] * x[1]) + (x[2] * x[2] + x[3] * x[3]); }
;             s += __shfl_xor(s, 16); s += __shfl_xor(s, 32);
;             if (fq == 0) P[(ai * HALF + wr * 64 + m * 16 + fr) * 4 + wc] = s;
;         }
;     __device__ __forceinline__ void fused(f32x4 (&acc)[2][2][4][2], const Unit& u, int wr, int wc, int fr, int fq, PG8_LAS unsigned char* lds, int wid, int lane) const {
;     ...
;         u32x4v pre[2][4][2];
; #pragma unroll
;         for (int ai = 0; ai < 2; ++ai)
; #pragma unroll
;             for (int m = 0; m < 4; ++m)
; #pragma unroll
;                 for (int bj = 0; bj < 2; ++bj) pre[ai][m][bj] = *(const u32x4v*)(X + (size_t)(u.pm * BM + ai * HALF + wr * 64 + m * 16 + fr) * 1024 + col0 + bj * HALF);
;         panel_rstd(acc, u, wr, wc, fr, fq, lds, wid, lane, xbuf, cnt, want1, 1e-6f);
.LBB0_725:
	s_lshl_b32 s0, s26, 5
	s_lshl_b32 s1, s10, 8
	s_lshl_b32 s40, s39, 8
	v_lshrrev_b32_e32 v0, 1, v206
	s_or_b32 s0, s1, s0
	s_add_i32 s4, s40, s33
	v_and_or_b32 v0, v0, 24, s0
	v_readlane_b32 s12, v255, 3
	v_readlane_b32 s28, v255, 7
	v_readlane_b32 s14, v255, 1
	v_readlane_b32 s30, v255, 5
	v_readlane_b32 s0, v252, 50
	v_or_b32_e32 v100, s4, v219
	v_readlane_b32 s13, v255, 4
	v_readlane_b32 s29, v255, 8
	v_readlane_b32 s15, v255, 2
	v_readlane_b32 s31, v255, 6
	v_readlane_b32 s1, v252, 51
	v_ashrrev_i32_e32 v1, 31, v0
	v_ashrrev_i32_e32 v101, 31, v100
	s_barrier
	v_readlane_b32 s22, v253, 6
	v_readlane_b32 s20, v255, 9
	v_readlane_b32 s24, v253, 4
	v_readlane_b32 s18, v255, 11
	v_lshl_add_u64 v[204:205], v[0:1], 1, s[0:1]
	v_lshlrev_b64 v[102:103], 11, v[100:101]
	v_readlane_b32 s23, v253, 7
	v_readlane_b32 s21, v255, 10
	v_readlane_b32 s25, v253, 5
	v_readlane_b32 s41, v255, 36
	v_readlane_b32 s19, v255, 12
	v_lshl_add_u64 v[102:103], v[204:205], 0, v[102:103]
	flat_load_dwordx4 v[192:195], v[102:103]
	flat_load_dwordx4 v[140:143], v[102:103] offset:256
	v_or_b32_e32 v102, 16, v100
	v_ashrrev_i32_e32 v103, 31, v102
	v_lshlrev_b64 v[102:103], 11, v[102:103]
	v_lshl_add_u64 v[102:103], v[204:205], 0, v[102:103]
	flat_load_dwordx4 v[188:191], v[102:103]
	flat_load_dwordx4 v[132:135], v[102:103] offset:256
	v_or_b32_e32 v102, 32, v100
	v_ashrrev_i32_e32 v103, 31, v102
	v_lshlrev_b64 v[102:103], 11, v[102:103]
	v_lshl_add_u64 v[102:103], v[204:205], 0, v[102:103]
	flat_load_dwordx4 v[184:187], v[102:103]
	flat_load_dwordx4 v[128:131], v[102:103] offset:256
	v_or_b32_e32 v102, 48, v100
	v_ashrrev_i32_e32 v103, 31, v102
	v_lshlrev_b64 v[102:103], 11, v[102:103]
	v_lshl_add_u64 v[102:103], v[204:205], 0, v[102:103]
	flat_load_dwordx4 v[180:183], v[102:103]
	flat_load_dwordx4 v[124:127], v[102:103] offset:256
	v_add_u32_e32 v102, 0x80, v100
	v_ashrrev_i32_e32 v103, 31, v102
	v_lshlrev_b64 v[102:103], 11, v[102:103]
	v_lshl_add_u64 v[102:103], v[204:205], 0, v[102:103]
	flat_load_dwordx4 v[176:179], v[102:103]
	flat_load_dwordx4 v[120:123], v[102:103] offset:256
	v_add_u32_e32 v102, 0x90, v100
	v_ashrrev_i32_e32 v103, 31, v102
	v_lshlrev_b64 v[102:103], 11, v[102:103]
	v_lshl_add_u64 v[102:103], v[204:205], 0, v[102:103]
	flat_load_dwordx4 v[172:175], v[102:103]
	flat_load_dwordx4 v[108:111], v[102:103] offset:256
	v_add_u32_e32 v102, 0xa0, v100
	v_add_u32_e32 v100, 0xb0, v100
	v_ashrrev_i32_e32 v103, 31, v102
	v_ashrrev_i32_e32 v101, 31, v100
	v_lshlrev_b64 v[102:103], 11, v[102:103]
	v_lshlrev_b64 v[100:101], 11, v[100:101]
	v_lshl_add_u64 v[102:103], v[204:205], 0, v[102:103]
	v_lshl_add_u64 v[100:101], v[204:205], 0, v[100:101]
	flat_load_dwordx4 v[168:171], v[102:103]
	flat_load_dwordx4 v[104:107], v[102:103] offset:256
	flat_load_dwordx4 v[164:167], v[100:101]
	s_nop 0
	flat_load_dwordx4 v[100:103], v[100:101] offset:256
	v_mul_f32_e32 v207, v97, v97
	v_mul_f32_e32 v208, v99, v99
	v_fmac_f32_e32 v207, v96, v96
	v_fmac_f32_e32 v208, v98, v98
	v_add_f32_e32 v207, v207, v208
	v_mul_f32_e32 v208, v161, v161
	v_mul_f32_e32 v209, v163, v163
	v_fmac_f32_e32 v208, v160, v160
	v_fmac_f32_e32 v209, v162, v162
	v_add_f32_e32 v208, v208, v209
	v_add_f32_e32 v207, v208, v207
	v_mul_f32_e32 v208, v85, v85
	v_mul_f32_e32 v209, v87, v87
	v_fmac_f32_e32 v208, v84, v84
	v_fmac_f32_e32 v209, v86, v86
	v_add_f32_e32 v208, v208, v209
	v_xor_b32_e32 v2, 16, v225
	v_add_f32_e32 v207, v208, v207
	v_mul_f32_e32 v208, v33, v33
	v_mul_f32_e32 v209, v35, v35
	v_cmp_lt_i32_e32 vcc, v2, v230
	v_fmac_f32_e32 v208, v32, v32
	v_fmac_f32_e32 v209, v34, v34
	v_cndmask_b32_e32 v2, v225, v2, vcc
	v_add_f32_e32 v208, v208, v209
	v_lshlrev_b32_e32 v2, 2, v2
	v_add_f32_e32 v207, v208, v207
	v_mov_b32_e32 v208, v207
	s_nop 1
	v_permlane16_swap_b32_e32 v208, v207
	v_xor_b32_e32 v209, 32, v225
	v_cmp_lt_i32_e32 vcc, v209, v230
	s_lshl_b32 s4, s26, 2
	s_add_i32 s48, s4, 0
	v_cndmask_b32_e32 v209, v225, v209, vcc
	v_lshlrev_b32_e32 v221, 2, v209
	s_nop 0
	v_add_f32_e32 v207, v207, v208
	v_mov_b32_e32 v209, v207
	s_nop 1
	v_permlane32_swap_b32_e32 v209, v207
	v_and_b32_e32 v208, 63, v206
	v_cmp_gt_u32_e64 s[0:1], 16, v208
	s_and_saveexec_b64 s[4:5], s[0:1]
	s_cbranch_execz .LBB0_727
	s_lshl_b32 s6, s38, 10
	s_add_i32 s6, s48, s6
	v_lshl_add_u32 v210, v219, 4, s6
	s_nop 0
	v_add_f32_e32 v207, v207, v209
	ds_write_b32 v210, v207
.LBB0_727:
	s_or_b64 exec, exec, s[4:5]
	v_mul_f32_e32 v207, v89, v89
	s_nop 0
	v_mul_f32_e32 v209, v91, v91
	v_fmac_f32_e32 v207, v88, v88
	v_fmac_f32_e32 v209, v90, v90
	v_add_f32_e32 v207, v207, v209
	v_mul_f32_e32 v209, v157, v157
	v_mul_f32_e32 v210, v159, v159
	v_fmac_f32_e32 v209, v156, v156
	v_fmac_f32_e32 v210, v158, v158
	v_add_f32_e32 v209, v209, v210
	v_add_f32_e32 v207, v209, v207
	v_mul_f32_e32 v209, v77, v77
	v_mul_f32_e32 v210, v79, v79
	v_fmac_f32_e32 v209, v76, v76
	v_fmac_f32_e32 v210, v78, v78
	v_add_f32_e32 v209, v209, v210
	v_add_f32_e32 v207, v209, v207
	v_mul_f32_e32 v209, v29, v29
	v_mul_f32_e32 v210, v31, v31
	v_fmac_f32_e32 v209, v28, v28
	v_fmac_f32_e32 v210, v30, v30
	v_add_f32_e32 v209, v209, v210
	v_add_f32_e32 v207, v209, v207
	v_mov_b32_e32 v209, v207
	s_nop 1
	v_permlane16_swap_b32_e32 v209, v207
	s_nop 0
	v_add_f32_e32 v207, v207, v209
	v_mov_b32_e32 v209, v207
	s_nop 1
	v_permlane32_swap_b32_e32 v209, v207
	s_and_saveexec_b64 s[4:5], s[0:1]
	s_cbranch_execz .LBB0_729
	s_lshl_b32 s6, s38, 10
	s_add_i32 s6, s48, s6
	v_lshl_add_u32 v210, v219, 4, s6
	s_nop 0
	v_add_f32_e32 v207, v207, v209
	ds_write_b32 v210, v207 offset:256
; __device__ __forceinline__ void panel_rstd(const f32x4 (&v)[2][2][4][2], const Unit& u, int wr, int wc, int fr, int fq, PG8_LAS unsigned char* lds, int wid, int lane,
;                                            float* xslots, unsigned* cnt, unsigned want, float eps) {
;     ...
; #pragma unroll
;     for (int ai = 0; ai < 2; ++ai)
; #pragma unroll
;         for (int m = 0; m < 4; ++m) {
;             float s = 0.f;
; #pragma unroll
;             for (int bj = 0; bj < 2; ++bj)
; #pragma unroll
;                 for (int n = 0; n < 2; ++n) { const f32x4 x = v[ai][bj][m][n]; s += (x[0] * x[0] + x[1] * x[1]) + (x[2] * x[2] + x[3] * x[3]); }
;             s += __shfl_xor(s, 16); s += __shfl_xor(s, 32);
;             if (fq == 0) P[(ai * HALF + wr * 64 + m * 16 + fr) * 4 + wc] = s;
;         }
.LBB0_729:
	s_or_b64 exec, exec, s[4:5]
	v_mul_f32_e32 v207, v93, v93
	s_nop 0
	v_mul_f32_e32 v209, v95, v95
	v_fmac_f32_e32 v207, v92, v92
	v_fmac_f32_e32 v209, v94, v94
	v_add_f32_e32 v207, v207, v209
	v_mul_f32_e32 v209, v153, v153
	v_mul_f32_e32 v210, v155, v155
	v_fmac_f32_e32 v209, v152, v152
	v_fmac_f32_e32 v210, v154, v154
	v_add_f32_e32 v209, v209, v210
	v_add_f32_e32 v207, v209, v207
	v_mul_f32_e32 v209, v61, v61
	v_mul_f32_e32 v210, v63, v63
	v_fmac_f32_e32 v209, v60, v60
	v_fmac_f32_e32 v210, v62, v62
	v_add_f32_e32 v209, v209, v210
	v_add_f32_e32 v207, v209, v207
	v_mul_f32_e32 v209, v25, v25
	v_mul_f32_e32 v210, v27, v27
	v_fmac_f32_e32 v209, v24, v24
	v_fmac_f32_e32 v210, v26, v26
	v_add_f32_e32 v209, v209, v210
	v_add_f32_e32 v207, v209, v207
	v_mov_b32_e32 v209, v207
	s_nop 1
	v_permlane16_swap_b32_e32 v209, v207
	s_nop 0
	v_add_f32_e32 v207, v207, v209
	v_mov_b32_e32 v209, v207
	s_nop 1
	v_permlane32_swap_b32_e32 v209, v207
	s_and_saveexec_b64 s[4:5], s[0:1]
	s_cbranch_execz .LBB0_731
	s_lshl_b32 s6, s38, 10
	s_add_i32 s6, s48, s6
	v_lshl_add_u32 v210, v219, 4, s6
	s_nop 0
	v_add_f32_e32 v207, v207, v209
	ds_write_b32 v210, v207 offset:512
.LBB0_731:
	s_or_b64 exec, exec, s[4:5]
	v_mul_f32_e32 v207, v73, v73
	s_nop 0
	v_mul_f32_e32 v209, v75, v75
	v_fmac_f32_e32 v207, v72, v72
	v_fmac_f32_e32 v209, v74, v74
	v_add_f32_e32 v207, v207, v209
	v_mul_f32_e32 v209, v149, v149
	v_mul_f32_e32 v210, v151, v151
	v_fmac_f32_e32 v209, v148, v148
	v_fmac_f32_e32 v210, v150, v150
	v_add_f32_e32 v209, v209, v210
	v_add_f32_e32 v207, v209, v207
	v_mul_f32_e32 v209, v57, v57
	v_mul_f32_e32 v210, v59, v59
	v_fmac_f32_e32 v209, v56, v56
	v_fmac_f32_e32 v210, v58, v58
	v_add_f32_e32 v209, v209, v210
	v_add_f32_e32 v207, v209, v207
	v_mul_f32_e32 v209, v21, v21
	v_mul_f32_e32 v210, v23, v23
	v_fmac_f32_e32 v209, v20, v20
	v_fmac_f32_e32 v210, v22, v22
	v_add_f32_e32 v209, v209, v210
	v_add_f32_e32 v207, v209, v207
	v_mov_b32_e32 v209, v207
	s_nop 1
	v_permlane16_swap_b32_e32 v209, v207
	s_nop 0
	v_add_f32_e32 v207, v207, v209
	v_mov_b32_e32 v209, v207
	s_nop 1
	v_permlane32_swap_b32_e32 v209, v207
	s_and_saveexec_b64 s[4:5], s[0:1]
	s_cbranch_execz .LBB0_733
	s_lshl_b32 s6, s38, 10
	s_add_i32 s6, s48, s6
	v_lshl_add_u32 v210, v219, 4, s6
	s_nop 0
	v_add_f32_e32 v207, v207, v209
	ds_write_b32 v210, v207 offset:768
.LBB0_733:
	s_or_b64 exec, exec, s[4:5]
	v_mul_f32_e32 v207, v81, v81
	s_nop 0
	v_mul_f32_e32 v209, v83, v83
	v_fmac_f32_e32 v207, v80, v80
	v_fmac_f32_e32 v209, v82, v82
	v_add_f32_e32 v207, v207, v209
	v_mul_f32_e32 v209, v145, v145
	v_mul_f32_e32 v210, v147, v147
	v_fmac_f32_e32 v209, v144, v144
	v_fmac_f32_e32 v210, v146, v146
	v_add_f32_e32 v209, v209, v210
	v_add_f32_e32 v207, v209, v207
	v_mul_f32_e32 v209, v49, v49
	v_mul_f32_e32 v210, v51, v51
	v_fmac_f32_e32 v209, v48, v48
	v_fmac_f32_e32 v210, v50, v50
	v_add_f32_e32 v209, v209, v210
	v_add_f32_e32 v207, v209, v207
	v_mul_f32_e32 v209, v17, v17
	v_mul_f32_e32 v210, v19, v19
	v_fmac_f32_e32 v209, v16, v16
	v_fmac_f32_e32 v210, v18, v18
	v_add_f32_e32 v209, v209, v210
	v_add_f32_e32 v207, v209, v207
	v_mov_b32_e32 v209, v207
	s_nop 1
	v_permlane16_swap_b32_e32 v209, v207
	s_nop 0
	v_add_f32_e32 v207, v207, v209
	v_mov_b32_e32 v209, v207
	s_nop 1
	v_permlane32_swap_b32_e32 v209, v207
	s_and_saveexec_b64 s[4:5], s[0:1]
	s_cbranch_execz .LBB0_735
	s_lshl_b32 s6, s38, 10
	s_add_i32 s6, s48, s6
	v_lshl_add_u32 v210, v219, 4, s6
	s_nop 0
	v_add_f32_e32 v207, v207, v209
	ds_write_b32 v210, v207 offset:2048
.LBB0_735:
	s_or_b64 exec, exec, s[4:5]
	v_mul_f32_e32 v207, v65, v65
	s_nop 0
	v_mul_f32_e32 v209, v67, v67
	v_fmac_f32_e32 v207, v64, v64
	v_fmac_f32_e32 v209, v66, v66
	v_add_f32_e32 v207, v207, v209
	v_mul_f32_e32 v209, v137, v137
	v_mul_f32_e32 v210, v139, v139
	v_fmac_f32_e32 v209, v136, v136
	v_fmac_f32_e32 v210, v138, v138
	v_add_f32_e32 v209, v209, v210
	v_add_f32_e32 v207, v209, v207
	v_mul_f32_e32 v209, v45, v45
	v_mul_f32_e32 v210, v47, v47
	v_fmac_f32_e32 v209, v44, v44
	v_fmac_f32_e32 v210, v46, v46
	v_add_f32_e32 v209, v209, v210
	v_add_f32_e32 v207, v209, v207
	v_mul_f32_e32 v209, v13, v13
	v_mul_f32_e32 v210, v15, v15
	v_fmac_f32_e32 v209, v12, v12
	v_fmac_f32_e32 v210, v14, v14
	v_add_f32_e32 v209, v209, v210
	v_add_f32_e32 v207, v209, v207
	v_mov_b32_e32 v209, v207
	s_nop 1
	v_permlane16_swap_b32_e32 v209, v207
	s_nop 0
	v_add_f32_e32 v207, v207, v209
	v_mov_b32_e32 v209, v207
	s_nop 1
	v_permlane32_swap_b32_e32 v209, v207
	s_and_saveexec_b64 s[4:5], s[0:1]
	s_cbranch_execz .LBB0_737
	s_lshl_b32 s6, s38, 10
	s_add_i32 s6, s48, s6
	v_lshl_add_u32 v210, v219, 4, s6
	s_nop 0
	v_add_f32_e32 v207, v207, v209
	ds_write_b32 v210, v207 offset:2304
.LBB0_737:
	s_or_b64 exec, exec, s[4:5]
	v_mul_f32_e32 v207, v69, v69
	s_nop 0
	v_mul_f32_e32 v209, v71, v71
	v_fmac_f32_e32 v207, v68, v68
	v_fmac_f32_e32 v209, v70, v70
	v_add_f32_e32 v207, v207, v209
	v_mul_f32_e32 v209, v117, v117
	v_mul_f32_e32 v210, v119, v119
	v_fmac_f32_e32 v209, v116, v116
	v_fmac_f32_e32 v210, v118, v118
	v_add_f32_e32 v209, v209, v210
	v_add_f32_e32 v207, v209, v207
	v_mul_f32_e32 v209, v41, v41
	v_mul_f32_e32 v210, v43, v43
	v_fmac_f32_e32 v209, v40, v40
	v_fmac_f32_e32 v210, v42, v42
	v_add_f32_e32 v209, v209, v210
	v_add_f32_e32 v207, v209, v207
	v_mul_f32_e32 v209, v9, v9
	v_mul_f32_e32 v210, v11, v11
	v_fmac_f32_e32 v209, v8, v8
	v_fmac_f32_e32 v210, v10, v10
	v_add_f32_e32 v209, v209, v210
	v_add_f32_e32 v207, v209, v207
	v_mov_b32_e32 v209, v207
	s_nop 1
	v_permlane16_swap_b32_e32 v209, v207
	s_nop 0
	v_add_f32_e32 v207, v207, v209
	v_mov_b32_e32 v209, v207
	s_nop 1
	v_permlane32_swap_b32_e32 v209, v207
	s_and_saveexec_b64 s[4:5], s[0:1]
	s_cbranch_execz .LBB0_739
	s_lshl_b32 s6, s38, 10
	s_add_i32 s6, s48, s6
	v_lshl_add_u32 v210, v219, 4, s6
	s_nop 0
	v_add_f32_e32 v207, v207, v209
	ds_write_b32 v210, v207 offset:2560
.LBB0_739:
	s_or_b64 exec, exec, s[4:5]
	v_mul_f32_e32 v207, v53, v53
	s_nop 0
	v_mul_f32_e32 v209, v55, v55
	v_fmac_f32_e32 v207, v52, v52
	v_fmac_f32_e32 v209, v54, v54
	v_add_f32_e32 v207, v207, v209
	v_mul_f32_e32 v209, v113, v113
	v_mul_f32_e32 v210, v115, v115
	v_fmac_f32_e32 v209, v112, v112
	v_fmac_f32_e32 v210, v114, v114
	v_add_f32_e32 v209, v209, v210
	v_add_f32_e32 v207, v209, v207
	v_mul_f32_e32 v209, v37, v37
	v_mul_f32_e32 v210, v39, v39
	v_fmac_f32_e32 v209, v36, v36
	v_fmac_f32_e32 v210, v38, v38
	v_add_f32_e32 v209, v209, v210
	v_add_f32_e32 v207, v209, v207
	v_mul_f32_e32 v209, v5, v5
	v_mul_f32_e32 v210, v7, v7
	v_fmac_f32_e32 v209, v4, v4
	v_fmac_f32_e32 v210, v6, v6
	v_add_f32_e32 v209, v209, v210
	v_add_f32_e32 v207, v209, v207
	v_mov_b32_e32 v209, v207
	s_nop 1
	v_permlane16_swap_b32_e32 v209, v207
	s_nop 0
	v_add_f32_e32 v207, v207, v209
	v_mov_b32_e32 v209, v207
	s_nop 1
	v_permlane32_swap_b32_e32 v209, v207
	s_and_saveexec_b64 s[4:5], s[0:1]
	s_cbranch_execz .LBB0_741
	s_lshl_b32 s6, s38, 10
	s_add_i32 s6, s48, s6
	v_lshl_add_u32 v210, v219, 4, s6
	s_nop 0
	v_add_f32_e32 v207, v207, v209
	ds_write_b32 v210, v207 offset:2816

; __device__ __forceinline__ float f16lo(unsigned w) { return (float)__builtin_bit_cast(f16x2, w)[0]; }
; __device__ __forceinline__ float f16hi(unsigned w) { return (float)__builtin_bit_cast(f16x2, w)[1]; }
;     __device__ __forceinline__ void fused(f32x4 (&acc)[2][2][4][2], const Unit& u, int wr, int wc, int fr, int fq, PG8_LAS unsigned char* lds, int wid, int lane) const {
;     ...
;         for (int bj = 0; bj < 2; ++bj)
; #pragma unroll
;             for (int n = 0; n < 2; ++n) {
;                 const int c = col0 + bj * HALF + n * 4;
;                 const f32x4 gg = *(const f32x4*)(gate + (size_t)b * 9216 + c) * *(const f32x4*)(gpost + c) * res_w;
; #pragma unroll
;                 for (int ai = 0; ai < 2; ++ai)
; #pragma unroll
;                     for (int m = 0; m < 4; ++m) { const int r = ai * HALF + wr * 64 + m * 16 + fr;
;                         const unsigned w0 = n ? pre[ai][m][bj].z : pre[ai][m][bj].x, w1 = n ? pre[ai][m][bj].w : pre[ai][m][bj].y;
;                         const f32x4 xv = {f16lo(w0), f16hi(w0), f16lo(w1), f16hi(w1)};
;                         acc[ai][bj][m][n] = xv + gg * (acc[ai][bj][m][n] * S[r]); }
;                 asm volatile("" ::: "memory");
.LBB0_753:
	s_or_b64 exec, exec, s[34:35]
	s_ashr_i32 s8, s39, 31
	s_lshr_b32 s8, s8, 27
	s_add_i32 s8, s39, s8
	s_ashr_i32 s8, s8, 5
	s_mul_i32 s35, s8, 0x9000
	s_mul_hi_i32 s34, s8, 0x9000
	s_add_u32 s8, s30, s35
	s_addc_u32 s9, s31, s34
	s_waitcnt lgkmcnt(0)
	v_lshlrev_b64 v[208:209], 2, v[0:1]
	s_waitcnt lgkmcnt(0)
	s_barrier
	v_lshl_add_u64 v[210:211], s[8:9], 0, v[208:209]
	v_lshl_add_u64 v[212:213], s[28:29], 0, v[208:209]
	flat_load_dwordx4 v[214:217], v[210:211]
	flat_load_dwordx4 v[236:239], v[212:213]
	s_and_b32 s11, s17, 0xffffff00
	s_add_i32 s11, s11, 0
	v_lshl_add_u32 v227, v219, 2, s11
	s_cmp_lg_u64 s[12:13], 0
	s_cselect_b64 s[8:9], -1, 0
	s_cmp_eq_u64 s[12:13], 0
	s_waitcnt vmcnt(0) lgkmcnt(0)
	v_pk_mul_f32 v[216:217], v[216:217], v[238:239]
	v_pk_mul_f32 v[236:237], v[214:215], v[236:237]
	v_pk_mul_f32 v[214:215], s[16:17], v[216:217] op_sel_hi:[0,1]
	v_pk_mul_f32 v[216:217], s[16:17], v[236:237] op_sel_hi:[0,1]
	v_cvt_f32_f16_sdwa v237, v192 dst_sel:DWORD dst_unused:UNUSED_PAD src0_sel:WORD_1
	v_cvt_f32_f16_e32 v236, v192
	v_add_u32_e32 v192, 0x1000, v227
	ds_read2_b32 v[240:241], v192 offset1:16
	v_cvt_f32_f16_sdwa v239, v193 dst_sel:DWORD dst_unused:UNUSED_PAD src0_sel:WORD_1
	v_cvt_f32_f16_e32 v238, v193
	s_waitcnt lgkmcnt(0)
	v_pk_mul_f32 v[96:97], v[96:97], v[240:241] op_sel_hi:[1,0]
	s_nop 0
	v_pk_fma_f32 v[96:97], v[216:217], v[96:97], v[236:237]
	v_cvt_f32_f16_sdwa v237, v188 dst_sel:DWORD dst_unused:UNUSED_PAD src0_sel:WORD_1
	v_cvt_f32_f16_e32 v236, v188
	v_mov_b32_e32 v188, v241
	v_pk_mul_f32 v[98:99], v[98:99], v[240:241] op_sel_hi:[1,0]
	v_pk_mul_f32 v[88:89], v[88:89], v[188:189] op_sel_hi:[1,0]
	v_pk_fma_f32 v[98:99], v[214:215], v[98:99], v[238:239]
	v_cvt_f32_f16_sdwa v239, v189 dst_sel:DWORD dst_unused:UNUSED_PAD src0_sel:WORD_1
	v_cvt_f32_f16_e32 v238, v189
	v_pk_mul_f32 v[90:91], v[90:91], v[188:189] op_sel_hi:[1,0]
	v_pk_fma_f32 v[88:89], v[216:217], v[88:89], v[236:237]
	v_cvt_f32_f16_sdwa v189, v184 dst_sel:DWORD dst_unused:UNUSED_PAD src0_sel:WORD_1
	v_cvt_f32_f16_e32 v188, v184
	v_cvt_f32_f16_sdwa v237, v185 dst_sel:DWORD dst_unused:UNUSED_PAD src0_sel:WORD_1
	v_cvt_f32_f16_e32 v236, v185
	ds_read2_b32 v[184:185], v192 offset0:32 offset1:48
	v_pk_fma_f32 v[90:91], v[214:215], v[90:91], v[238:239]
	s_waitcnt lgkmcnt(0)
	v_pk_mul_f32 v[92:93], v[92:93], v[184:185] op_sel_hi:[1,0]
	v_pk_mul_f32 v[94:95], v[94:95], v[184:185] op_sel_hi:[1,0]
	v_pk_fma_f32 v[92:93], v[216:217], v[92:93], v[188:189]
	v_cvt_f32_f16_sdwa v189, v180 dst_sel:DWORD dst_unused:UNUSED_PAD src0_sel:WORD_1
	v_cvt_f32_f16_e32 v188, v180
	v_mov_b32_e32 v180, v185
	v_pk_fma_f32 v[94:95], v[214:215], v[94:95], v[236:237]
	v_cvt_f32_f16_sdwa v237, v181 dst_sel:DWORD dst_unused:UNUSED_PAD src0_sel:WORD_1
	v_cvt_f32_f16_e32 v236, v181
	v_pk_mul_f32 v[74:75], v[74:75], v[180:181] op_sel_hi:[1,0]
	v_pk_mul_f32 v[72:73], v[72:73], v[180:181] op_sel_hi:[1,0]
	v_cvt_f32_f16_sdwa v181, v176 dst_sel:DWORD dst_unused:UNUSED_PAD src0_sel:WORD_1
	v_cvt_f32_f16_e32 v180, v176
	v_cvt_f32_f16_sdwa v185, v177 dst_sel:DWORD dst_unused:UNUSED_PAD src0_sel:WORD_1
	v_cvt_f32_f16_e32 v184, v177
	ds_read2_b32 v[176:177], v192 offset0:128 offset1:144
	v_pk_fma_f32 v[74:75], v[214:215], v[74:75], v[236:237]
	v_pk_fma_f32 v[72:73], v[216:217], v[72:73], v[188:189]
	s_waitcnt lgkmcnt(0)
	v_pk_mul_f32 v[80:81], v[80:81], v[176:177] op_sel_hi:[1,0]
	v_pk_mul_f32 v[82:83], v[82:83], v[176:177] op_sel_hi:[1,0]
	v_pk_fma_f32 v[80:81], v[216:217], v[80:81], v[180:181]
	v_cvt_f32_f16_sdwa v181, v172 dst_sel:DWORD dst_unused:UNUSED_PAD src0_sel:WORD_1
	v_cvt_f32_f16_e32 v180, v172
	v_mov_b32_e32 v172, v177
	v_pk_fma_f32 v[82:83], v[214:215], v[82:83], v[184:185]
	v_cvt_f32_f16_sdwa v185, v173 dst_sel:DWORD dst_unused:UNUSED_PAD src0_sel:WORD_1
	v_cvt_f32_f16_e32 v184, v173
	v_pk_mul_f32 v[66:67], v[66:67], v[172:173] op_sel_hi:[1,0]
	v_pk_mul_f32 v[64:65], v[64:65], v[172:173] op_sel_hi:[1,0]
	v_cvt_f32_f16_sdwa v173, v168 dst_sel:DWORD dst_unused:UNUSED_PAD src0_sel:WORD_1
	v_cvt_f32_f16_e32 v172, v168
	v_cvt_f32_f16_sdwa v177, v169 dst_sel:DWORD dst_unused:UNUSED_PAD src0_sel:WORD_1
	v_cvt_f32_f16_e32 v176, v169
	ds_read2_b32 v[168:169], v192 offset0:160 offset1:176
	v_pk_fma_f32 v[66:67], v[214:215], v[66:67], v[184:185]
	v_pk_fma_f32 v[64:65], v[216:217], v[64:65], v[180:181]
	s_waitcnt lgkmcnt(0)
	v_pk_mul_f32 v[70:71], v[70:71], v[168:169] op_sel_hi:[1,0]
	v_pk_mul_f32 v[68:69], v[68:69], v[168:169] op_sel_hi:[1,0]
	v_pk_fma_f32 v[70:71], v[214:215], v[70:71], v[176:177]
	v_pk_fma_f32 v[68:69], v[216:217], v[68:69], v[172:173]
	v_cvt_f32_f16_sdwa v173, v164 dst_sel:DWORD dst_unused:UNUSED_PAD src0_sel:WORD_1
	v_cvt_f32_f16_e32 v172, v164
	v_cvt_f32_f16_sdwa v177, v165 dst_sel:DWORD dst_unused:UNUSED_PAD src0_sel:WORD_1
	v_cvt_f32_f16_e32 v176, v165
	v_mov_b32_e32 v164, v169
	v_pk_mul_f32 v[54:55], v[54:55], v[164:165] op_sel_hi:[1,0]
	v_pk_mul_f32 v[52:53], v[52:53], v[164:165] op_sel_hi:[1,0]
	v_pk_fma_f32 v[54:55], v[214:215], v[54:55], v[176:177]
	v_pk_fma_f32 v[52:53], v[216:217], v[52:53], v[172:173]
	flat_load_dwordx4 v[214:217], v[210:211] offset:16
	flat_load_dwordx4 v[236:239], v[212:213] offset:16
	ds_read2_b32 v[180:181], v192 offset1:16
	v_cvt_f32_f16_sdwa v173, v194 dst_sel:DWORD dst_unused:UNUSED_PAD src0_sel:WORD_1
	v_cvt_f32_f16_e32 v172, v194
	v_cvt_f32_f16_sdwa v177, v195 dst_sel:DWORD dst_unused:UNUSED_PAD src0_sel:WORD_1
	v_cvt_f32_f16_e32 v176, v195
	s_waitcnt lgkmcnt(0)
; __device__ __forceinline__ float f16lo(unsigned w) { return (float)__builtin_bit_cast(f16x2, w)[0]; }
; __device__ __forceinline__ float f16hi(unsigned w) { return (float)__builtin_bit_cast(f16x2, w)[1]; }
;     __device__ __forceinline__ void fused(f32x4 (&acc)[2][2][4][2], const Unit& u, int wr, int wc, int fr, int fq, PG8_LAS unsigned char* lds, int wid, int lane) const {
;     ...
;         for (int bj = 0; bj < 2; ++bj)
; #pragma unroll
;             for (int n = 0; n < 2; ++n) {
;                 const int c = col0 + bj * HALF + n * 4;
;                 const f32x4 gg = *(const f32x4*)(gate + (size_t)b * 9216 + c) * *(const f32x4*)(gpost + c) * res_w;
; #pragma unroll
;                 for (int ai = 0; ai < 2; ++ai)
; #pragma unroll
;                     for (int m = 0; m < 4; ++m) { const int r = ai * HALF + wr * 64 + m * 16 + fr;
;                         const unsigned w0 = n ? pre[ai][m][bj].z : pre[ai][m][bj].x, w1 = n ? pre[ai][m][bj].w : pre[ai][m][bj].y;
;                         const f32x4 xv = {f16lo(w0), f16hi(w0), f16lo(w1), f16hi(w1)};
;                         acc[ai][bj][m][n] = xv + gg * (acc[ai][bj][m][n] * S[r]); }
;                 asm volatile("" ::: "memory");
	v_pk_mul_f32 v[162:163], v[162:163], v[180:181] op_sel_hi:[1,0]
	v_pk_mul_f32 v[160:161], v[160:161], v[180:181] op_sel_hi:[1,0]
	v_mov_b32_e32 v180, v181
	v_pk_mul_f32 v[158:159], v[158:159], v[180:181] op_sel_hi:[1,0]
	v_pk_mul_f32 v[156:157], v[156:157], v[180:181] op_sel_hi:[1,0]
	ds_read2_b32 v[180:181], v192 offset0:32 offset1:48
	s_waitcnt lgkmcnt(0)
	v_pk_mul_f32 v[154:155], v[154:155], v[180:181] op_sel_hi:[1,0]
	v_pk_mul_f32 v[152:153], v[152:153], v[180:181] op_sel_hi:[1,0]
	v_mov_b32_e32 v180, v181
	v_pk_mul_f32 v[150:151], v[150:151], v[180:181] op_sel_hi:[1,0]
	v_pk_mul_f32 v[148:149], v[148:149], v[180:181] op_sel_hi:[1,0]
	s_waitcnt vmcnt(0)
	v_pk_mul_f32 v[164:165], v[216:217], v[238:239]
	v_pk_mul_f32 v[168:169], v[214:215], v[236:237]
	v_pk_mul_f32 v[164:165], s[16:17], v[164:165] op_sel_hi:[0,1]
	v_pk_mul_f32 v[168:169], s[16:17], v[168:169] op_sel_hi:[0,1]
	v_pk_fma_f32 v[162:163], v[164:165], v[162:163], v[176:177]
	v_pk_fma_f32 v[160:161], v[168:169], v[160:161], v[172:173]
	v_cvt_f32_f16_sdwa v173, v190 dst_sel:DWORD dst_unused:UNUSED_PAD src0_sel:WORD_1
	v_cvt_f32_f16_e32 v172, v190
	v_cvt_f32_f16_sdwa v177, v191 dst_sel:DWORD dst_unused:UNUSED_PAD src0_sel:WORD_1
	v_cvt_f32_f16_e32 v176, v191
	v_pk_fma_f32 v[156:157], v[168:169], v[156:157], v[172:173]
	v_cvt_f32_f16_sdwa v173, v186 dst_sel:DWORD dst_unused:UNUSED_PAD src0_sel:WORD_1
	v_pk_fma_f32 v[158:159], v[164:165], v[158:159], v[176:177]
	v_cvt_f32_f16_e32 v172, v186
	v_cvt_f32_f16_sdwa v177, v187 dst_sel:DWORD dst_unused:UNUSED_PAD src0_sel:WORD_1
	v_cvt_f32_f16_e32 v176, v187
	v_pk_fma_f32 v[152:153], v[168:169], v[152:153], v[172:173]
	v_cvt_f32_f16_sdwa v173, v182 dst_sel:DWORD dst_unused:UNUSED_PAD src0_sel:WORD_1
	v_pk_fma_f32 v[154:155], v[164:165], v[154:155], v[176:177]
	v_cvt_f32_f16_e32 v172, v182
	v_cvt_f32_f16_sdwa v177, v183 dst_sel:DWORD dst_unused:UNUSED_PAD src0_sel:WORD_1
	v_cvt_f32_f16_e32 v176, v183
	v_pk_fma_f32 v[148:149], v[168:169], v[148:149], v[172:173]
	v_cvt_f32_f16_sdwa v173, v178 dst_sel:DWORD dst_unused:UNUSED_PAD src0_sel:WORD_1
	v_pk_fma_f32 v[150:151], v[164:165], v[150:151], v[176:177]
	v_cvt_f32_f16_e32 v172, v178
	v_cvt_f32_f16_sdwa v177, v179 dst_sel:DWORD dst_unused:UNUSED_PAD src0_sel:WORD_1
	v_cvt_f32_f16_e32 v176, v179
	ds_read2_b32 v[178:179], v192 offset0:128 offset1:144
	s_waitcnt lgkmcnt(0)
	v_pk_mul_f32 v[144:145], v[144:145], v[178:179] op_sel_hi:[1,0]
	s_nop 0
	v_pk_fma_f32 v[144:145], v[168:169], v[144:145], v[172:173]
	v_cvt_f32_f16_sdwa v173, v174 dst_sel:DWORD dst_unused:UNUSED_PAD src0_sel:WORD_1
	v_cvt_f32_f16_e32 v172, v174
	v_mov_b32_e32 v174, v179
	v_pk_mul_f32 v[146:147], v[146:147], v[178:179] op_sel_hi:[1,0]
	v_pk_mul_f32 v[136:137], v[136:137], v[174:175] op_sel_hi:[1,0]
	v_pk_fma_f32 v[146:147], v[164:165], v[146:147], v[176:177]
	v_cvt_f32_f16_sdwa v177, v175 dst_sel:DWORD dst_unused:UNUSED_PAD src0_sel:WORD_1
	v_cvt_f32_f16_e32 v176, v175
	v_pk_mul_f32 v[138:139], v[138:139], v[174:175] op_sel_hi:[1,0]
	v_pk_fma_f32 v[136:137], v[168:169], v[136:137], v[172:173]
	v_cvt_f32_f16_sdwa v173, v170 dst_sel:DWORD dst_unused:UNUSED_PAD src0_sel:WORD_1
	v_cvt_f32_f16_e32 v172, v170
	v_cvt_f32_f16_sdwa v175, v171 dst_sel:DWORD dst_unused:UNUSED_PAD src0_sel:WORD_1
	v_cvt_f32_f16_e32 v174, v171
	ds_read2_b32 v[170:171], v192 offset0:160 offset1:176
	v_pk_fma_f32 v[138:139], v[164:165], v[138:139], v[176:177]
	s_waitcnt lgkmcnt(0)
	v_pk_mul_f32 v[118:119], v[118:119], v[170:171] op_sel_hi:[1,0]
	v_pk_mul_f32 v[116:117], v[116:117], v[170:171] op_sel_hi:[1,0]
	v_pk_fma_f32 v[118:119], v[164:165], v[118:119], v[174:175]
	v_pk_fma_f32 v[116:117], v[168:169], v[116:117], v[172:173]
	v_cvt_f32_f16_sdwa v173, v166 dst_sel:DWORD dst_unused:UNUSED_PAD src0_sel:WORD_1
	v_cvt_f32_f16_e32 v172, v166
	v_cvt_f32_f16_sdwa v175, v167 dst_sel:DWORD dst_unused:UNUSED_PAD src0_sel:WORD_1
	v_cvt_f32_f16_e32 v174, v167
	v_mov_b32_e32 v166, v171
	v_pk_mul_f32 v[114:115], v[114:115], v[166:167] op_sel_hi:[1,0]
	v_pk_mul_f32 v[112:113], v[112:113], v[166:167] op_sel_hi:[1,0]
	v_pk_fma_f32 v[114:115], v[164:165], v[114:115], v[174:175]
	v_pk_fma_f32 v[112:113], v[168:169], v[112:113], v[172:173]
	flat_load_dwordx4 v[164:167], v[210:211] offset:512
	flat_load_dwordx4 v[168:171], v[212:213] offset:512
	s_waitcnt vmcnt(0) lgkmcnt(0)
	v_pk_mul_f32 v[166:167], v[166:167], v[170:171]
	v_pk_mul_f32 v[168:169], v[164:165], v[168:169]
	v_pk_mul_f32 v[164:165], s[16:17], v[166:167] op_sel_hi:[0,1]
	v_pk_mul_f32 v[166:167], s[16:17], v[168:169] op_sel_hi:[0,1]
	v_cvt_f32_f16_sdwa v169, v140 dst_sel:DWORD dst_unused:UNUSED_PAD src0_sel:WORD_1
	v_cvt_f32_f16_e32 v168, v140
	v_cvt_f32_f16_sdwa v171, v141 dst_sel:DWORD dst_unused:UNUSED_PAD src0_sel:WORD_1
	v_cvt_f32_f16_e32 v170, v141
	ds_read2_b32 v[140:141], v192 offset1:16
	s_waitcnt lgkmcnt(0)
	v_pk_mul_f32 v[84:85], v[84:85], v[140:141] op_sel_hi:[1,0]
	v_pk_mul_f32 v[86:87], v[86:87], v[140:141] op_sel_hi:[1,0]
	v_pk_fma_f32 v[84:85], v[166:167], v[84:85], v[168:169]
	v_cvt_f32_f16_sdwa v169, v132 dst_sel:DWORD dst_unused:UNUSED_PAD src0_sel:WORD_1
	v_cvt_f32_f16_e32 v168, v132
	v_mov_b32_e32 v132, v141
	v_pk_fma_f32 v[86:87], v[164:165], v[86:87], v[170:171]
	v_cvt_f32_f16_sdwa v171, v133 dst_sel:DWORD dst_unused:UNUSED_PAD src0_sel:WORD_1
	v_cvt_f32_f16_e32 v170, v133
	v_pk_mul_f32 v[78:79], v[78:79], v[132:133] op_sel_hi:[1,0]
	v_pk_mul_f32 v[76:77], v[76:77], v[132:133] op_sel_hi:[1,0]
	v_cvt_f32_f16_sdwa v133, v128 dst_sel:DWORD dst_unused:UNUSED_PAD src0_sel:WORD_1
	v_cvt_f32_f16_e32 v132, v128
	v_cvt_f32_f16_sdwa v141, v129 dst_sel:DWORD dst_unused:UNUSED_PAD src0_sel:WORD_1
	v_cvt_f32_f16_e32 v140, v129
	ds_read2_b32 v[128:129], v192 offset0:32 offset1:48
	v_pk_fma_f32 v[78:79], v[164:165], v[78:79], v[170:171]
	v_pk_fma_f32 v[76:77], v[166:167], v[76:77], v[168:169]
	s_waitcnt lgkmcnt(0)
; __device__ __forceinline__ float f16lo(unsigned w) { return (float)__builtin_bit_cast(f16x2, w)[0]; }
; __device__ __forceinline__ float f16hi(unsigned w) { return (float)__builtin_bit_cast(f16x2, w)[1]; }
;     __device__ __forceinline__ void fused(f32x4 (&acc)[2][2][4][2], const Unit& u, int wr, int wc, int fr, int fq, PG8_LAS unsigned char* lds, int wid, int lane) const {
;     ...
;         for (int bj = 0; bj < 2; ++bj)
; #pragma unroll
;             for (int n = 0; n < 2; ++n) {
;                 const int c = col0 + bj * HALF + n * 4;
;                 const f32x4 gg = *(const f32x4*)(gate + (size_t)b * 9216 + c) * *(const f32x4*)(gpost + c) * res_w;
; #pragma unroll
;                 for (int ai = 0; ai < 2; ++ai)
; #pragma unroll
;                     for (int m = 0; m < 4; ++m) { const int r = ai * HALF + wr * 64 + m * 16 + fr;
;                         const unsigned w0 = n ? pre[ai][m][bj].z : pre[ai][m][bj].x, w1 = n ? pre[ai][m][bj].w : pre[ai][m][bj].y;
;                         const f32x4 xv = {f16lo(w0), f16hi(w0), f16lo(w1), f16hi(w1)};
;                         acc[ai][bj][m][n] = xv + gg * (acc[ai][bj][m][n] * S[r]); }
;                 asm volatile("" ::: "memory");
	v_pk_mul_f32 v[60:61], v[60:61], v[128:129] op_sel_hi:[1,0]
	v_pk_mul_f32 v[62:63], v[62:63], v[128:129] op_sel_hi:[1,0]
	v_pk_fma_f32 v[60:61], v[166:167], v[60:61], v[132:133]
	v_cvt_f32_f16_sdwa v133, v124 dst_sel:DWORD dst_unused:UNUSED_PAD src0_sel:WORD_1
	v_cvt_f32_f16_e32 v132, v124
	v_mov_b32_e32 v124, v129
	v_pk_fma_f32 v[62:63], v[164:165], v[62:63], v[140:141]
	v_cvt_f32_f16_sdwa v141, v125 dst_sel:DWORD dst_unused:UNUSED_PAD src0_sel:WORD_1
	v_cvt_f32_f16_e32 v140, v125
	v_pk_mul_f32 v[58:59], v[58:59], v[124:125] op_sel_hi:[1,0]
	v_pk_mul_f32 v[56:57], v[56:57], v[124:125] op_sel_hi:[1,0]
	v_cvt_f32_f16_sdwa v125, v120 dst_sel:DWORD dst_unused:UNUSED_PAD src0_sel:WORD_1
	v_cvt_f32_f16_e32 v124, v120
	v_cvt_f32_f16_sdwa v129, v121 dst_sel:DWORD dst_unused:UNUSED_PAD src0_sel:WORD_1
	v_cvt_f32_f16_e32 v128, v121
	ds_read2_b32 v[120:121], v192 offset0:128 offset1:144
	v_pk_fma_f32 v[58:59], v[164:165], v[58:59], v[140:141]
	v_pk_fma_f32 v[56:57], v[166:167], v[56:57], v[132:133]
	s_waitcnt lgkmcnt(0)
	v_pk_mul_f32 v[48:49], v[48:49], v[120:121] op_sel_hi:[1,0]
	v_pk_mul_f32 v[50:51], v[50:51], v[120:121] op_sel_hi:[1,0]
	v_pk_fma_f32 v[48:49], v[166:167], v[48:49], v[124:125]
	v_cvt_f32_f16_sdwa v125, v108 dst_sel:DWORD dst_unused:UNUSED_PAD src0_sel:WORD_1
	v_cvt_f32_f16_e32 v124, v108
	v_mov_b32_e32 v108, v121
	v_pk_fma_f32 v[50:51], v[164:165], v[50:51], v[128:129]
	v_cvt_f32_f16_sdwa v129, v109 dst_sel:DWORD dst_unused:UNUSED_PAD src0_sel:WORD_1
	v_cvt_f32_f16_e32 v128, v109
	v_pk_mul_f32 v[46:47], v[46:47], v[108:109] op_sel_hi:[1,0]
	v_pk_mul_f32 v[44:45], v[44:45], v[108:109] op_sel_hi:[1,0]
	v_cvt_f32_f16_sdwa v109, v104 dst_sel:DWORD dst_unused:UNUSED_PAD src0_sel:WORD_1
	v_cvt_f32_f16_e32 v108, v104
	v_cvt_f32_f16_sdwa v121, v105 dst_sel:DWORD dst_unused:UNUSED_PAD src0_sel:WORD_1
	v_cvt_f32_f16_e32 v120, v105
	ds_read2_b32 v[104:105], v192 offset0:160 offset1:176
	v_pk_fma_f32 v[46:47], v[164:165], v[46:47], v[128:129]
	v_pk_fma_f32 v[44:45], v[166:167], v[44:45], v[124:125]
	s_waitcnt lgkmcnt(0)
	v_pk_mul_f32 v[42:43], v[42:43], v[104:105] op_sel_hi:[1,0]
	v_pk_mul_f32 v[40:41], v[40:41], v[104:105] op_sel_hi:[1,0]
	v_pk_fma_f32 v[42:43], v[164:165], v[42:43], v[120:121]
	v_pk_fma_f32 v[40:41], v[166:167], v[40:41], v[108:109]
	v_cvt_f32_f16_sdwa v109, v100 dst_sel:DWORD dst_unused:UNUSED_PAD src0_sel:WORD_1
	v_cvt_f32_f16_e32 v108, v100
	v_cvt_f32_f16_sdwa v121, v101 dst_sel:DWORD dst_unused:UNUSED_PAD src0_sel:WORD_1
	v_cvt_f32_f16_e32 v120, v101
	v_mov_b32_e32 v100, v105
	v_pk_mul_f32 v[38:39], v[38:39], v[100:101] op_sel_hi:[1,0]
	v_pk_mul_f32 v[36:37], v[36:37], v[100:101] op_sel_hi:[1,0]
	v_pk_fma_f32 v[38:39], v[164:165], v[38:39], v[120:121]
	v_pk_fma_f32 v[36:37], v[166:167], v[36:37], v[108:109]
	flat_load_dwordx4 v[164:167], v[210:211] offset:528
	flat_load_dwordx4 v[168:171], v[212:213] offset:528
	ds_read2_b32 v[124:125], v192 offset1:16
	v_cvt_f32_f16_sdwa v109, v142 dst_sel:DWORD dst_unused:UNUSED_PAD src0_sel:WORD_1
	v_cvt_f32_f16_e32 v108, v142
	v_cvt_f32_f16_sdwa v121, v143 dst_sel:DWORD dst_unused:UNUSED_PAD src0_sel:WORD_1
	v_cvt_f32_f16_e32 v120, v143
	s_waitcnt lgkmcnt(0)
	v_pk_mul_f32 v[34:35], v[34:35], v[124:125] op_sel_hi:[1,0]
	v_pk_mul_f32 v[32:33], v[32:33], v[124:125] op_sel_hi:[1,0]
	v_mov_b32_e32 v124, v125
	v_pk_mul_f32 v[30:31], v[30:31], v[124:125] op_sel_hi:[1,0]
	v_pk_mul_f32 v[28:29], v[28:29], v[124:125] op_sel_hi:[1,0]
	ds_read2_b32 v[124:125], v192 offset0:32 offset1:48
	s_waitcnt lgkmcnt(0)
	v_pk_mul_f32 v[26:27], v[26:27], v[124:125] op_sel_hi:[1,0]
	v_pk_mul_f32 v[24:25], v[24:25], v[124:125] op_sel_hi:[1,0]
	v_mov_b32_e32 v124, v125
	v_pk_mul_f32 v[22:23], v[22:23], v[124:125] op_sel_hi:[1,0]
	v_pk_mul_f32 v[20:21], v[20:21], v[124:125] op_sel_hi:[1,0]
	s_waitcnt vmcnt(0)
	v_pk_mul_f32 v[100:101], v[166:167], v[170:171]
	v_pk_mul_f32 v[104:105], v[164:165], v[168:169]
	v_pk_mul_f32 v[100:101], s[16:17], v[100:101] op_sel_hi:[0,1]
	v_pk_mul_f32 v[104:105], s[16:17], v[104:105] op_sel_hi:[0,1]
	v_pk_fma_f32 v[34:35], v[100:101], v[34:35], v[120:121]
	v_pk_fma_f32 v[32:33], v[104:105], v[32:33], v[108:109]
	v_cvt_f32_f16_sdwa v109, v134 dst_sel:DWORD dst_unused:UNUSED_PAD src0_sel:WORD_1
	v_cvt_f32_f16_e32 v108, v134
	v_cvt_f32_f16_sdwa v121, v135 dst_sel:DWORD dst_unused:UNUSED_PAD src0_sel:WORD_1
	v_cvt_f32_f16_e32 v120, v135
	v_pk_fma_f32 v[28:29], v[104:105], v[28:29], v[108:109]
	v_cvt_f32_f16_sdwa v109, v130 dst_sel:DWORD dst_unused:UNUSED_PAD src0_sel:WORD_1
	v_pk_fma_f32 v[30:31], v[100:101], v[30:31], v[120:121]
	v_cvt_f32_f16_e32 v108, v130
	v_cvt_f32_f16_sdwa v121, v131 dst_sel:DWORD dst_unused:UNUSED_PAD src0_sel:WORD_1
	v_cvt_f32_f16_e32 v120, v131
	v_pk_fma_f32 v[24:25], v[104:105], v[24:25], v[108:109]
	v_cvt_f32_f16_sdwa v109, v126 dst_sel:DWORD dst_unused:UNUSED_PAD src0_sel:WORD_1
	v_pk_fma_f32 v[26:27], v[100:101], v[26:27], v[120:121]
	v_cvt_f32_f16_e32 v108, v126
	v_cvt_f32_f16_sdwa v121, v127 dst_sel:DWORD dst_unused:UNUSED_PAD src0_sel:WORD_1
	v_cvt_f32_f16_e32 v120, v127
	v_pk_fma_f32 v[20:21], v[104:105], v[20:21], v[108:109]
	v_cvt_f32_f16_sdwa v109, v122 dst_sel:DWORD dst_unused:UNUSED_PAD src0_sel:WORD_1
	v_pk_fma_f32 v[22:23], v[100:101], v[22:23], v[120:121]
	v_cvt_f32_f16_e32 v108, v122
	v_cvt_f32_f16_sdwa v121, v123 dst_sel:DWORD dst_unused:UNUSED_PAD src0_sel:WORD_1
	v_cvt_f32_f16_e32 v120, v123
	ds_read2_b32 v[122:123], v192 offset0:128 offset1:144
	s_waitcnt lgkmcnt(0)
; __device__ __forceinline__ float f16lo(unsigned w) { return (float)__builtin_bit_cast(f16x2, w)[0]; }
; __device__ __forceinline__ float f16hi(unsigned w) { return (float)__builtin_bit_cast(f16x2, w)[1]; }
; __device__ __forceinline__ void panel_rstd(const f32x4 (&v)[2][2][4][2], const Unit& u, int wr, int wc, int fr, int fq, PG8_LAS unsigned char* lds, int wid, int lane,
;                                            float* xslots, unsigned* cnt, unsigned want, float eps) {
;     ...
; #pragma unroll
;     for (int ai = 0; ai < 2; ++ai)
; #pragma unroll
;         for (int m = 0; m < 4; ++m) {
;             float s = 0.f;
; #pragma unroll
;             for (int bj = 0; bj < 2; ++bj)
; #pragma unroll
;                 for (int n = 0; n < 2; ++n) { const f32x4 x = v[ai][bj][m][n]; s += (x[0] * x[0] + x[1] * x[1]) + (x[2] * x[2] + x[3] * x[3]); }
;             s += __shfl_xor(s, 16); s += __shfl_xor(s, 32);
;             if (fq == 0) P[(ai * HALF + wr * 64 + m * 16 + fr) * 4 + wc] = s;
;     __device__ __forceinline__ void fused(f32x4 (&acc)[2][2][4][2], const Unit& u, int wr, int wc, int fr, int fq, PG8_LAS unsigned char* lds, int wid, int lane) const {
;     ...
;                     for (int m = 0; m < 4; ++m) { const int r = ai * HALF + wr * 64 + m * 16 + fr;
;                         const unsigned w0 = n ? pre[ai][m][bj].z : pre[ai][m][bj].x, w1 = n ? pre[ai][m][bj].w : pre[ai][m][bj].y;
;                         const f32x4 xv = {f16lo(w0), f16hi(w0), f16lo(w1), f16hi(w1)};
;                         acc[ai][bj][m][n] = xv + gg * (acc[ai][bj][m][n] * S[r]); }
;                 asm volatile("" ::: "memory");
;             }
;         if (HH) panel_rstd(acc, u, wr, wc, fr, fq, lds, wid, lane, xbuf + (size_t)16384 * 4, cnt, want1 + 32u, 1e-6f);
	v_pk_mul_f32 v[16:17], v[16:17], v[122:123] op_sel_hi:[1,0]
	s_nop 0
	v_pk_fma_f32 v[16:17], v[104:105], v[16:17], v[108:109]
	v_cvt_f32_f16_sdwa v109, v110 dst_sel:DWORD dst_unused:UNUSED_PAD src0_sel:WORD_1
	v_cvt_f32_f16_e32 v108, v110
	v_mov_b32_e32 v110, v123
	v_pk_mul_f32 v[18:19], v[18:19], v[122:123] op_sel_hi:[1,0]
	v_pk_mul_f32 v[12:13], v[12:13], v[110:111] op_sel_hi:[1,0]
	v_pk_fma_f32 v[18:19], v[100:101], v[18:19], v[120:121]
	v_cvt_f32_f16_sdwa v121, v111 dst_sel:DWORD dst_unused:UNUSED_PAD src0_sel:WORD_1
	v_cvt_f32_f16_e32 v120, v111
	v_pk_mul_f32 v[14:15], v[14:15], v[110:111] op_sel_hi:[1,0]
	v_pk_fma_f32 v[12:13], v[104:105], v[12:13], v[108:109]
	v_cvt_f32_f16_sdwa v109, v106 dst_sel:DWORD dst_unused:UNUSED_PAD src0_sel:WORD_1
	v_cvt_f32_f16_e32 v108, v106
	v_cvt_f32_f16_sdwa v111, v107 dst_sel:DWORD dst_unused:UNUSED_PAD src0_sel:WORD_1
	v_cvt_f32_f16_e32 v110, v107
	ds_read2_b32 v[106:107], v192 offset0:160 offset1:176
	v_pk_fma_f32 v[14:15], v[100:101], v[14:15], v[120:121]
	s_waitcnt lgkmcnt(0)
	v_pk_mul_f32 v[10:11], v[10:11], v[106:107] op_sel_hi:[1,0]
	v_pk_mul_f32 v[8:9], v[8:9], v[106:107] op_sel_hi:[1,0]
	v_pk_fma_f32 v[10:11], v[100:101], v[10:11], v[110:111]
	v_pk_fma_f32 v[8:9], v[104:105], v[8:9], v[108:109]
	v_cvt_f32_f16_sdwa v109, v102 dst_sel:DWORD dst_unused:UNUSED_PAD src0_sel:WORD_1
	v_cvt_f32_f16_e32 v108, v102
	v_cvt_f32_f16_sdwa v111, v103 dst_sel:DWORD dst_unused:UNUSED_PAD src0_sel:WORD_1
	v_cvt_f32_f16_e32 v110, v103
	v_mov_b32_e32 v102, v107
	v_pk_mul_f32 v[6:7], v[6:7], v[102:103] op_sel_hi:[1,0]
	v_pk_mul_f32 v[4:5], v[4:5], v[102:103] op_sel_hi:[1,0]
	v_pk_fma_f32 v[6:7], v[100:101], v[6:7], v[110:111]
	v_pk_fma_f32 v[4:5], v[104:105], v[4:5], v[108:109]
	s_cbranch_scc1 .LBB0_783
	v_mul_f32_e32 v100, v97, v97
	v_mul_f32_e32 v101, v99, v99
	v_fmac_f32_e32 v100, v96, v96
	v_fmac_f32_e32 v101, v98, v98
	v_add_f32_e32 v100, v100, v101
	v_mul_f32_e32 v101, v161, v161
	v_mul_f32_e32 v102, v163, v163
	v_fmac_f32_e32 v101, v160, v160
	v_fmac_f32_e32 v102, v162, v162
	v_add_f32_e32 v101, v101, v102
	v_add_f32_e32 v100, v100, v101
	v_mul_f32_e32 v101, v85, v85
	v_mul_f32_e32 v102, v87, v87
	v_fmac_f32_e32 v101, v84, v84
	v_fmac_f32_e32 v102, v86, v86
	v_add_f32_e32 v101, v101, v102
	v_add_f32_e32 v100, v100, v101
	v_mul_f32_e32 v101, v33, v33
	v_mul_f32_e32 v102, v35, v35
	v_fmac_f32_e32 v101, v32, v32
	v_fmac_f32_e32 v102, v34, v34
	v_add_f32_e32 v101, v101, v102
	v_add_f32_e32 v100, v100, v101
	v_mov_b32_e32 v101, v100
	s_nop 1
	v_permlane16_swap_b32_e32 v101, v100
	s_nop 0
	v_add_f32_e32 v100, v100, v101
	v_mov_b32_e32 v101, v100
	s_nop 1
	v_permlane32_swap_b32_e32 v101, v100
	s_and_saveexec_b64 s[16:17], s[0:1]
	s_cbranch_execz .LBB0_756
	s_lshl_b32 s11, s38, 10
	s_add_i32 s11, s48, s11
	v_lshl_add_u32 v102, v219, 4, s11
	s_nop 0
	v_add_f32_e32 v100, v100, v101
	ds_write_b32 v102, v100
.LBB0_756:
	s_or_b64 exec, exec, s[16:17]
	v_mul_f32_e32 v100, v89, v89
	s_nop 0
	v_mul_f32_e32 v101, v91, v91
	v_fmac_f32_e32 v100, v88, v88
	v_fmac_f32_e32 v101, v90, v90
	v_add_f32_e32 v100, v100, v101
	v_mul_f32_e32 v101, v157, v157
	v_mul_f32_e32 v102, v159, v159
	v_fmac_f32_e32 v101, v156, v156
	v_fmac_f32_e32 v102, v158, v158
	v_add_f32_e32 v101, v101, v102
	v_add_f32_e32 v100, v100, v101
	v_mul_f32_e32 v101, v77, v77
	v_mul_f32_e32 v102, v79, v79
	v_fmac_f32_e32 v101, v76, v76
	v_fmac_f32_e32 v102, v78, v78
	v_add_f32_e32 v101, v101, v102
	v_add_f32_e32 v100, v100, v101
	v_mul_f32_e32 v101, v29, v29
	v_mul_f32_e32 v102, v31, v31
	v_fmac_f32_e32 v101, v28, v28
	v_fmac_f32_e32 v102, v30, v30
	v_add_f32_e32 v101, v101, v102
	v_add_f32_e32 v100, v100, v101
	v_mov_b32_e32 v101, v100
	s_nop 1
	v_permlane16_swap_b32_e32 v101, v100
	s_nop 0
	v_add_f32_e32 v100, v100, v101
	v_mov_b32_e32 v101, v100
	s_nop 1
	v_permlane32_swap_b32_e32 v101, v100
	s_and_saveexec_b64 s[16:17], s[0:1]
	s_cbranch_execz .LBB0_758
	s_lshl_b32 s11, s38, 10
	s_add_i32 s11, s48, s11
	v_lshl_add_u32 v102, v219, 4, s11
	s_nop 0
	v_add_f32_e32 v100, v100, v101
	ds_write_b32 v102, v100 offset:256
.LBB0_758:
	s_or_b64 exec, exec, s[16:17]
	v_mul_f32_e32 v100, v93, v93
	s_nop 0
	v_mul_f32_e32 v101, v95, v95
	v_fmac_f32_e32 v100, v92, v92
	v_fmac_f32_e32 v101, v94, v94
	v_add_f32_e32 v100, v100, v101
	v_mul_f32_e32 v101, v153, v153
	v_mul_f32_e32 v102, v155, v155
	v_fmac_f32_e32 v101, v152, v152
	v_fmac_f32_e32 v102, v154, v154
	v_add_f32_e32 v101, v101, v102
	v_add_f32_e32 v100, v100, v101
	v_mul_f32_e32 v101, v61, v61
	v_mul_f32_e32 v102, v63, v63
	v_fmac_f32_e32 v101, v60, v60
	v_fmac_f32_e32 v102, v62, v62
	v_add_f32_e32 v101, v101, v102
	v_add_f32_e32 v100, v100, v101
	v_mul_f32_e32 v101, v25, v25
	v_mul_f32_e32 v102, v27, v27
	v_fmac_f32_e32 v101, v24, v24
	v_fmac_f32_e32 v102, v26, v26
	v_add_f32_e32 v101, v101, v102
	v_add_f32_e32 v100, v100, v101
	v_mov_b32_e32 v101, v100
	s_nop 1
	v_permlane16_swap_b32_e32 v101, v100
	s_nop 0
	v_add_f32_e32 v100, v100, v101
	v_mov_b32_e32 v101, v100
	s_nop 1
	v_permlane32_swap_b32_e32 v101, v100
	s_and_saveexec_b64 s[16:17], s[0:1]
	s_cbranch_execz .LBB0_760
	s_lshl_b32 s11, s38, 10
	s_add_i32 s11, s48, s11
	v_lshl_add_u32 v102, v219, 4, s11
	s_nop 0
	v_add_f32_e32 v100, v100, v101
	ds_write_b32 v102, v100 offset:512
; __device__ __forceinline__ void panel_rstd(const f32x4 (&v)[2][2][4][2], const Unit& u, int wr, int wc, int fr, int fq, PG8_LAS unsigned char* lds, int wid, int lane,
;                                            float* xslots, unsigned* cnt, unsigned want, float eps) {
;     ...
; #pragma unroll
;     for (int ai = 0; ai < 2; ++ai)
; #pragma unroll
;         for (int m = 0; m < 4; ++m) {
;             float s = 0.f;
; #pragma unroll
;             for (int bj = 0; bj < 2; ++bj)
; #pragma unroll
;                 for (int n = 0; n < 2; ++n) { const f32x4 x = v[ai][bj][m][n]; s += (x[0] * x[0] + x[1] * x[1]) + (x[2] * x[2] + x[3] * x[3]); }
;             s += __shfl_xor(s, 16); s += __shfl_xor(s, 32);
;             if (fq == 0) P[(ai * HALF + wr * 64 + m * 16 + fr) * 4 + wc] = s;
;         }
.LBB0_760:
	s_or_b64 exec, exec, s[16:17]
	v_mul_f32_e32 v100, v73, v73
	s_nop 0
	v_mul_f32_e32 v101, v75, v75
	v_fmac_f32_e32 v100, v72, v72
	v_fmac_f32_e32 v101, v74, v74
	v_add_f32_e32 v100, v100, v101
	v_mul_f32_e32 v101, v149, v149
	v_mul_f32_e32 v102, v151, v151
	v_fmac_f32_e32 v101, v148, v148
	v_fmac_f32_e32 v102, v150, v150
	v_add_f32_e32 v101, v101, v102
	v_add_f32_e32 v100, v100, v101
	v_mul_f32_e32 v101, v57, v57
	v_mul_f32_e32 v102, v59, v59
	v_fmac_f32_e32 v101, v56, v56
	v_fmac_f32_e32 v102, v58, v58
	v_add_f32_e32 v101, v101, v102
	v_add_f32_e32 v100, v100, v101
	v_mul_f32_e32 v101, v21, v21
	v_mul_f32_e32 v102, v23, v23
	v_fmac_f32_e32 v101, v20, v20
	v_fmac_f32_e32 v102, v22, v22
	v_add_f32_e32 v101, v101, v102
	v_add_f32_e32 v100, v100, v101
	v_mov_b32_e32 v101, v100
	s_nop 1
	v_permlane16_swap_b32_e32 v101, v100
	s_nop 0
	v_add_f32_e32 v100, v100, v101
	v_mov_b32_e32 v101, v100
	s_nop 1
	v_permlane32_swap_b32_e32 v101, v100
	s_and_saveexec_b64 s[16:17], s[0:1]
	s_cbranch_execz .LBB0_762
	s_lshl_b32 s11, s38, 10
	s_add_i32 s11, s48, s11
	v_lshl_add_u32 v102, v219, 4, s11
	s_nop 0
	v_add_f32_e32 v100, v100, v101
	ds_write_b32 v102, v100 offset:768
.LBB0_762:
	s_or_b64 exec, exec, s[16:17]
	v_mul_f32_e32 v100, v81, v81
	s_nop 0
	v_mul_f32_e32 v101, v83, v83
	v_fmac_f32_e32 v100, v80, v80
	v_fmac_f32_e32 v101, v82, v82
	v_add_f32_e32 v100, v100, v101
	v_mul_f32_e32 v101, v145, v145
	v_mul_f32_e32 v102, v147, v147
	v_fmac_f32_e32 v101, v144, v144
	v_fmac_f32_e32 v102, v146, v146
	v_add_f32_e32 v101, v101, v102
	v_add_f32_e32 v100, v100, v101
	v_mul_f32_e32 v101, v49, v49
	v_mul_f32_e32 v102, v51, v51
	v_fmac_f32_e32 v101, v48, v48
	v_fmac_f32_e32 v102, v50, v50
	v_add_f32_e32 v101, v101, v102
	v_add_f32_e32 v100, v100, v101
	v_mul_f32_e32 v101, v17, v17
	v_mul_f32_e32 v102, v19, v19
	v_fmac_f32_e32 v101, v16, v16
	v_fmac_f32_e32 v102, v18, v18
	v_add_f32_e32 v101, v101, v102
	v_add_f32_e32 v100, v100, v101
	v_mov_b32_e32 v101, v100
	s_nop 1
	v_permlane16_swap_b32_e32 v101, v100
	s_nop 0
	v_add_f32_e32 v100, v100, v101
	v_mov_b32_e32 v101, v100
	s_nop 1
	v_permlane32_swap_b32_e32 v101, v100
	s_and_saveexec_b64 s[16:17], s[0:1]
	s_cbranch_execz .LBB0_764
	s_lshl_b32 s11, s38, 10
	s_add_i32 s11, s48, s11
	v_lshl_add_u32 v102, v219, 4, s11
	s_nop 0
	v_add_f32_e32 v100, v100, v101
	ds_write_b32 v102, v100 offset:2048
.LBB0_764:
	s_or_b64 exec, exec, s[16:17]
	v_mul_f32_e32 v100, v65, v65
	s_nop 0
	v_mul_f32_e32 v101, v67, v67
	v_fmac_f32_e32 v100, v64, v64
	v_fmac_f32_e32 v101, v66, v66
	v_add_f32_e32 v100, v100, v101
	v_mul_f32_e32 v101, v137, v137
	v_mul_f32_e32 v102, v139, v139
	v_fmac_f32_e32 v101, v136, v136
	v_fmac_f32_e32 v102, v138, v138
	v_add_f32_e32 v101, v101, v102
	v_add_f32_e32 v100, v100, v101
	v_mul_f32_e32 v101, v45, v45
	v_mul_f32_e32 v102, v47, v47
	v_fmac_f32_e32 v101, v44, v44
	v_fmac_f32_e32 v102, v46, v46
	v_add_f32_e32 v101, v101, v102
	v_add_f32_e32 v100, v100, v101
	v_mul_f32_e32 v101, v13, v13
	v_mul_f32_e32 v102, v15, v15
	v_fmac_f32_e32 v101, v12, v12
	v_fmac_f32_e32 v102, v14, v14
	v_add_f32_e32 v101, v101, v102
	v_add_f32_e32 v100, v100, v101
	v_mov_b32_e32 v101, v100
	s_nop 1
	v_permlane16_swap_b32_e32 v101, v100
	s_nop 0
	v_add_f32_e32 v100, v100, v101
	v_mov_b32_e32 v101, v100
	s_nop 1
	v_permlane32_swap_b32_e32 v101, v100
	s_and_saveexec_b64 s[16:17], s[0:1]
	s_cbranch_execz .LBB0_766
	s_lshl_b32 s11, s38, 10
	s_add_i32 s11, s48, s11
	v_lshl_add_u32 v102, v219, 4, s11
	s_nop 0
	v_add_f32_e32 v100, v100, v101
	ds_write_b32 v102, v100 offset:2304
.LBB0_766:
	s_or_b64 exec, exec, s[16:17]
	v_mul_f32_e32 v100, v69, v69
	s_nop 0
	v_mul_f32_e32 v101, v71, v71
	v_fmac_f32_e32 v100, v68, v68
	v_fmac_f32_e32 v101, v70, v70
	v_add_f32_e32 v100, v100, v101
	v_mul_f32_e32 v101, v117, v117
	v_mul_f32_e32 v102, v119, v119
	v_fmac_f32_e32 v101, v116, v116
	v_fmac_f32_e32 v102, v118, v118
	v_add_f32_e32 v101, v101, v102
	v_add_f32_e32 v100, v100, v101
	v_mul_f32_e32 v101, v41, v41
	v_mul_f32_e32 v102, v43, v43
	v_fmac_f32_e32 v101, v40, v40
	v_fmac_f32_e32 v102, v42, v42
	v_add_f32_e32 v101, v101, v102
	v_add_f32_e32 v100, v100, v101
	v_mul_f32_e32 v101, v9, v9
	v_mul_f32_e32 v102, v11, v11
	v_fmac_f32_e32 v101, v8, v8
	v_fmac_f32_e32 v102, v10, v10
	v_add_f32_e32 v101, v101, v102
	v_add_f32_e32 v100, v100, v101
	v_mov_b32_e32 v101, v100
	s_nop 1
	v_permlane16_swap_b32_e32 v101, v100
	s_nop 0
	v_add_f32_e32 v100, v100, v101
	v_mov_b32_e32 v101, v100
	s_nop 1
	v_permlane32_swap_b32_e32 v101, v100
	s_and_saveexec_b64 s[16:17], s[0:1]
	s_cbranch_execz .LBB0_768
	s_lshl_b32 s11, s38, 10
	s_add_i32 s11, s48, s11
	v_lshl_add_u32 v102, v219, 4, s11
	s_nop 0
	v_add_f32_e32 v100, v100, v101
	ds_write_b32 v102, v100 offset:2560
.LBB0_768:
	s_or_b64 exec, exec, s[16:17]
	v_mul_f32_e32 v100, v53, v53
	s_nop 0
	v_mul_f32_e32 v101, v55, v55
	v_fmac_f32_e32 v100, v52, v52
	v_fmac_f32_e32 v101, v54, v54
	v_add_f32_e32 v100, v100, v101
	v_mul_f32_e32 v101, v113, v113
	v_mul_f32_e32 v102, v115, v115
	v_fmac_f32_e32 v101, v112, v112
	v_fmac_f32_e32 v102, v114, v114
	v_add_f32_e32 v101, v101, v102
	v_add_f32_e32 v100, v100, v101
	v_mul_f32_e32 v101, v37, v37
	v_mul_f32_e32 v102, v39, v39
	v_fmac_f32_e32 v101, v36, v36
	v_fmac_f32_e32 v102, v38, v38
	v_add_f32_e32 v101, v101, v102
	v_add_f32_e32 v100, v100, v101
	v_mul_f32_e32 v101, v5, v5
	v_mul_f32_e32 v102, v7, v7
	v_fmac_f32_e32 v101, v4, v4
	v_fmac_f32_e32 v102, v6, v6
	v_add_f32_e32 v101, v101, v102
	v_add_f32_e32 v100, v100, v101
	v_mov_b32_e32 v2, v100
	s_nop 1
	v_permlane16_swap_b32_e32 v2, v100
	s_nop 0
	v_add_f32_e32 v2, v100, v2
	v_mov_b32_e32 v100, v2
	s_nop 1
	v_permlane32_swap_b32_e32 v100, v2
	s_and_saveexec_b64 s[16:17], s[0:1]
	s_cbranch_execz .LBB0_770
	s_lshl_b32 s0, s38, 10
	s_add_i32 s48, s48, s0
	v_lshl_add_u32 v101, v219, 4, s48
	s_nop 0
	v_add_f32_e32 v2, v2, v100
	ds_write_b32 v101, v2 offset:2816

; #define PG8_STAGE(bufoff, gbase, voff) do { _Pragma("unroll") for (int _i = 0; _i < 2; ++_i) \
;         __builtin_amdgcn_global_load_lds((const unsigned*)((const char*)(gbase) + (voff)[_i]), (PG8_LAS unsigned*)(lds + (bufoff) + ldsw + _i * 8192), 16, 0, 0); } while (0)
; #define PG8_LDA(dst, b, h) do { _Pragma("unroll") for (int m = 0; m < 4; ++m) _Pragma("unroll") for (int k = 0; k < 2; ++k) dst[m][k] = *(const PG8_LAS bf16x8*)(lds + PG8_SA(b, h) + aoff + m * 2048 + k * 1024); } while (0)
; #define PG8_LDB(dst, b, h) do { _Pragma("unroll") for (int n = 0; n < 2; ++n) _Pragma("unroll") for (int k = 0; k < 2; ++k) dst[n][k] = *(const PG8_LAS bf16x8*)(lds + PG8_SB(b, h) + boff + n * 2048 + k * 1024); } while (0)
; #define PG8_MMA(ai, bj, At, Bt) do { __builtin_amdgcn_s_setprio(1); _Pragma("unroll") for (int m = 0; m < 4; ++m) _Pragma("unroll") for (int n = 0; n < 2; ++n) _Pragma("unroll") for (int k = 0; k < 2; ++k) \
;         acc[ai][bj][m][n] = __builtin_amdgcn_mfma_f32_16x16x32_bf16(Bt[n][k], At[m][k], acc[ai][bj][m][n], 0, 0, 0); __builtin_amdgcn_s_setprio(0); } while (0)
; #define PG8_WAIT_V(n) asm volatile("s_waitcnt vmcnt(" #n ")" ::: "memory")
; #define PG8_WAIT_L(n) asm volatile("s_waitcnt lgkmcnt(" #n ")" ::: "memory")
; #define PG8_BAR __builtin_amdgcn_s_barrier()
; #define PG8_SCHED __builtin_amdgcn_sched_barrier(0)
; template <class Epi, class Sched, bool ALIGN_EPI = false, bool SP2 = false>
; __device__ __forceinline__ void gemm_phase(PG8_LAS unsigned char* lds, const Gemm g, const Sched& S, const Epi& E) {
;     ...
;             PG8_LDB(B0, 0, 0); PG8_LDB(B1, 0, 1); PG8_SCHED; PG8_LDA(At, 0, 0); PG8_STAGE(PG8_SA(1, 1), a1 + hstep, voffA);
;             PG8_WAIT_V(8); PG8_WAIT_L(0); PG8_BAR; PG8_MMA(0, 0, At, B0); PG8_MMA(0, 1, At, B1); PG8_BAR; PG8_SCHED;
;             PG8_LDA(At, 0, 1); PG8_STAGE(PG8_SB(0, 0), b2, voffB); PG8_STAGE(PG8_SB(0, 1), b2 + hstep, voffB); PG8_STAGE(PG8_SA(0, 0), a2, voffA);
;             PG8_WAIT_V(8); PG8_WAIT_L(0); PG8_BAR; PG8_MMA(1, 0, At, B0); PG8_MMA(1, 1, At, B1); PG8_BAR; PG8_SCHED;
.LBB0_883:
	s_add_u32 s18, s16, 0xfffc0080
	s_addc_u32 s19, s17, -1
	s_add_i32 s40, 0, 0x10000
	s_cmp_eq_u32 s39, 12
	s_cselect_b32 s21, s11, s19
	s_cselect_b32 s20, s33, s18
	s_cselect_b32 s19, s9, s38
	s_cselect_b32 s18, s34, s35
	s_add_i32 s46, 0, 0x14000
	v_add_u32_e32 v156, s40, v141
	v_add_u32_e32 v172, s46, v141
	ds_read_b128 v[144:147], v156
	ds_read_b128 v[148:151], v156 offset:1024
	ds_read_b128 v[152:155], v156 offset:2048
	ds_read_b128 v[156:159], v156 offset:3072
	ds_read_b128 v[160:163], v172
	ds_read_b128 v[164:167], v172 offset:1024
	ds_read_b128 v[168:171], v172 offset:2048
	ds_read_b128 v[172:175], v172 offset:3072
	v_lshl_add_u64 v[216:217], s[16:17], 0, v[136:137]
	s_add_i32 m0, s23, 0xc000
	ds_read_b128 v[176:179], v143
	ds_read_b128 v[180:183], v143 offset:1024
	ds_read_b128 v[184:187], v143 offset:2048
	ds_read_b128 v[188:191], v143 offset:3072
	ds_read_b128 v[192:195], v143 offset:4096
	ds_read_b128 v[204:207], v143 offset:5120
	ds_read_b128 v[208:211], v143 offset:6144
	ds_read_b128 v[212:215], v143 offset:7168
	global_load_lds_dwordx4 v[216:217], off
	v_lshl_add_u64 v[216:217], s[16:17], 0, v[138:139]
	s_add_i32 m0, s23, 0xe000
	s_nop 0
	global_load_lds_dwordx4 v[216:217], off
	s_waitcnt vmcnt(8)
	s_waitcnt lgkmcnt(0)
	s_barrier
	s_setprio 1
	s_waitcnt lgkmcnt(0)
	v_mfma_f32_16x16x32_bf16 v[128:131], v[144:147], v[176:179], v[128:131]
	v_mfma_f32_16x16x32_bf16 v[124:127], v[152:155], v[176:179], v[124:127]
	v_mfma_f32_16x16x32_bf16 v[112:115], v[144:147], v[184:187], v[112:115]
	v_mfma_f32_16x16x32_bf16 v[108:111], v[152:155], v[184:187], v[108:111]
	v_mfma_f32_16x16x32_bf16 v[96:99], v[144:147], v[192:195], v[96:99]
	v_mfma_f32_16x16x32_bf16 v[92:95], v[152:155], v[192:195], v[92:95]
	v_mfma_f32_16x16x32_bf16 v[80:83], v[144:147], v[208:211], v[80:83]
	v_mfma_f32_16x16x32_bf16 v[76:79], v[152:155], v[208:211], v[76:79]
	v_mfma_f32_16x16x32_bf16 v[128:131], v[148:151], v[180:183], v[128:131]
	v_mfma_f32_16x16x32_bf16 v[124:127], v[156:159], v[180:183], v[124:127]
	v_mfma_f32_16x16x32_bf16 v[112:115], v[148:151], v[188:191], v[112:115]
	v_mfma_f32_16x16x32_bf16 v[108:111], v[156:159], v[188:191], v[108:111]
	v_mfma_f32_16x16x32_bf16 v[96:99], v[148:151], v[204:207], v[96:99]
	v_mfma_f32_16x16x32_bf16 v[92:95], v[156:159], v[204:207], v[92:95]
	v_mfma_f32_16x16x32_bf16 v[80:83], v[148:151], v[212:215], v[80:83]
	v_mfma_f32_16x16x32_bf16 v[76:79], v[156:159], v[212:215], v[76:79]
	v_mfma_f32_16x16x32_bf16 v[120:123], v[160:163], v[176:179], v[120:123]
	v_mfma_f32_16x16x32_bf16 v[116:119], v[168:171], v[176:179], v[116:119]
	v_mfma_f32_16x16x32_bf16 v[104:107], v[160:163], v[184:187], v[104:107]
	v_mfma_f32_16x16x32_bf16 v[100:103], v[168:171], v[184:187], v[100:103]
	v_mfma_f32_16x16x32_bf16 v[88:91], v[160:163], v[192:195], v[88:91]
	v_mfma_f32_16x16x32_bf16 v[84:87], v[168:171], v[192:195], v[84:87]
	v_mfma_f32_16x16x32_bf16 v[72:75], v[160:163], v[208:211], v[72:75]
	v_mfma_f32_16x16x32_bf16 v[68:71], v[168:171], v[208:211], v[68:71]
	v_mfma_f32_16x16x32_bf16 v[120:123], v[164:167], v[180:183], v[120:123]
	v_mfma_f32_16x16x32_bf16 v[116:119], v[172:175], v[180:183], v[116:119]
	v_mfma_f32_16x16x32_bf16 v[104:107], v[164:167], v[188:191], v[104:107]
	v_mfma_f32_16x16x32_bf16 v[100:103], v[172:175], v[188:191], v[100:103]
	v_mfma_f32_16x16x32_bf16 v[88:91], v[164:167], v[204:207], v[88:91]
	v_mfma_f32_16x16x32_bf16 v[84:87], v[172:175], v[204:207], v[84:87]
	v_mfma_f32_16x16x32_bf16 v[72:75], v[164:167], v[212:215], v[72:75]
	v_mfma_f32_16x16x32_bf16 v[68:71], v[172:175], v[212:215], v[68:71]
	s_setprio 0
	s_barrier
	s_add_i32 s40, s40, s22
	v_lshl_add_u64 v[216:217], s[18:19], 0, v[2:3]
	s_mov_b32 m0, s40
	ds_read_b128 v[176:179], v143 offset:16384
	ds_read_b128 v[180:183], v143 offset:17408
	ds_read_b128 v[184:187], v143 offset:18432
	ds_read_b128 v[188:191], v143 offset:19456
	ds_read_b128 v[192:195], v143 offset:20480
	ds_read_b128 v[204:207], v143 offset:21504
	ds_read_b128 v[208:211], v143 offset:22528
	ds_read_b128 v[212:215], v143 offset:23552
	global_load_lds_dwordx4 v[216:217], off
	s_add_i32 m0, s40, 0x2000
	s_add_u32 s40, s18, 0x40000
	v_lshl_add_u64 v[218:219], s[18:19], 0, v[0:1]
	s_addc_u32 s41, s19, 0
	s_add_i32 s46, s46, s22
	global_load_lds_dwordx4 v[218:219], off
	v_lshl_add_u64 v[236:237], s[40:41], 0, v[2:3]
	s_mov_b32 m0, s46
	v_lshl_add_u64 v[238:239], s[20:21], 0, v[132:133]
	global_load_lds_dwordx4 v[236:237], off
	v_lshl_add_u64 v[236:237], s[40:41], 0, v[0:1]
	s_add_i32 m0, s46, 0x2000
	s_nop 0
	global_load_lds_dwordx4 v[236:237], off
	v_lshl_add_u64 v[236:237], s[20:21], 0, v[134:135]
	s_mov_b32 m0, s23
	s_nop 0
	global_load_lds_dwordx4 v[236:237], off
	s_mov_b32 m0, s24
	s_nop 0
	global_load_lds_dwordx4 v[238:239], off
	s_waitcnt vmcnt(8)
	s_waitcnt lgkmcnt(0)
	s_barrier
; #define PG8_STAGE(bufoff, gbase, voff) do { _Pragma("unroll") for (int _i = 0; _i < 2; ++_i) \
;         __builtin_amdgcn_global_load_lds((const unsigned*)((const char*)(gbase) + (voff)[_i]), (PG8_LAS unsigned*)(lds + (bufoff) + ldsw + _i * 8192), 16, 0, 0); } while (0)
; #define PG8_LDA(dst, b, h) do { _Pragma("unroll") for (int m = 0; m < 4; ++m) _Pragma("unroll") for (int k = 0; k < 2; ++k) dst[m][k] = *(const PG8_LAS bf16x8*)(lds + PG8_SA(b, h) + aoff + m * 2048 + k * 1024); } while (0)
; #define PG8_LDB(dst, b, h) do { _Pragma("unroll") for (int n = 0; n < 2; ++n) _Pragma("unroll") for (int k = 0; k < 2; ++k) dst[n][k] = *(const PG8_LAS bf16x8*)(lds + PG8_SB(b, h) + boff + n * 2048 + k * 1024); } while (0)
; #define PG8_MMA(ai, bj, At, Bt) do { __builtin_amdgcn_s_setprio(1); _Pragma("unroll") for (int m = 0; m < 4; ++m) _Pragma("unroll") for (int n = 0; n < 2; ++n) _Pragma("unroll") for (int k = 0; k < 2; ++k) \
;         acc[ai][bj][m][n] = __builtin_amdgcn_mfma_f32_16x16x32_bf16(Bt[n][k], At[m][k], acc[ai][bj][m][n], 0, 0, 0); __builtin_amdgcn_s_setprio(0); } while (0)
; #define PG8_WAIT_V(n) asm volatile("s_waitcnt vmcnt(" #n ")" ::: "memory")
; #define PG8_WAIT_L(n) asm volatile("s_waitcnt lgkmcnt(" #n ")" ::: "memory")
; #define PG8_BAR __builtin_amdgcn_s_barrier()
; #define PG8_SCHED __builtin_amdgcn_sched_barrier(0)
; template <class Epi, class Sched, bool ALIGN_EPI = false, bool SP2 = false>
; __device__ __forceinline__ void gemm_phase(PG8_LAS unsigned char* lds, const Gemm g, const Sched& S, const Epi& E) {
;     ...
;             PG8_WAIT_V(8); PG8_WAIT_L(0); PG8_BAR; PG8_MMA(1, 0, At, B0); PG8_MMA(1, 1, At, B1); PG8_BAR; PG8_SCHED;
;             PG8_LDB(B0, 1, 0); PG8_LDB(B1, 1, 1); PG8_SCHED; PG8_LDA(At, 1, 0); PG8_STAGE(PG8_SA(0, 1), a2 + hstep, voffA);
;             PG8_WAIT_V(8); PG8_WAIT_L(0); PG8_BAR; PG8_MMA(0, 0, At, B0); PG8_MMA(0, 1, At, B1); PG8_BAR; PG8_SCHED;
	s_setprio 1
	s_waitcnt lgkmcnt(0)
	v_mfma_f32_16x16x32_bf16 v[64:67], v[144:147], v[176:179], v[64:67]
	v_mfma_f32_16x16x32_bf16 v[60:63], v[152:155], v[176:179], v[60:63]
	v_mfma_f32_16x16x32_bf16 v[48:51], v[144:147], v[184:187], v[48:51]
	v_mfma_f32_16x16x32_bf16 v[44:47], v[152:155], v[184:187], v[44:47]
	v_mfma_f32_16x16x32_bf16 v[32:35], v[144:147], v[192:195], v[32:35]
	v_mfma_f32_16x16x32_bf16 v[28:31], v[152:155], v[192:195], v[28:31]
	v_mfma_f32_16x16x32_bf16 v[16:19], v[144:147], v[208:211], v[16:19]
	v_mfma_f32_16x16x32_bf16 v[12:15], v[152:155], v[208:211], v[12:15]
	v_mfma_f32_16x16x32_bf16 v[64:67], v[148:151], v[180:183], v[64:67]
	v_mfma_f32_16x16x32_bf16 v[60:63], v[156:159], v[180:183], v[60:63]
	v_mfma_f32_16x16x32_bf16 v[48:51], v[148:151], v[188:191], v[48:51]
	v_mfma_f32_16x16x32_bf16 v[44:47], v[156:159], v[188:191], v[44:47]
	v_mfma_f32_16x16x32_bf16 v[32:35], v[148:151], v[204:207], v[32:35]
	v_mfma_f32_16x16x32_bf16 v[28:31], v[156:159], v[204:207], v[28:31]
	v_mfma_f32_16x16x32_bf16 v[16:19], v[148:151], v[212:215], v[16:19]
	v_mfma_f32_16x16x32_bf16 v[12:15], v[156:159], v[212:215], v[12:15]
	v_mfma_f32_16x16x32_bf16 v[56:59], v[160:163], v[176:179], v[56:59]
	v_mfma_f32_16x16x32_bf16 v[52:55], v[168:171], v[176:179], v[52:55]
	v_mfma_f32_16x16x32_bf16 v[40:43], v[160:163], v[184:187], v[40:43]
	v_mfma_f32_16x16x32_bf16 v[36:39], v[168:171], v[184:187], v[36:39]
	v_mfma_f32_16x16x32_bf16 v[24:27], v[160:163], v[192:195], v[24:27]
	v_mfma_f32_16x16x32_bf16 v[20:23], v[168:171], v[192:195], v[20:23]
	v_mfma_f32_16x16x32_bf16 v[8:11], v[160:163], v[208:211], v[8:11]
	v_mfma_f32_16x16x32_bf16 v[4:7], v[168:171], v[208:211], v[4:7]
	v_mfma_f32_16x16x32_bf16 v[56:59], v[164:167], v[180:183], v[56:59]
	v_mfma_f32_16x16x32_bf16 v[52:55], v[172:175], v[180:183], v[52:55]
	v_mfma_f32_16x16x32_bf16 v[40:43], v[164:167], v[188:191], v[40:43]
	v_mfma_f32_16x16x32_bf16 v[36:39], v[172:175], v[188:191], v[36:39]
	v_mfma_f32_16x16x32_bf16 v[24:27], v[164:167], v[204:207], v[24:27]
	v_mfma_f32_16x16x32_bf16 v[20:23], v[172:175], v[204:207], v[20:23]
	v_mfma_f32_16x16x32_bf16 v[8:11], v[164:167], v[212:215], v[8:11]
	v_mfma_f32_16x16x32_bf16 v[4:7], v[172:175], v[212:215], v[4:7]
	s_setprio 0
	s_barrier
	s_add_i32 s40, 0, 0x18000
	s_add_i32 s41, 0, 0x1c000
	v_add_u32_e32 v156, s40, v141
	v_add_u32_e32 v172, s41, v141
	ds_read_b128 v[144:147], v156
	ds_read_b128 v[148:151], v156 offset:1024
	ds_read_b128 v[152:155], v156 offset:2048
	ds_read_b128 v[156:159], v156 offset:3072
	ds_read_b128 v[160:163], v172
	ds_read_b128 v[164:167], v172 offset:1024
	ds_read_b128 v[168:171], v172 offset:2048
	ds_read_b128 v[172:175], v172 offset:3072
	s_add_u32 s20, s20, 0x40000
	s_addc_u32 s21, s21, 0
	s_mov_b32 m0, s25
	v_lshl_add_u64 v[240:241], s[20:21], 0, v[134:135]
	ds_read_b128 v[176:179], v143 offset:32768
	ds_read_b128 v[180:183], v143 offset:33792
	ds_read_b128 v[184:187], v143 offset:34816
	ds_read_b128 v[188:191], v143 offset:35840
	ds_read_b128 v[192:195], v143 offset:36864
	ds_read_b128 v[204:207], v143 offset:37888
	ds_read_b128 v[208:211], v143 offset:38912
	ds_read_b128 v[212:215], v143 offset:39936
	global_load_lds_dwordx4 v[240:241], off
	v_lshl_add_u64 v[240:241], s[20:21], 0, v[132:133]
	s_mov_b32 m0, s26
	s_nop 0
	global_load_lds_dwordx4 v[240:241], off
	s_waitcnt vmcnt(8)
	s_waitcnt lgkmcnt(0)
	s_barrier
	s_setprio 1
	s_waitcnt lgkmcnt(0)
	v_mfma_f32_16x16x32_bf16 v[128:131], v[144:147], v[176:179], v[128:131]
	v_mfma_f32_16x16x32_bf16 v[124:127], v[152:155], v[176:179], v[124:127]
	v_mfma_f32_16x16x32_bf16 v[112:115], v[144:147], v[184:187], v[112:115]
	v_mfma_f32_16x16x32_bf16 v[108:111], v[152:155], v[184:187], v[108:111]
	v_mfma_f32_16x16x32_bf16 v[96:99], v[144:147], v[192:195], v[96:99]
	v_mfma_f32_16x16x32_bf16 v[92:95], v[152:155], v[192:195], v[92:95]
	v_mfma_f32_16x16x32_bf16 v[80:83], v[144:147], v[208:211], v[80:83]
	v_mfma_f32_16x16x32_bf16 v[76:79], v[152:155], v[208:211], v[76:79]
	v_mfma_f32_16x16x32_bf16 v[128:131], v[148:151], v[180:183], v[128:131]
	v_mfma_f32_16x16x32_bf16 v[124:127], v[156:159], v[180:183], v[124:127]
	v_mfma_f32_16x16x32_bf16 v[112:115], v[148:151], v[188:191], v[112:115]
	v_mfma_f32_16x16x32_bf16 v[108:111], v[156:159], v[188:191], v[108:111]
	v_mfma_f32_16x16x32_bf16 v[96:99], v[148:151], v[204:207], v[96:99]
	v_mfma_f32_16x16x32_bf16 v[92:95], v[156:159], v[204:207], v[92:95]
	v_mfma_f32_16x16x32_bf16 v[80:83], v[148:151], v[212:215], v[80:83]
	v_mfma_f32_16x16x32_bf16 v[76:79], v[156:159], v[212:215], v[76:79]
	v_mfma_f32_16x16x32_bf16 v[120:123], v[160:163], v[176:179], v[120:123]
	v_mfma_f32_16x16x32_bf16 v[116:119], v[168:171], v[176:179], v[116:119]
	v_mfma_f32_16x16x32_bf16 v[104:107], v[160:163], v[184:187], v[104:107]
	v_mfma_f32_16x16x32_bf16 v[100:103], v[168:171], v[184:187], v[100:103]
	v_mfma_f32_16x16x32_bf16 v[88:91], v[160:163], v[192:195], v[88:91]
	v_mfma_f32_16x16x32_bf16 v[84:87], v[168:171], v[192:195], v[84:87]
	v_mfma_f32_16x16x32_bf16 v[72:75], v[160:163], v[208:211], v[72:75]
	v_mfma_f32_16x16x32_bf16 v[68:71], v[168:171], v[208:211], v[68:71]
	v_mfma_f32_16x16x32_bf16 v[120:123], v[164:167], v[180:183], v[120:123]
	v_mfma_f32_16x16x32_bf16 v[116:119], v[172:175], v[180:183], v[116:119]
	v_mfma_f32_16x16x32_bf16 v[104:107], v[164:167], v[188:191], v[104:107]
	v_mfma_f32_16x16x32_bf16 v[100:103], v[172:175], v[188:191], v[100:103]
	v_mfma_f32_16x16x32_bf16 v[88:91], v[164:167], v[204:207], v[88:91]
	v_mfma_f32_16x16x32_bf16 v[84:87], v[172:175], v[204:207], v[84:87]
	v_mfma_f32_16x16x32_bf16 v[72:75], v[164:167], v[212:215], v[72:75]
	v_mfma_f32_16x16x32_bf16 v[68:71], v[172:175], v[212:215], v[68:71]
	s_setprio 0
	s_barrier
; #define PG8_STAGE(bufoff, gbase, voff) do { _Pragma("unroll") for (int _i = 0; _i < 2; ++_i) \
;         __builtin_amdgcn_global_load_lds((const unsigned*)((const char*)(gbase) + (voff)[_i]), (PG8_LAS unsigned*)(lds + (bufoff) + ldsw + _i * 8192), 16, 0, 0); } while (0)
; #define PG8_LDA(dst, b, h) do { _Pragma("unroll") for (int m = 0; m < 4; ++m) _Pragma("unroll") for (int k = 0; k < 2; ++k) dst[m][k] = *(const PG8_LAS bf16x8*)(lds + PG8_SA(b, h) + aoff + m * 2048 + k * 1024); } while (0)
; #define PG8_MMA(ai, bj, At, Bt) do { __builtin_amdgcn_s_setprio(1); _Pragma("unroll") for (int m = 0; m < 4; ++m) _Pragma("unroll") for (int n = 0; n < 2; ++n) _Pragma("unroll") for (int k = 0; k < 2; ++k) \
;         acc[ai][bj][m][n] = __builtin_amdgcn_mfma_f32_16x16x32_bf16(Bt[n][k], At[m][k], acc[ai][bj][m][n], 0, 0, 0); __builtin_amdgcn_s_setprio(0); } while (0)
; #define PG8_WAIT_V(n) asm volatile("s_waitcnt vmcnt(" #n ")" ::: "memory")
; #define PG8_WAIT_L(n) asm volatile("s_waitcnt lgkmcnt(" #n ")" ::: "memory")
; #define PG8_BAR __builtin_amdgcn_s_barrier()
; #define PG8_SCHED __builtin_amdgcn_sched_barrier(0)
; template <class Epi, class Sched, bool ALIGN_EPI = false, bool SP2 = false>
; __device__ __forceinline__ void gemm_phase(PG8_LAS unsigned char* lds, const Gemm g, const Sched& S, const Epi& E) {
;     ...
;         for (int t = 0; t < nt; t += 2) {
;             const bool last = (t == nt - 2);
;             const char* a1 = cA + (size_t)(t + 1) * kstep;
;             const char* a2 = last ? nA : cA + (size_t)(t + 2) * kstep; const char* b2 = last ? nB : cB + (size_t)(t + 2) * kstep;
;     ...
;             PG8_LDA(At, 1, 1); PG8_STAGE(PG8_SB(1, 0), b3, voffB); PG8_STAGE(PG8_SB(1, 1), b3 + hstep, voffB); PG8_STAGE(PG8_SA(1, 0), a3, voffA);
;             PG8_WAIT_V(8); PG8_WAIT_L(0); PG8_BAR; PG8_MMA(1, 0, At, B0); PG8_MMA(1, 1, At, B1); PG8_BAR; PG8_SCHED;
;     ...
;         if constexpr (ALIGN_EPI) { if (wr == 0) PG8_BAR; }
	s_add_i32 s20, s40, s22
	v_lshl_add_u64 v[216:217], v[216:217], 0, s[42:43]
	s_mov_b32 m0, s20
	ds_read_b128 v[176:179], v143 offset:49152
	ds_read_b128 v[180:183], v143 offset:50176
	ds_read_b128 v[184:187], v143 offset:51200
	ds_read_b128 v[188:191], v143 offset:52224
	ds_read_b128 v[192:195], v143 offset:53248
	ds_read_b128 v[204:207], v143 offset:54272
	ds_read_b128 v[208:211], v143 offset:55296
	ds_read_b128 v[212:215], v143 offset:56320
	global_load_lds_dwordx4 v[216:217], off
	s_add_i32 m0, s20, 0x2000
	s_add_u32 s18, s18, 0x40080
	v_lshl_add_u64 v[216:217], v[218:219], 0, s[42:43]
	s_addc_u32 s19, s19, 0
	s_add_i32 s20, s41, s22
	global_load_lds_dwordx4 v[216:217], off
	v_lshl_add_u64 v[216:217], s[18:19], 0, v[2:3]
	s_mov_b32 m0, s20
	s_nop 0
	global_load_lds_dwordx4 v[216:217], off
	v_lshl_add_u64 v[216:217], s[18:19], 0, v[0:1]
	s_add_i32 m0, s20, 0x2000
	s_nop 0
	global_load_lds_dwordx4 v[216:217], off
	v_lshl_add_u64 v[216:217], v[236:237], 0, s[42:43]
	s_mov_b32 m0, s27
	s_nop 0
	global_load_lds_dwordx4 v[216:217], off
	v_lshl_add_u64 v[216:217], v[238:239], 0, s[42:43]
	s_mov_b32 m0, s28
	s_nop 0
	global_load_lds_dwordx4 v[216:217], off
	s_waitcnt vmcnt(8)
	s_waitcnt lgkmcnt(0)
	s_barrier
	s_setprio 1
	s_waitcnt lgkmcnt(0)
	v_mfma_f32_16x16x32_bf16 v[64:67], v[144:147], v[176:179], v[64:67]
	v_mfma_f32_16x16x32_bf16 v[60:63], v[152:155], v[176:179], v[60:63]
	v_mfma_f32_16x16x32_bf16 v[48:51], v[144:147], v[184:187], v[48:51]
	v_mfma_f32_16x16x32_bf16 v[44:47], v[152:155], v[184:187], v[44:47]
	v_mfma_f32_16x16x32_bf16 v[32:35], v[144:147], v[192:195], v[32:35]
	v_mfma_f32_16x16x32_bf16 v[28:31], v[152:155], v[192:195], v[28:31]
	v_mfma_f32_16x16x32_bf16 v[16:19], v[144:147], v[208:211], v[16:19]
	v_mfma_f32_16x16x32_bf16 v[12:15], v[152:155], v[208:211], v[12:15]
	v_mfma_f32_16x16x32_bf16 v[64:67], v[148:151], v[180:183], v[64:67]
	v_mfma_f32_16x16x32_bf16 v[60:63], v[156:159], v[180:183], v[60:63]
	v_mfma_f32_16x16x32_bf16 v[48:51], v[148:151], v[188:191], v[48:51]
	v_mfma_f32_16x16x32_bf16 v[44:47], v[156:159], v[188:191], v[44:47]
	v_mfma_f32_16x16x32_bf16 v[32:35], v[148:151], v[204:207], v[32:35]
	v_mfma_f32_16x16x32_bf16 v[28:31], v[156:159], v[204:207], v[28:31]
	v_mfma_f32_16x16x32_bf16 v[16:19], v[148:151], v[212:215], v[16:19]
	v_mfma_f32_16x16x32_bf16 v[12:15], v[156:159], v[212:215], v[12:15]
	v_mfma_f32_16x16x32_bf16 v[56:59], v[160:163], v[176:179], v[56:59]
	v_mfma_f32_16x16x32_bf16 v[52:55], v[168:171], v[176:179], v[52:55]
	v_mfma_f32_16x16x32_bf16 v[40:43], v[160:163], v[184:187], v[40:43]
	v_mfma_f32_16x16x32_bf16 v[36:39], v[168:171], v[184:187], v[36:39]
	v_mfma_f32_16x16x32_bf16 v[24:27], v[160:163], v[192:195], v[24:27]
	v_mfma_f32_16x16x32_bf16 v[20:23], v[168:171], v[192:195], v[20:23]
	v_mfma_f32_16x16x32_bf16 v[8:11], v[160:163], v[208:211], v[8:11]
	v_mfma_f32_16x16x32_bf16 v[4:7], v[168:171], v[208:211], v[4:7]
	v_mfma_f32_16x16x32_bf16 v[56:59], v[164:167], v[180:183], v[56:59]
	v_mfma_f32_16x16x32_bf16 v[52:55], v[172:175], v[180:183], v[52:55]
	v_mfma_f32_16x16x32_bf16 v[40:43], v[164:167], v[188:191], v[40:43]
	v_mfma_f32_16x16x32_bf16 v[36:39], v[172:175], v[188:191], v[36:39]
	v_mfma_f32_16x16x32_bf16 v[24:27], v[164:167], v[204:207], v[24:27]
	v_mfma_f32_16x16x32_bf16 v[20:23], v[172:175], v[204:207], v[20:23]
	v_mfma_f32_16x16x32_bf16 v[8:11], v[164:167], v[212:215], v[8:11]
	v_mfma_f32_16x16x32_bf16 v[4:7], v[172:175], v[212:215], v[4:7]
	s_setprio 0
	s_barrier
	s_add_i32 s39, s39, 2
	s_add_u32 s16, s16, 0x100
	s_addc_u32 s17, s17, 0
	s_add_u32 s35, s35, 0x100
	s_addc_u32 s38, s38, 0
	s_cmp_gt_u32 s39, 13
	s_cbranch_scc0 .LBB0_883
	s_and_b64 vcc, exec, s[6:7]
	s_cbranch_vccz .LBB0_886
	s_barrier
